# MLA sample units on the pipelined loop too (masked last tile); K prefetch lead 3 tiles in the MLA prompt loop
# speedup vs baseline: 1.0481x; 1.0032x over previous
.Lsm_entry:
	s_mov_b32 s30, 0x20000
	s_mov_b32 s31, 0
	s_mov_b32 s12, 0x1000
	s_mov_b32 s13, 0
	s_mov_b32 s78, 0
	s_cmp_lt_u32 s24, 4
	s_cbranch_scc0 .Lsm_B
	s_barrier
	s_mov_b32 s0, 0x60000
	s_mov_b32 s1, 0
	v_lshl_add_u64 v[24:25], v[16:17], 0, s[0:1]
	s_add_u32 m0, s40, 0x9000
	s_mov_b32 s0, 0x3000
	global_load_lds_dwordx4 v[24:25], off
	v_lshl_add_u64 v[30:31], v[222:223], 0, s[0:1]
	s_add_u32 m0, s43, 0x9000
	s_nop 0
	global_load_lds_dwordx4 v[30:31], off
	s_mov_b32 s0, 0x80000
	s_mov_b32 s1, 0
	v_lshl_add_u64 v[24:25], v[16:17], 0, s[0:1]
	s_mov_b32 s0, 0x60000
	v_lshl_add_u64 v[28:29], v[224:225], 0, s[0:1]
	s_mov_b32 s0, 0x4000
	v_lshl_add_u64 v[30:31], v[222:223], 0, s[0:1]
	s_cmp_eq_u32 s24, 0
	s_cbranch_scc0 .Lsm_A_skel
	s_waitcnt lgkmcnt(0)
	v_mfma_f32_32x32x16_bf16 v[82:97], v[218:221], v[4:7], v[66:81]
	v_mfma_f32_32x32x16_bf16 v[98:113], v[214:217], v[4:7], v[66:81]
	v_mfma_f32_32x32x16_bf16 v[82:97], v[210:213], v[8:11], v[82:97]
	v_mfma_f32_32x32x16_bf16 v[98:113], v[206:209], v[8:11], v[98:113]
	v_mfma_f32_32x32x16_bf16 v[82:97], v[202:205], v[12:15], v[82:97]
	v_mfma_f32_32x32x16_bf16 v[98:113], v[198:201], v[12:15], v[98:113]
	v_mfma_f32_32x32x16_bf16 v[82:97], v[194:197], v[130:133], v[82:97]
	v_mfma_f32_32x32x16_bf16 v[98:113], v[190:193], v[130:133], v[98:113]
	v_mfma_f32_32x32x16_bf16 v[82:97], v[186:189], v[134:137], v[82:97]
	v_mfma_f32_32x32x16_bf16 v[98:113], v[182:185], v[134:137], v[98:113]
	v_mfma_f32_32x32x16_bf16 v[82:97], v[178:181], v[138:141], v[82:97]
	v_mfma_f32_32x32x16_bf16 v[98:113], v[174:177], v[138:141], v[98:113]
	v_add_u32_e32 v2, 0x3000, v238
	ds_read_b128 v[218:221], v2
	ds_read_b128 v[214:217], v2 offset:512
	ds_read_b128 v[210:213], v2 offset:2048
	ds_read_b128 v[206:209], v2 offset:2560
	ds_read_b128 v[202:205], v2 offset:4096
	ds_read_b128 v[198:201], v2 offset:4608
	ds_read_b128 v[194:197], v2 offset:6144
	ds_read_b128 v[190:193], v2 offset:6656
	ds_read_b128 v[186:189], v2 offset:8192
	ds_read_b128 v[182:185], v2 offset:8704
	ds_read_b128 v[178:181], v2 offset:10240
	ds_read_b128 v[174:177], v2 offset:10752
	s_nop 7
	v_max3_f32 v19, v82, v83, v84
	v_max3_f32 v26, v85, v86, v87
	v_max3_f32 v19, v19, v88, v89
	v_max3_f32 v26, v26, v90, v91
	v_max3_f32 v19, v19, v92, v93
	v_max3_f32 v26, v26, v94, v95
	v_max3_f32 v19, v19, v96, v97
	v_max3_f32 v26, v26, v98, v99
	v_max3_f32 v19, v19, v100, v101
	v_max3_f32 v26, v26, v102, v103
	v_max3_f32 v19, v19, v104, v105
	v_max3_f32 v26, v26, v106, v107
	v_max3_f32 v19, v19, v108, v109
	v_max3_f32 v26, v26, v110, v111
	v_max3_f32 v19, v19, v112, v113
	v_max_f32_e32 v19, v19, v26
	v_mov_b32_e32 v26, v19
	s_nop 1
	v_permlane32_swap_b32_e32 v19, v26
	v_max_f32_e32 v19, v19, v26
	v_max_f32_e32 v19, v19, v19
	v_mov_b32_e32 v239, v19
	v_xor_b32_e32 v66, 0x80000000, v19
	v_mov_b32_e32 v67, v66
	v_mov_b32_e32 v68, v66
	v_mov_b32_e32 v69, v66
	v_mov_b32_e32 v70, v66
	v_mov_b32_e32 v71, v66
	v_mov_b32_e32 v72, v66
	v_mov_b32_e32 v73, v66
	v_mov_b32_e32 v74, v66
	v_mov_b32_e32 v75, v66
	v_mov_b32_e32 v76, v66
	v_mov_b32_e32 v77, v66
	v_mov_b32_e32 v78, v66
	v_mov_b32_e32 v79, v66
	v_mov_b32_e32 v80, v66
	v_mov_b32_e32 v81, v66
	v_sub_f32_e32 v82, v82, v19
	v_sub_f32_e32 v83, v83, v19
	v_sub_f32_e32 v84, v84, v19
	v_sub_f32_e32 v85, v85, v19
	v_sub_f32_e32 v86, v86, v19
	v_sub_f32_e32 v87, v87, v19
	v_sub_f32_e32 v88, v88, v19
	v_sub_f32_e32 v89, v89, v19
	v_sub_f32_e32 v90, v90, v19
	v_sub_f32_e32 v91, v91, v19
	v_sub_f32_e32 v92, v92, v19
	v_sub_f32_e32 v93, v93, v19
	v_sub_f32_e32 v94, v94, v19
	v_sub_f32_e32 v95, v95, v19
	v_sub_f32_e32 v96, v96, v19
	v_sub_f32_e32 v97, v97, v19
	v_sub_f32_e32 v98, v98, v19
	v_sub_f32_e32 v99, v99, v19
	v_sub_f32_e32 v100, v100, v19
	v_sub_f32_e32 v101, v101, v19
	v_sub_f32_e32 v102, v102, v19
	v_sub_f32_e32 v103, v103, v19
	v_sub_f32_e32 v104, v104, v19
	v_sub_f32_e32 v105, v105, v19
	v_sub_f32_e32 v106, v106, v19
	v_sub_f32_e32 v107, v107, v19
	v_sub_f32_e32 v108, v108, v19
	v_sub_f32_e32 v109, v109, v19
	v_sub_f32_e32 v110, v110, v19
	v_sub_f32_e32 v111, v111, v19
	v_sub_f32_e32 v112, v112, v19
	v_sub_f32_e32 v113, v113, v19
	s_mov_b32 s79, 31
.Lsm_loop:
	s_waitcnt vmcnt(3)
	s_cmp_lt_u32 s78, 62
	s_cbranch_scc1 .Lsm_w_1
	s_waitcnt vmcnt(0)
.Lsm_w_1:
	s_waitcnt lgkmcnt(0)
	s_barrier
	s_cmp_gt_u32 s78, 61
	s_cbranch_scc1 .Lsm_dk_2
	s_add_i32 s0, s78, 3
	s_and_b32 s0, s0, 3
	s_lshl_b32 s0, s0, 13
	s_add_u32 m0, s57, s0
	s_cmp_gt_u32 s78, 60
	global_load_lds_dwordx4 v[28:29], off
	v_lshl_add_u64 v[28:29], v[28:29], 0, s[30:31]
	s_cbranch_scc1 .Lsm_dk_2
	s_and_b32 s0, s78, 3
	s_mulk_i32 s0, 0x3000
	s_add_u32 m0, s40, s0
	s_add_u32 s0, s43, s0
	global_load_lds_dwordx4 v[24:25], off
	v_lshl_add_u64 v[24:25], v[24:25], 0, s[30:31]
	s_mov_b32 m0, s0
	s_nop 0
	global_load_lds_dwordx4 v[30:31], off
	v_lshl_add_u64 v[30:31], v[30:31], 0, s[12:13]
.Lsm_dk_2:
	s_and_b32 s17, s78, 3
	s_lshl_b32 s17, s17, 13
	v_add_u32_e32 v2, s17, v237
	v_mfma_f32_32x32x16_bf16 v[142:157], v[218:221], v[4:7], v[66:81]
	v_exp_f32_e32 v82, v82
	v_exp_f32_e32 v83, v83
	v_exp_f32_e32 v84, v84
	v_add_f32_e32 v27, v82, v83
	v_exp_f32_e32 v85, v85
	ds_read_b64_tr_b16 v[114:115], v2 offset:49152
	ds_read_b64_tr_b16 v[116:117], v2 offset:49664
	ds_read_b64_tr_b16 v[118:119], v2 offset:50176
	ds_read_b64_tr_b16 v[120:121], v2 offset:50688
	v_mfma_f32_32x32x16_bf16 v[158:173], v[214:217], v[4:7], v[66:81]
	v_exp_f32_e32 v86, v86
	v_add_f32_e32 v27, v27, v84
	v_exp_f32_e32 v87, v87
	v_add_f32_e32 v27, v27, v85
	v_exp_f32_e32 v88, v88
	ds_read_b64_tr_b16 v[122:123], v2 offset:51200
	ds_read_b64_tr_b16 v[124:125], v2 offset:51712
	ds_read_b64_tr_b16 v[126:127], v2 offset:52224
	ds_read_b64_tr_b16 v[128:129], v2 offset:52736
	v_mfma_f32_32x32x16_bf16 v[142:157], v[210:213], v[8:11], v[142:157]
	v_add_f32_e32 v27, v27, v86
	v_exp_f32_e32 v89, v89
	v_add_f32_e32 v27, v27, v87
	v_add_f32_e32 v27, v27, v88
	v_add_f32_e32 v27, v27, v89
	ds_read_b64_tr_b16 v[240:241], v2 offset:53248
	ds_read_b64_tr_b16 v[242:243], v2 offset:53760
	ds_read_b64_tr_b16 v[244:245], v2 offset:54272
	ds_read_b64_tr_b16 v[246:247], v2 offset:54784
	v_mfma_f32_32x32x16_bf16 v[158:173], v[206:209], v[8:11], v[158:173]
	v_cvt_pk_bf16_f32 v82, v82, v83
	v_cvt_pk_bf16_f32 v83, v84, v85
	v_cvt_pk_bf16_f32 v84, v86, v87
	v_cvt_pk_bf16_f32 v85, v88, v89
	ds_read_b64_tr_b16 v[248:249], v2 offset:55296
	ds_read_b64_tr_b16 v[250:251], v2 offset:55808
	ds_read_b64_tr_b16 v[20:21], v2 offset:56320
	ds_read_b64_tr_b16 v[22:23], v2 offset:56832
	v_mfma_f32_32x32x16_bf16 v[142:157], v[202:205], v[12:15], v[142:157]
	v_exp_f32_e32 v90, v90
	v_exp_f32_e32 v91, v91
	v_exp_f32_e32 v92, v92
	v_add_f32_e32 v27, v27, v90
	v_exp_f32_e32 v93, v93
	v_mfma_f32_32x32x16_bf16 v[158:173], v[198:201], v[12:15], v[158:173]
	v_add_f32_e32 v27, v27, v91
	v_exp_f32_e32 v94, v94
	v_add_f32_e32 v27, v27, v92
	v_exp_f32_e32 v95, v95
	v_add_f32_e32 v27, v27, v93
	v_mfma_f32_32x32x16_bf16 v[142:157], v[194:197], v[130:133], v[142:157]
	v_exp_f32_e32 v96, v96
	v_add_f32_e32 v27, v27, v94
	v_exp_f32_e32 v97, v97
	v_add_f32_e32 v27, v27, v95
	v_add_f32_e32 v27, v27, v96
	v_mfma_f32_32x32x16_bf16 v[158:173], v[190:193], v[130:133], v[158:173]
	v_add_f32_e32 v27, v27, v97
	v_cvt_pk_bf16_f32 v90, v90, v91
	v_cvt_pk_bf16_f32 v91, v92, v93
	v_cvt_pk_bf16_f32 v92, v94, v95
	v_cvt_pk_bf16_f32 v93, v96, v97
	v_mfma_f32_32x32x16_bf16 v[142:157], v[186:189], v[134:137], v[142:157]
	v_exp_f32_e32 v98, v98
	v_exp_f32_e32 v99, v99
	v_exp_f32_e32 v100, v100
	v_add_f32_e32 v27, v27, v98
	v_exp_f32_e32 v101, v101
	v_mfma_f32_32x32x16_bf16 v[158:173], v[182:185], v[134:137], v[158:173]
	v_add_f32_e32 v27, v27, v99
	v_exp_f32_e32 v102, v102
	v_add_f32_e32 v27, v27, v100
	v_exp_f32_e32 v103, v103
	v_add_f32_e32 v27, v27, v101
	v_mfma_f32_32x32x16_bf16 v[142:157], v[178:181], v[138:141], v[142:157]
	v_exp_f32_e32 v104, v104
	v_add_f32_e32 v27, v27, v102
	v_exp_f32_e32 v105, v105
	v_add_f32_e32 v27, v27, v103
	v_add_f32_e32 v27, v27, v104
	v_mfma_f32_32x32x16_bf16 v[158:173], v[174:177], v[138:141], v[158:173]
	v_add_f32_e32 v27, v27, v105
	v_cvt_pk_bf16_f32 v98, v98, v99
	v_cvt_pk_bf16_f32 v99, v100, v101
	v_cvt_pk_bf16_f32 v100, v102, v103
	v_cvt_pk_bf16_f32 v101, v104, v105
	s_waitcnt lgkmcnt(0)
	s_add_i32 s17, s78, 2
	s_and_b32 s17, s17, 3
	s_mulk_i32 s17, 0x3000
	v_add_u32_e32 v2, s17, v238
	v_mfma_f32_32x32x16_bf16 v[34:49], v[82:85], v[114:117], v[34:49]
	v_exp_f32_e32 v106, v106
	v_exp_f32_e32 v107, v107
	v_exp_f32_e32 v108, v108
	v_add_f32_e32 v27, v27, v106
	v_exp_f32_e32 v109, v109
	v_add_f32_e32 v27, v27, v107
	v_exp_f32_e32 v110, v110
	v_add_f32_e32 v27, v27, v108
	v_exp_f32_e32 v111, v111
	v_add_f32_e32 v27, v27, v109
	ds_read_b128 v[218:221], v2
	ds_read_b128 v[214:217], v2 offset:512
	ds_read_b128 v[210:213], v2 offset:2048
	v_mfma_f32_32x32x16_bf16 v[50:65], v[82:85], v[240:243], v[50:65]
	v_exp_f32_e32 v112, v112
	v_add_f32_e32 v27, v27, v110
	v_exp_f32_e32 v113, v113
	v_add_f32_e32 v27, v27, v111
	v_add_f32_e32 v27, v27, v112
	v_add_f32_e32 v27, v27, v113
	v_cvt_pk_bf16_f32 v106, v106, v107
	v_cvt_pk_bf16_f32 v107, v108, v109
	v_cvt_pk_bf16_f32 v108, v110, v111
	v_cvt_pk_bf16_f32 v109, v112, v113
	v_add_f32_e32 v236, v236, v27
	ds_read_b128 v[206:209], v2 offset:2560
	ds_read_b128 v[202:205], v2 offset:4096
	ds_read_b128 v[198:201], v2 offset:4608
	v_mfma_f32_32x32x16_bf16 v[34:49], v[90:93], v[118:121], v[34:49]
	ds_read_b128 v[194:197], v2 offset:6144
	ds_read_b128 v[190:193], v2 offset:6656
	ds_read_b128 v[186:189], v2 offset:8192
	v_max3_f32 v19, v142, v143, v144
	v_max3_f32 v26, v145, v146, v147
	v_max3_f32 v19, v19, v148, v149
	v_max3_f32 v26, v26, v150, v151
	v_max3_f32 v19, v19, v152, v153
	v_mfma_f32_32x32x16_bf16 v[50:65], v[90:93], v[244:247], v[50:65]
	ds_read_b128 v[182:185], v2 offset:8704
	ds_read_b128 v[178:181], v2 offset:10240
	ds_read_b128 v[174:177], v2 offset:10752
	v_max3_f32 v26, v26, v154, v155
	v_max3_f32 v19, v19, v156, v157
	v_max3_f32 v26, v26, v158, v159
	v_max3_f32 v19, v19, v160, v161
	v_max3_f32 v26, v26, v162, v163
	v_mfma_f32_32x32x16_bf16 v[34:49], v[98:101], v[122:125], v[34:49]
	v_max3_f32 v19, v19, v164, v165
	v_max3_f32 v26, v26, v166, v167
	v_max3_f32 v19, v19, v168, v169
	v_max3_f32 v26, v26, v170, v171
	v_mfma_f32_32x32x16_bf16 v[50:65], v[98:101], v[248:251], v[50:65]
	v_max3_f32 v19, v19, v172, v173
	v_max_f32_e32 v19, v19, v26
	v_mfma_f32_32x32x16_bf16 v[34:49], v[106:109], v[126:129], v[34:49]
	v_mfma_f32_32x32x16_bf16 v[50:65], v[106:109], v[20:23], v[50:65]
	v_cmp_lt_f32_e32 vcc, s41, v19
	s_cbranch_vccz .Lsm_nors_3
	s_nop 15
	s_nop 15
	v_mov_b32_e32 v26, v19
	s_nop 1
	v_permlane32_swap_b32_e32 v19, v26
	v_max_f32_e32 v19, v19, v26
	v_max_f32_e32 v19, v19, v19
	v_max_f32_e32 v90, 0, v19
	v_exp_f32_e64 v91, -v90
	v_add_f32_e32 v239, v239, v90
	v_xor_b32_e32 v66, 0x80000000, v239
	v_mov_b32_e32 v67, v66
	v_mov_b32_e32 v68, v66
	v_mov_b32_e32 v69, v66
	v_mov_b32_e32 v70, v66
	v_mov_b32_e32 v71, v66
	v_mov_b32_e32 v72, v66
	v_mov_b32_e32 v73, v66
	v_mov_b32_e32 v74, v66
	v_mov_b32_e32 v75, v66
	v_mov_b32_e32 v76, v66
	v_mov_b32_e32 v77, v66
	v_mov_b32_e32 v78, v66
	v_mov_b32_e32 v79, v66
	v_mov_b32_e32 v80, v66
	v_mov_b32_e32 v81, v66
	v_sub_f32_e32 v142, v142, v90
	v_sub_f32_e32 v143, v143, v90
	v_sub_f32_e32 v144, v144, v90
	v_sub_f32_e32 v145, v145, v90
	v_sub_f32_e32 v146, v146, v90
	v_sub_f32_e32 v147, v147, v90
	v_sub_f32_e32 v148, v148, v90
	v_sub_f32_e32 v149, v149, v90
	v_sub_f32_e32 v150, v150, v90
	v_sub_f32_e32 v151, v151, v90
	v_sub_f32_e32 v152, v152, v90
	v_sub_f32_e32 v153, v153, v90
	v_sub_f32_e32 v154, v154, v90
	v_sub_f32_e32 v155, v155, v90
	v_sub_f32_e32 v156, v156, v90
	v_sub_f32_e32 v157, v157, v90
	v_sub_f32_e32 v158, v158, v90
	v_sub_f32_e32 v159, v159, v90
	v_sub_f32_e32 v160, v160, v90
	v_sub_f32_e32 v161, v161, v90
	v_sub_f32_e32 v162, v162, v90
	v_sub_f32_e32 v163, v163, v90
	v_sub_f32_e32 v164, v164, v90
	v_sub_f32_e32 v165, v165, v90
	v_sub_f32_e32 v166, v166, v90
	v_sub_f32_e32 v167, v167, v90
	v_sub_f32_e32 v168, v168, v90
	v_sub_f32_e32 v169, v169, v90
	v_sub_f32_e32 v170, v170, v90
	v_sub_f32_e32 v171, v171, v90
	v_sub_f32_e32 v172, v172, v90
	v_sub_f32_e32 v173, v173, v90
	v_mul_f32_e32 v236, v236, v91
	s_mov_b64 s[96:97], exec
	s_and_b64 exec, exec, s[8:9]
	ds_write_b32 v235, v91
	s_mov_b64 exec, s[96:97]
	v_lshl_add_u32 v2, v228, 4, s47
	ds_read_b128 v[94:97], v2 offset:0
	s_waitcnt lgkmcnt(0)
	v_mul_f32_e32 v34, v34, v94
	v_mul_f32_e32 v50, v50, v94
	v_mul_f32_e32 v35, v35, v95
	v_mul_f32_e32 v51, v51, v95
	v_mul_f32_e32 v36, v36, v96
	v_mul_f32_e32 v52, v52, v96
	v_mul_f32_e32 v37, v37, v97
	v_mul_f32_e32 v53, v53, v97
	ds_read_b128 v[94:97], v2 offset:32
	s_waitcnt lgkmcnt(0)
	v_mul_f32_e32 v38, v38, v94
	v_mul_f32_e32 v54, v54, v94
	v_mul_f32_e32 v39, v39, v95
	v_mul_f32_e32 v55, v55, v95
	v_mul_f32_e32 v40, v40, v96
	v_mul_f32_e32 v56, v56, v96
	v_mul_f32_e32 v41, v41, v97
	v_mul_f32_e32 v57, v57, v97
	ds_read_b128 v[94:97], v2 offset:64
	s_waitcnt lgkmcnt(0)
	v_mul_f32_e32 v42, v42, v94
	v_mul_f32_e32 v58, v58, v94
	v_mul_f32_e32 v43, v43, v95
	v_mul_f32_e32 v59, v59, v95
	v_mul_f32_e32 v44, v44, v96
	v_mul_f32_e32 v60, v60, v96
	v_mul_f32_e32 v45, v45, v97
	v_mul_f32_e32 v61, v61, v97
	ds_read_b128 v[94:97], v2 offset:96
	s_waitcnt lgkmcnt(0)
	v_mul_f32_e32 v46, v46, v94
	v_mul_f32_e32 v62, v62, v94
	v_mul_f32_e32 v47, v47, v95
	v_mul_f32_e32 v63, v63, v95
	v_mul_f32_e32 v48, v48, v96
	v_mul_f32_e32 v64, v64, v96
	v_mul_f32_e32 v49, v49, v97
	v_mul_f32_e32 v65, v65, v97
.Lsm_nors_3:
	s_add_i32 s78, s78, 1
	s_waitcnt vmcnt(3)
	s_cmp_lt_u32 s78, 62
	s_cbranch_scc1 .Lsm_w_4
	s_waitcnt vmcnt(0)

.Lsm_dk_5:
	s_and_b32 s17, s78, 3
	s_lshl_b32 s17, s17, 13
	v_add_u32_e32 v2, s17, v237
	v_mfma_f32_32x32x16_bf16 v[82:97], v[218:221], v[4:7], v[66:81]
	v_exp_f32_e32 v142, v142
	v_exp_f32_e32 v143, v143
	v_exp_f32_e32 v144, v144
	v_add_f32_e32 v27, v142, v143
	v_exp_f32_e32 v145, v145
	ds_read_b64_tr_b16 v[114:115], v2 offset:49152
	ds_read_b64_tr_b16 v[116:117], v2 offset:49664
	ds_read_b64_tr_b16 v[118:119], v2 offset:50176
	ds_read_b64_tr_b16 v[120:121], v2 offset:50688
	v_mfma_f32_32x32x16_bf16 v[98:113], v[214:217], v[4:7], v[66:81]
	v_exp_f32_e32 v146, v146
	v_add_f32_e32 v27, v27, v144
	v_exp_f32_e32 v147, v147
	v_add_f32_e32 v27, v27, v145
	v_exp_f32_e32 v148, v148
	ds_read_b64_tr_b16 v[122:123], v2 offset:51200
	ds_read_b64_tr_b16 v[124:125], v2 offset:51712
	ds_read_b64_tr_b16 v[126:127], v2 offset:52224
	ds_read_b64_tr_b16 v[128:129], v2 offset:52736
	v_mfma_f32_32x32x16_bf16 v[82:97], v[210:213], v[8:11], v[82:97]
	v_add_f32_e32 v27, v27, v146
	v_exp_f32_e32 v149, v149
	v_add_f32_e32 v27, v27, v147
	v_add_f32_e32 v27, v27, v148
	v_add_f32_e32 v27, v27, v149
	ds_read_b64_tr_b16 v[240:241], v2 offset:53248
	ds_read_b64_tr_b16 v[242:243], v2 offset:53760
	ds_read_b64_tr_b16 v[244:245], v2 offset:54272
	ds_read_b64_tr_b16 v[246:247], v2 offset:54784
	v_mfma_f32_32x32x16_bf16 v[98:113], v[206:209], v[8:11], v[98:113]
	v_cvt_pk_bf16_f32 v142, v142, v143
	v_cvt_pk_bf16_f32 v143, v144, v145
	v_cvt_pk_bf16_f32 v144, v146, v147
	v_cvt_pk_bf16_f32 v145, v148, v149
	ds_read_b64_tr_b16 v[248:249], v2 offset:55296
	ds_read_b64_tr_b16 v[250:251], v2 offset:55808
	ds_read_b64_tr_b16 v[20:21], v2 offset:56320
	ds_read_b64_tr_b16 v[22:23], v2 offset:56832
	v_mfma_f32_32x32x16_bf16 v[82:97], v[202:205], v[12:15], v[82:97]
	v_exp_f32_e32 v150, v150
	v_exp_f32_e32 v151, v151
	v_exp_f32_e32 v152, v152
	v_add_f32_e32 v27, v27, v150
	v_exp_f32_e32 v153, v153
	v_mfma_f32_32x32x16_bf16 v[98:113], v[198:201], v[12:15], v[98:113]
	v_add_f32_e32 v27, v27, v151
	v_exp_f32_e32 v154, v154
	v_add_f32_e32 v27, v27, v152
	v_exp_f32_e32 v155, v155
	v_add_f32_e32 v27, v27, v153
	v_mfma_f32_32x32x16_bf16 v[82:97], v[194:197], v[130:133], v[82:97]
	v_exp_f32_e32 v156, v156
	v_add_f32_e32 v27, v27, v154
	v_exp_f32_e32 v157, v157
	v_add_f32_e32 v27, v27, v155
	v_add_f32_e32 v27, v27, v156
	v_mfma_f32_32x32x16_bf16 v[98:113], v[190:193], v[130:133], v[98:113]
	v_add_f32_e32 v27, v27, v157
	v_cvt_pk_bf16_f32 v150, v150, v151
	v_cvt_pk_bf16_f32 v151, v152, v153
	v_cvt_pk_bf16_f32 v152, v154, v155
	v_cvt_pk_bf16_f32 v153, v156, v157
	v_mfma_f32_32x32x16_bf16 v[82:97], v[186:189], v[134:137], v[82:97]
	v_exp_f32_e32 v158, v158
	v_exp_f32_e32 v159, v159
	v_exp_f32_e32 v160, v160
	v_add_f32_e32 v27, v27, v158
	v_exp_f32_e32 v161, v161
	v_mfma_f32_32x32x16_bf16 v[98:113], v[182:185], v[134:137], v[98:113]
	v_add_f32_e32 v27, v27, v159
	v_exp_f32_e32 v162, v162
	v_add_f32_e32 v27, v27, v160
	v_exp_f32_e32 v163, v163
	v_add_f32_e32 v27, v27, v161
	v_mfma_f32_32x32x16_bf16 v[82:97], v[178:181], v[138:141], v[82:97]
	v_exp_f32_e32 v164, v164
	v_add_f32_e32 v27, v27, v162
	v_exp_f32_e32 v165, v165
	v_add_f32_e32 v27, v27, v163
	v_add_f32_e32 v27, v27, v164
	v_mfma_f32_32x32x16_bf16 v[98:113], v[174:177], v[138:141], v[98:113]
	v_add_f32_e32 v27, v27, v165
	v_cvt_pk_bf16_f32 v158, v158, v159
	v_cvt_pk_bf16_f32 v159, v160, v161
	v_cvt_pk_bf16_f32 v160, v162, v163
	v_cvt_pk_bf16_f32 v161, v164, v165
	s_waitcnt lgkmcnt(0)
	s_add_i32 s17, s78, 2
	s_and_b32 s17, s17, 3
	s_mulk_i32 s17, 0x3000
	v_add_u32_e32 v2, s17, v238
	v_mfma_f32_32x32x16_bf16 v[34:49], v[142:145], v[114:117], v[34:49]
	v_exp_f32_e32 v166, v166
	v_exp_f32_e32 v167, v167
	v_exp_f32_e32 v168, v168
	v_add_f32_e32 v27, v27, v166
	v_exp_f32_e32 v169, v169
	v_add_f32_e32 v27, v27, v167
	v_exp_f32_e32 v170, v170
	v_add_f32_e32 v27, v27, v168
	v_exp_f32_e32 v171, v171
	v_add_f32_e32 v27, v27, v169
	ds_read_b128 v[218:221], v2
	ds_read_b128 v[214:217], v2 offset:512
	ds_read_b128 v[210:213], v2 offset:2048
	v_mfma_f32_32x32x16_bf16 v[50:65], v[142:145], v[240:243], v[50:65]
	v_exp_f32_e32 v172, v172
	v_add_f32_e32 v27, v27, v170
	v_exp_f32_e32 v173, v173
	v_add_f32_e32 v27, v27, v171
	v_add_f32_e32 v27, v27, v172
	v_add_f32_e32 v27, v27, v173
	v_cvt_pk_bf16_f32 v166, v166, v167
	v_cvt_pk_bf16_f32 v167, v168, v169
	v_cvt_pk_bf16_f32 v168, v170, v171
	v_cvt_pk_bf16_f32 v169, v172, v173
	v_add_f32_e32 v236, v236, v27
	ds_read_b128 v[206:209], v2 offset:2560
	ds_read_b128 v[202:205], v2 offset:4096
	ds_read_b128 v[198:201], v2 offset:4608
	v_mfma_f32_32x32x16_bf16 v[34:49], v[150:153], v[118:121], v[34:49]
	ds_read_b128 v[194:197], v2 offset:6144
	ds_read_b128 v[190:193], v2 offset:6656
	ds_read_b128 v[186:189], v2 offset:8192
	v_max3_f32 v19, v82, v83, v84
	v_max3_f32 v26, v85, v86, v87
	v_max3_f32 v19, v19, v88, v89
	v_max3_f32 v26, v26, v90, v91
	v_max3_f32 v19, v19, v92, v93
	v_mfma_f32_32x32x16_bf16 v[50:65], v[150:153], v[244:247], v[50:65]
	ds_read_b128 v[182:185], v2 offset:8704
	ds_read_b128 v[178:181], v2 offset:10240
	ds_read_b128 v[174:177], v2 offset:10752
	v_max3_f32 v26, v26, v94, v95
	v_max3_f32 v19, v19, v96, v97
	v_max3_f32 v26, v26, v98, v99
	v_max3_f32 v19, v19, v100, v101
	v_max3_f32 v26, v26, v102, v103
	v_mfma_f32_32x32x16_bf16 v[34:49], v[158:161], v[122:125], v[34:49]
	v_max3_f32 v19, v19, v104, v105
	v_max3_f32 v26, v26, v106, v107
	v_max3_f32 v19, v19, v108, v109
	v_max3_f32 v26, v26, v110, v111
	v_mfma_f32_32x32x16_bf16 v[50:65], v[158:161], v[248:251], v[50:65]
	v_max3_f32 v19, v19, v112, v113
	v_max_f32_e32 v19, v19, v26
	v_mfma_f32_32x32x16_bf16 v[34:49], v[166:169], v[126:129], v[34:49]
	v_mfma_f32_32x32x16_bf16 v[50:65], v[166:169], v[20:23], v[50:65]
	v_cmp_lt_f32_e32 vcc, s41, v19
	s_cbranch_vccz .Lsm_nors_6
	s_nop 15
	s_nop 15
	v_mov_b32_e32 v26, v19
	s_nop 1
	v_permlane32_swap_b32_e32 v19, v26
	v_max_f32_e32 v19, v19, v26
	v_max_f32_e32 v19, v19, v19
	v_max_f32_e32 v150, 0, v19
	v_exp_f32_e64 v151, -v150
	v_add_f32_e32 v239, v239, v150
	v_xor_b32_e32 v66, 0x80000000, v239
	v_mov_b32_e32 v67, v66
	v_mov_b32_e32 v68, v66
	v_mov_b32_e32 v69, v66
	v_mov_b32_e32 v70, v66
	v_mov_b32_e32 v71, v66
	v_mov_b32_e32 v72, v66
	v_mov_b32_e32 v73, v66
	v_mov_b32_e32 v74, v66
	v_mov_b32_e32 v75, v66
	v_mov_b32_e32 v76, v66
	v_mov_b32_e32 v77, v66
	v_mov_b32_e32 v78, v66
	v_mov_b32_e32 v79, v66
	v_mov_b32_e32 v80, v66
	v_mov_b32_e32 v81, v66
	v_sub_f32_e32 v82, v82, v150
	v_sub_f32_e32 v83, v83, v150
	v_sub_f32_e32 v84, v84, v150
	v_sub_f32_e32 v85, v85, v150
	v_sub_f32_e32 v86, v86, v150
	v_sub_f32_e32 v87, v87, v150
	v_sub_f32_e32 v88, v88, v150
	v_sub_f32_e32 v89, v89, v150
	v_sub_f32_e32 v90, v90, v150
	v_sub_f32_e32 v91, v91, v150
	v_sub_f32_e32 v92, v92, v150
	v_sub_f32_e32 v93, v93, v150
	v_sub_f32_e32 v94, v94, v150
	v_sub_f32_e32 v95, v95, v150
	v_sub_f32_e32 v96, v96, v150
	v_sub_f32_e32 v97, v97, v150
	v_sub_f32_e32 v98, v98, v150
	v_sub_f32_e32 v99, v99, v150
	v_sub_f32_e32 v100, v100, v150
	v_sub_f32_e32 v101, v101, v150
	v_sub_f32_e32 v102, v102, v150
	v_sub_f32_e32 v103, v103, v150
	v_sub_f32_e32 v104, v104, v150
	v_sub_f32_e32 v105, v105, v150
	v_sub_f32_e32 v106, v106, v150
	v_sub_f32_e32 v107, v107, v150
	v_sub_f32_e32 v108, v108, v150
	v_sub_f32_e32 v109, v109, v150
	v_sub_f32_e32 v110, v110, v150
	v_sub_f32_e32 v111, v111, v150
	v_sub_f32_e32 v112, v112, v150
	v_sub_f32_e32 v113, v113, v150
	v_mul_f32_e32 v236, v236, v151
	s_mov_b64 s[96:97], exec
	s_and_b64 exec, exec, s[8:9]
	ds_write_b32 v235, v151
	s_mov_b64 exec, s[96:97]
	v_lshl_add_u32 v2, v228, 4, s47
	ds_read_b128 v[154:157], v2 offset:0
	s_waitcnt lgkmcnt(0)
	v_mul_f32_e32 v34, v34, v154
	v_mul_f32_e32 v50, v50, v154
	v_mul_f32_e32 v35, v35, v155
	v_mul_f32_e32 v51, v51, v155
	v_mul_f32_e32 v36, v36, v156
	v_mul_f32_e32 v52, v52, v156
	v_mul_f32_e32 v37, v37, v157
	v_mul_f32_e32 v53, v53, v157
	ds_read_b128 v[154:157], v2 offset:32
	s_waitcnt lgkmcnt(0)
	v_mul_f32_e32 v38, v38, v154
	v_mul_f32_e32 v54, v54, v154
	v_mul_f32_e32 v39, v39, v155
	v_mul_f32_e32 v55, v55, v155
	v_mul_f32_e32 v40, v40, v156
	v_mul_f32_e32 v56, v56, v156
	v_mul_f32_e32 v41, v41, v157
	v_mul_f32_e32 v57, v57, v157
	ds_read_b128 v[154:157], v2 offset:64
	s_waitcnt lgkmcnt(0)
	v_mul_f32_e32 v42, v42, v154
	v_mul_f32_e32 v58, v58, v154
	v_mul_f32_e32 v43, v43, v155
	v_mul_f32_e32 v59, v59, v155
	v_mul_f32_e32 v44, v44, v156
	v_mul_f32_e32 v60, v60, v156
	v_mul_f32_e32 v45, v45, v157
	v_mul_f32_e32 v61, v61, v157
	ds_read_b128 v[154:157], v2 offset:96
	s_waitcnt lgkmcnt(0)
	v_mul_f32_e32 v46, v46, v154
	v_mul_f32_e32 v62, v62, v154
	v_mul_f32_e32 v47, v47, v155
	v_mul_f32_e32 v63, v63, v155
	v_mul_f32_e32 v48, v48, v156
	v_mul_f32_e32 v64, v64, v156
	v_mul_f32_e32 v49, v49, v157
	v_mul_f32_e32 v65, v65, v157
.Lsm_nors_6:
	s_add_i32 s78, s78, 1
	s_add_i32 s79, s79, -1
	s_cmp_gt_i32 s79, 0
	s_cbranch_scc1 .Lsm_loop
	s_waitcnt vmcnt(3)
	s_cmp_lt_u32 s78, 62
	s_cbranch_scc1 .Lsm_w_7
	s_waitcnt vmcnt(0)

.Lsm_dk_11:
	s_and_b32 s17, s78, 3
	s_lshl_b32 s17, s17, 13
	v_add_u32_e32 v2, s17, v237
	v_mfma_f32_32x32x16_bf16 v[82:97], v[218:221], v[4:7], v[66:81]
	v_exp_f32_e32 v142, v142
	v_exp_f32_e32 v143, v143
	v_exp_f32_e32 v144, v144
	v_add_f32_e32 v27, v142, v143
	v_exp_f32_e32 v145, v145
	ds_read_b64_tr_b16 v[114:115], v2 offset:49152
	ds_read_b64_tr_b16 v[116:117], v2 offset:49664
	ds_read_b64_tr_b16 v[118:119], v2 offset:50176
	ds_read_b64_tr_b16 v[120:121], v2 offset:50688
	v_mfma_f32_32x32x16_bf16 v[98:113], v[214:217], v[4:7], v[66:81]
	v_exp_f32_e32 v146, v146
	v_add_f32_e32 v27, v27, v144
	v_exp_f32_e32 v147, v147
	v_add_f32_e32 v27, v27, v145
	v_exp_f32_e32 v148, v148
	ds_read_b64_tr_b16 v[122:123], v2 offset:51200
	ds_read_b64_tr_b16 v[124:125], v2 offset:51712
	ds_read_b64_tr_b16 v[126:127], v2 offset:52224
	ds_read_b64_tr_b16 v[128:129], v2 offset:52736
	v_mfma_f32_32x32x16_bf16 v[82:97], v[210:213], v[8:11], v[82:97]
	v_add_f32_e32 v27, v27, v146
	v_exp_f32_e32 v149, v149
	v_add_f32_e32 v27, v27, v147
	v_add_f32_e32 v27, v27, v148
	v_add_f32_e32 v27, v27, v149
	ds_read_b64_tr_b16 v[240:241], v2 offset:53248
	ds_read_b64_tr_b16 v[242:243], v2 offset:53760
	ds_read_b64_tr_b16 v[244:245], v2 offset:54272
	ds_read_b64_tr_b16 v[246:247], v2 offset:54784
	v_mfma_f32_32x32x16_bf16 v[98:113], v[206:209], v[8:11], v[98:113]
	v_cvt_pk_bf16_f32 v142, v142, v143
	v_cvt_pk_bf16_f32 v143, v144, v145
	v_cvt_pk_bf16_f32 v144, v146, v147
	v_cvt_pk_bf16_f32 v145, v148, v149
	ds_read_b64_tr_b16 v[248:249], v2 offset:55296
	ds_read_b64_tr_b16 v[250:251], v2 offset:55808
	ds_read_b64_tr_b16 v[20:21], v2 offset:56320
	ds_read_b64_tr_b16 v[22:23], v2 offset:56832
	v_mfma_f32_32x32x16_bf16 v[82:97], v[202:205], v[12:15], v[82:97]
	v_exp_f32_e32 v150, v150
	v_exp_f32_e32 v151, v151
	v_exp_f32_e32 v152, v152
	v_add_f32_e32 v27, v27, v150
	v_exp_f32_e32 v153, v153
	v_mfma_f32_32x32x16_bf16 v[98:113], v[198:201], v[12:15], v[98:113]
	v_add_f32_e32 v27, v27, v151
	v_exp_f32_e32 v154, v154
	v_add_f32_e32 v27, v27, v152
	v_exp_f32_e32 v155, v155
	v_add_f32_e32 v27, v27, v153
	v_mfma_f32_32x32x16_bf16 v[82:97], v[194:197], v[130:133], v[82:97]
	v_exp_f32_e32 v156, v156
	v_add_f32_e32 v27, v27, v154
	v_exp_f32_e32 v157, v157
	v_add_f32_e32 v27, v27, v155
	v_add_f32_e32 v27, v27, v156
	v_mfma_f32_32x32x16_bf16 v[98:113], v[190:193], v[130:133], v[98:113]
	v_add_f32_e32 v27, v27, v157
	v_cvt_pk_bf16_f32 v150, v150, v151
	v_cvt_pk_bf16_f32 v151, v152, v153
	v_cvt_pk_bf16_f32 v152, v154, v155
	v_cvt_pk_bf16_f32 v153, v156, v157
	v_mfma_f32_32x32x16_bf16 v[82:97], v[186:189], v[134:137], v[82:97]
	v_exp_f32_e32 v158, v158
	v_exp_f32_e32 v159, v159
	v_exp_f32_e32 v160, v160
	v_add_f32_e32 v27, v27, v158
	v_exp_f32_e32 v161, v161
	v_mfma_f32_32x32x16_bf16 v[98:113], v[182:185], v[134:137], v[98:113]
	v_add_f32_e32 v27, v27, v159
	v_exp_f32_e32 v162, v162
	v_add_f32_e32 v27, v27, v160
	v_exp_f32_e32 v163, v163
	v_add_f32_e32 v27, v27, v161
	v_mfma_f32_32x32x16_bf16 v[82:97], v[178:181], v[138:141], v[82:97]
	v_exp_f32_e32 v164, v164
	v_add_f32_e32 v27, v27, v162
	v_exp_f32_e32 v165, v165
	v_add_f32_e32 v27, v27, v163
	v_add_f32_e32 v27, v27, v164
	v_mfma_f32_32x32x16_bf16 v[98:113], v[174:177], v[138:141], v[98:113]
	v_add_f32_e32 v27, v27, v165
	v_cvt_pk_bf16_f32 v158, v158, v159
	v_cvt_pk_bf16_f32 v159, v160, v161
	v_cvt_pk_bf16_f32 v160, v162, v163
	v_cvt_pk_bf16_f32 v161, v164, v165
	s_waitcnt lgkmcnt(0)
	v_mfma_f32_32x32x16_bf16 v[34:49], v[142:145], v[114:117], v[34:49]
	v_exp_f32_e32 v166, v166
	v_exp_f32_e32 v167, v167
	v_exp_f32_e32 v168, v168
	v_add_f32_e32 v27, v27, v166
	v_exp_f32_e32 v169, v169
	v_add_f32_e32 v27, v27, v167
	v_exp_f32_e32 v170, v170
	v_add_f32_e32 v27, v27, v168
	v_exp_f32_e32 v171, v171
	v_add_f32_e32 v27, v27, v169
	v_mfma_f32_32x32x16_bf16 v[50:65], v[142:145], v[240:243], v[50:65]
	v_exp_f32_e32 v172, v172
	v_add_f32_e32 v27, v27, v170
	v_exp_f32_e32 v173, v173
	v_add_f32_e32 v27, v27, v171
	v_add_f32_e32 v27, v27, v172
	v_add_f32_e32 v27, v27, v173
	v_cvt_pk_bf16_f32 v166, v166, v167
	v_cvt_pk_bf16_f32 v167, v168, v169
	v_cvt_pk_bf16_f32 v168, v170, v171
	v_cvt_pk_bf16_f32 v169, v172, v173
	v_add_f32_e32 v236, v236, v27
	v_mfma_f32_32x32x16_bf16 v[34:49], v[150:153], v[118:121], v[34:49]
	v_mfma_f32_32x32x16_bf16 v[50:65], v[150:153], v[244:247], v[50:65]
	v_mfma_f32_32x32x16_bf16 v[34:49], v[158:161], v[122:125], v[34:49]
	v_mov_b32_e32 v98, 0xff800000
	v_mov_b32_e32 v99, 0xff800000
	v_mov_b32_e32 v100, 0xff800000
	v_mov_b32_e32 v101, 0xff800000
	v_mov_b32_e32 v102, 0xff800000
	v_mov_b32_e32 v103, 0xff800000
	v_mov_b32_e32 v104, 0xff800000
	v_mov_b32_e32 v105, 0xff800000
	v_mov_b32_e32 v106, 0xff800000
	v_mov_b32_e32 v107, 0xff800000
	v_mov_b32_e32 v108, 0xff800000
	v_mov_b32_e32 v109, 0xff800000
	v_mov_b32_e32 v110, 0xff800000
	v_mov_b32_e32 v111, 0xff800000
	v_mov_b32_e32 v112, 0xff800000
	v_mov_b32_e32 v113, 0xff800000
	v_mfma_f32_32x32x16_bf16 v[50:65], v[158:161], v[248:251], v[50:65]
	v_max3_f32 v19, v82, v83, v84
	v_max3_f32 v26, v85, v86, v87
	v_max3_f32 v19, v19, v88, v89
	v_max3_f32 v26, v26, v90, v91
	v_max3_f32 v19, v19, v92, v93
	v_max3_f32 v26, v26, v94, v95
	v_max3_f32 v19, v19, v96, v97
	v_max_f32_e32 v19, v19, v26
	v_mfma_f32_32x32x16_bf16 v[34:49], v[166:169], v[126:129], v[34:49]
	v_mfma_f32_32x32x16_bf16 v[50:65], v[166:169], v[20:23], v[50:65]
	v_cmp_lt_f32_e32 vcc, s41, v19
	s_cbranch_vccz .Lsm_nors_12
	s_nop 15
	s_nop 15
	v_mov_b32_e32 v26, v19
	s_nop 1
	v_permlane32_swap_b32_e32 v19, v26
	v_max_f32_e32 v19, v19, v26
	v_max_f32_e32 v19, v19, v19
	v_max_f32_e32 v150, 0, v19
	v_exp_f32_e64 v151, -v150
	v_add_f32_e32 v239, v239, v150
	v_xor_b32_e32 v66, 0x80000000, v239
	v_mov_b32_e32 v67, v66
	v_mov_b32_e32 v68, v66
	v_mov_b32_e32 v69, v66
	v_mov_b32_e32 v70, v66
	v_mov_b32_e32 v71, v66
	v_mov_b32_e32 v72, v66
	v_mov_b32_e32 v73, v66
	v_mov_b32_e32 v74, v66
	v_mov_b32_e32 v75, v66
	v_mov_b32_e32 v76, v66
	v_mov_b32_e32 v77, v66
	v_mov_b32_e32 v78, v66
	v_mov_b32_e32 v79, v66
	v_mov_b32_e32 v80, v66
	v_mov_b32_e32 v81, v66
	v_sub_f32_e32 v82, v82, v150
	v_sub_f32_e32 v83, v83, v150
	v_sub_f32_e32 v84, v84, v150
	v_sub_f32_e32 v85, v85, v150
	v_sub_f32_e32 v86, v86, v150
	v_sub_f32_e32 v87, v87, v150
	v_sub_f32_e32 v88, v88, v150
	v_sub_f32_e32 v89, v89, v150
	v_sub_f32_e32 v90, v90, v150
	v_sub_f32_e32 v91, v91, v150
	v_sub_f32_e32 v92, v92, v150
	v_sub_f32_e32 v93, v93, v150
	v_sub_f32_e32 v94, v94, v150
	v_sub_f32_e32 v95, v95, v150
	v_sub_f32_e32 v96, v96, v150
	v_sub_f32_e32 v97, v97, v150
	v_sub_f32_e32 v98, v98, v150
	v_sub_f32_e32 v99, v99, v150
	v_sub_f32_e32 v100, v100, v150
	v_sub_f32_e32 v101, v101, v150
	v_sub_f32_e32 v102, v102, v150
	v_sub_f32_e32 v103, v103, v150
	v_sub_f32_e32 v104, v104, v150
	v_sub_f32_e32 v105, v105, v150
	v_sub_f32_e32 v106, v106, v150
	v_sub_f32_e32 v107, v107, v150
	v_sub_f32_e32 v108, v108, v150
	v_sub_f32_e32 v109, v109, v150
	v_sub_f32_e32 v110, v110, v150
	v_sub_f32_e32 v111, v111, v150
	v_sub_f32_e32 v112, v112, v150
	v_sub_f32_e32 v113, v113, v150
	v_mul_f32_e32 v236, v236, v151
	s_mov_b64 s[96:97], exec
	s_and_b64 exec, exec, s[8:9]
	ds_write_b32 v235, v151
	s_mov_b64 exec, s[96:97]
	v_lshl_add_u32 v2, v228, 4, s47
	ds_read_b128 v[154:157], v2 offset:0
	s_waitcnt lgkmcnt(0)
	v_mul_f32_e32 v34, v34, v154
	v_mul_f32_e32 v50, v50, v154
	v_mul_f32_e32 v35, v35, v155
	v_mul_f32_e32 v51, v51, v155
	v_mul_f32_e32 v36, v36, v156
	v_mul_f32_e32 v52, v52, v156
	v_mul_f32_e32 v37, v37, v157
	v_mul_f32_e32 v53, v53, v157
	ds_read_b128 v[154:157], v2 offset:32
	s_waitcnt lgkmcnt(0)
	v_mul_f32_e32 v38, v38, v154
	v_mul_f32_e32 v54, v54, v154
	v_mul_f32_e32 v39, v39, v155
	v_mul_f32_e32 v55, v55, v155
	v_mul_f32_e32 v40, v40, v156
	v_mul_f32_e32 v56, v56, v156
	v_mul_f32_e32 v41, v41, v157
	v_mul_f32_e32 v57, v57, v157
	ds_read_b128 v[154:157], v2 offset:64
	s_waitcnt lgkmcnt(0)
	v_mul_f32_e32 v42, v42, v154
	v_mul_f32_e32 v58, v58, v154
	v_mul_f32_e32 v43, v43, v155
	v_mul_f32_e32 v59, v59, v155
	v_mul_f32_e32 v44, v44, v156
	v_mul_f32_e32 v60, v60, v156
	v_mul_f32_e32 v45, v45, v157
	v_mul_f32_e32 v61, v61, v157
	ds_read_b128 v[154:157], v2 offset:96
	s_waitcnt lgkmcnt(0)
	v_mul_f32_e32 v46, v46, v154
	v_mul_f32_e32 v62, v62, v154
	v_mul_f32_e32 v47, v47, v155
	v_mul_f32_e32 v63, v63, v155
	v_mul_f32_e32 v48, v48, v156
	v_mul_f32_e32 v64, v64, v156
	v_mul_f32_e32 v49, v49, v157
	v_mul_f32_e32 v65, v65, v157

.Lsm_dk_14:
	s_and_b32 s17, s78, 3
	s_lshl_b32 s17, s17, 13
	v_add_u32_e32 v2, s17, v237
	ds_read_b64_tr_b16 v[114:115], v2 offset:49152
	ds_read_b64_tr_b16 v[116:117], v2 offset:49664
	ds_read_b64_tr_b16 v[118:119], v2 offset:50176
	ds_read_b64_tr_b16 v[120:121], v2 offset:50688
	ds_read_b64_tr_b16 v[122:123], v2 offset:51200
	ds_read_b64_tr_b16 v[124:125], v2 offset:51712
	ds_read_b64_tr_b16 v[126:127], v2 offset:52224
	ds_read_b64_tr_b16 v[128:129], v2 offset:52736
	ds_read_b64_tr_b16 v[240:241], v2 offset:53248
	ds_read_b64_tr_b16 v[242:243], v2 offset:53760
	ds_read_b64_tr_b16 v[244:245], v2 offset:54272
	ds_read_b64_tr_b16 v[246:247], v2 offset:54784
	ds_read_b64_tr_b16 v[248:249], v2 offset:55296
	ds_read_b64_tr_b16 v[250:251], v2 offset:55808
	ds_read_b64_tr_b16 v[20:21], v2 offset:56320
	ds_read_b64_tr_b16 v[22:23], v2 offset:56832
	v_exp_f32_e32 v82, v82
	v_exp_f32_e32 v83, v83
	v_exp_f32_e32 v84, v84
	v_add_f32_e32 v27, v82, v83
	v_exp_f32_e32 v85, v85
	v_exp_f32_e32 v86, v86
	v_add_f32_e32 v27, v27, v84
	v_exp_f32_e32 v87, v87
	v_add_f32_e32 v27, v27, v85
	v_exp_f32_e32 v88, v88
	v_add_f32_e32 v27, v27, v86
	v_exp_f32_e32 v89, v89
	v_add_f32_e32 v27, v27, v87
	v_add_f32_e32 v27, v27, v88
	v_add_f32_e32 v27, v27, v89
	v_cvt_pk_bf16_f32 v82, v82, v83
	v_cvt_pk_bf16_f32 v83, v84, v85
	v_cvt_pk_bf16_f32 v84, v86, v87
	v_cvt_pk_bf16_f32 v85, v88, v89
	v_exp_f32_e32 v90, v90
	v_exp_f32_e32 v91, v91
	v_exp_f32_e32 v92, v92
	v_add_f32_e32 v27, v27, v90
	v_exp_f32_e32 v93, v93
	v_add_f32_e32 v27, v27, v91
	v_exp_f32_e32 v94, v94
	v_add_f32_e32 v27, v27, v92
	v_exp_f32_e32 v95, v95
	v_add_f32_e32 v27, v27, v93
	v_exp_f32_e32 v96, v96
	v_add_f32_e32 v27, v27, v94
	v_exp_f32_e32 v97, v97
	v_add_f32_e32 v27, v27, v95
	v_add_f32_e32 v27, v27, v96
	v_add_f32_e32 v27, v27, v97
	v_cvt_pk_bf16_f32 v90, v90, v91
	v_cvt_pk_bf16_f32 v91, v92, v93
	v_cvt_pk_bf16_f32 v92, v94, v95
	v_cvt_pk_bf16_f32 v93, v96, v97
	s_waitcnt lgkmcnt(0)
	v_mfma_f32_32x32x16_bf16 v[34:49], v[82:85], v[114:117], v[34:49]
	v_mfma_f32_32x32x16_bf16 v[50:65], v[82:85], v[240:243], v[50:65]
	v_exp_f32_e32 v98, v98
	v_exp_f32_e32 v99, v99
	v_exp_f32_e32 v100, v100
	v_add_f32_e32 v27, v27, v98
	v_exp_f32_e32 v101, v101
	v_add_f32_e32 v27, v27, v99
	v_exp_f32_e32 v102, v102
	v_add_f32_e32 v27, v27, v100
	v_exp_f32_e32 v103, v103
	v_add_f32_e32 v27, v27, v101
	v_exp_f32_e32 v104, v104
	v_add_f32_e32 v27, v27, v102
	v_exp_f32_e32 v105, v105
	v_add_f32_e32 v27, v27, v103
	v_add_f32_e32 v27, v27, v104
	v_add_f32_e32 v27, v27, v105
	v_cvt_pk_bf16_f32 v98, v98, v99
	v_cvt_pk_bf16_f32 v99, v100, v101
	v_cvt_pk_bf16_f32 v100, v102, v103
	v_cvt_pk_bf16_f32 v101, v104, v105
	v_mfma_f32_32x32x16_bf16 v[34:49], v[90:93], v[118:121], v[34:49]
	v_mfma_f32_32x32x16_bf16 v[50:65], v[90:93], v[244:247], v[50:65]
	v_exp_f32_e32 v106, v106
	v_exp_f32_e32 v107, v107
	v_exp_f32_e32 v108, v108
	v_add_f32_e32 v27, v27, v106
	v_exp_f32_e32 v109, v109
	v_add_f32_e32 v27, v27, v107
	v_exp_f32_e32 v110, v110
	v_add_f32_e32 v27, v27, v108
	v_exp_f32_e32 v111, v111
	v_add_f32_e32 v27, v27, v109
	v_exp_f32_e32 v112, v112
	v_add_f32_e32 v27, v27, v110
	v_exp_f32_e32 v113, v113
	v_add_f32_e32 v27, v27, v111
	v_add_f32_e32 v27, v27, v112
	v_add_f32_e32 v27, v27, v113
	v_cvt_pk_bf16_f32 v106, v106, v107
	v_cvt_pk_bf16_f32 v107, v108, v109
	v_cvt_pk_bf16_f32 v108, v110, v111
	v_cvt_pk_bf16_f32 v109, v112, v113
	v_add_f32_e32 v236, v236, v27
	s_nop 1
	v_mfma_f32_32x32x16_bf16 v[34:49], v[98:101], v[122:125], v[34:49]
	v_mfma_f32_32x32x16_bf16 v[50:65], v[98:101], v[248:251], v[50:65]
	v_mfma_f32_32x32x16_bf16 v[34:49], v[106:109], v[126:129], v[34:49]
	v_mfma_f32_32x32x16_bf16 v[50:65], v[106:109], v[20:23], v[50:65]
	s_add_i32 s78, s78, 1
	s_branch .Lsm_done
.Lsm_A_skel:
	s_mov_b32 s79, 65

.Lsm_dk_16:
	s_add_i32 s78, s78, 1
	s_add_i32 s79, s79, -1
	s_cmp_gt_i32 s79, 0
	s_cbranch_scc1 .Lsm_A_skel_loop
	s_branch .Lsm_done
.Lsm_B:
	s_mov_b32 s0, 0x80000
	s_mov_b32 s1, 0
	v_lshl_add_u64 v[24:25], v[16:17], 0, s[0:1]
	s_mov_b32 s0, 0x60000
	v_lshl_add_u64 v[28:29], v[224:225], 0, s[0:1]
	s_mov_b32 s0, 0x4000
	v_lshl_add_u64 v[30:31], v[222:223], 0, s[0:1]
	s_mov_b32 s79, 65
.Lsm_B_skel_loop:
	s_waitcnt vmcnt(2)
	s_cmp_lt_u32 s78, 62
	s_cbranch_scc1 .Lsm_w_17
	s_waitcnt vmcnt(0)
.Lsm_w_17:
	s_waitcnt lgkmcnt(0)
	s_barrier
	s_cmp_gt_u32 s78, 61
	s_cbranch_scc1 .Lsm_dk_18
	s_add_i32 s0, s78, 3
	s_and_b32 s0, s0, 3
	s_lshl_b32 s0, s0, 13
	s_add_u32 m0, s57, s0
	s_cmp_gt_u32 s78, 60
	global_load_lds_dwordx4 v[28:29], off
	v_lshl_add_u64 v[28:29], v[28:29], 0, s[30:31]
	s_cbranch_scc1 .Lsm_dk_18
	s_and_b32 s0, s78, 3
	s_mulk_i32 s0, 0x3000
	s_add_u32 m0, s40, s0
	s_add_u32 s0, s43, s0
	global_load_lds_dwordx4 v[24:25], off
	v_lshl_add_u64 v[24:25], v[24:25], 0, s[30:31]
.Lsm_dk_18:
	s_add_i32 s78, s78, 1
	s_add_i32 s79, s79, -1
	s_cmp_gt_i32 s79, 0
	s_cbranch_scc1 .Lsm_B_skel_loop

.Lmy_A_entry:
	s_mov_b32 s30, 0x20000
	s_mov_b32 s31, 0
	s_mov_b32 s12, 0x1000
	s_mov_b32 s13, 0
	s_lshr_b32 s71, s24, 1
	s_lshr_b32 s79, s25, 2
	s_add_i32 s79, s79, -1
	s_barrier
	s_mov_b32 s0, 0x60000
	s_mov_b32 s1, 0
	v_lshl_add_u64 v[24:25], v[16:17], 0, s[0:1]
	s_add_u32 m0, s40, 0x9000
	s_mov_b32 s0, 0x3000
	global_load_lds_dwordx4 v[24:25], off
	v_lshl_add_u64 v[30:31], v[222:223], 0, s[0:1]
	s_add_u32 m0, s43, 0x9000
	s_nop 0
	global_load_lds_dwordx4 v[30:31], off
	s_mov_b32 s0, 0x80000
	s_mov_b32 s1, 0
	v_lshl_add_u64 v[24:25], v[16:17], 0, s[0:1]
	s_mov_b32 s0, 0x60000
	v_lshl_add_u64 v[28:29], v[224:225], 0, s[0:1]
	s_mov_b32 s0, 0x4000
	v_lshl_add_u64 v[30:31], v[222:223], 0, s[0:1]
	s_waitcnt lgkmcnt(0)
	v_mfma_f32_32x32x16_bf16 v[82:97], v[218:221], v[4:7], v[66:81]
	v_mfma_f32_32x32x16_bf16 v[98:113], v[214:217], v[4:7], v[66:81]
	v_mfma_f32_32x32x16_bf16 v[82:97], v[210:213], v[8:11], v[82:97]
	v_mfma_f32_32x32x16_bf16 v[98:113], v[206:209], v[8:11], v[98:113]
	v_mfma_f32_32x32x16_bf16 v[82:97], v[202:205], v[12:15], v[82:97]
	v_mfma_f32_32x32x16_bf16 v[98:113], v[198:201], v[12:15], v[98:113]
	v_mfma_f32_32x32x16_bf16 v[82:97], v[194:197], v[130:133], v[82:97]
	v_mfma_f32_32x32x16_bf16 v[98:113], v[190:193], v[130:133], v[98:113]
	v_mfma_f32_32x32x16_bf16 v[82:97], v[186:189], v[134:137], v[82:97]
	v_mfma_f32_32x32x16_bf16 v[98:113], v[182:185], v[134:137], v[98:113]
	v_mfma_f32_32x32x16_bf16 v[82:97], v[178:181], v[138:141], v[82:97]
	v_mfma_f32_32x32x16_bf16 v[98:113], v[174:177], v[138:141], v[98:113]
	v_add_u32_e32 v2, 0x3000, v238
	ds_read_b128 v[218:221], v2
	ds_read_b128 v[214:217], v2 offset:512
	ds_read_b128 v[210:213], v2 offset:2048
	ds_read_b128 v[206:209], v2 offset:2560
	ds_read_b128 v[202:205], v2 offset:4096
	ds_read_b128 v[198:201], v2 offset:4608
	ds_read_b128 v[194:197], v2 offset:6144
	ds_read_b128 v[190:193], v2 offset:6656
	ds_read_b128 v[186:189], v2 offset:8192
	ds_read_b128 v[182:185], v2 offset:8704
	ds_read_b128 v[178:181], v2 offset:10240
	ds_read_b128 v[174:177], v2 offset:10752
	s_nop 7
	v_max3_f32 v19, v82, v83, v84
	v_max3_f32 v26, v85, v86, v87
	v_max3_f32 v19, v19, v88, v89
	v_max3_f32 v26, v26, v90, v91
	v_max3_f32 v19, v19, v92, v93
	v_max3_f32 v26, v26, v94, v95
	v_max3_f32 v19, v19, v96, v97
	v_max3_f32 v26, v26, v98, v99
	v_max3_f32 v19, v19, v100, v101
	v_max3_f32 v26, v26, v102, v103
	v_max3_f32 v19, v19, v104, v105
	v_max3_f32 v26, v26, v106, v107
	v_max3_f32 v19, v19, v108, v109
	v_max3_f32 v26, v26, v110, v111
	v_max3_f32 v19, v19, v112, v113
	v_max_f32_e32 v19, v19, v26
	v_mov_b32_e32 v26, v19
	s_nop 1
	v_permlane32_swap_b32_e32 v19, v26
	v_max_f32_e32 v19, v19, v26
	v_max_f32_e32 v19, v19, v19
	v_mov_b32_e32 v239, v19
	v_xor_b32_e32 v66, 0x80000000, v19
	v_mov_b32_e32 v67, v66
	v_mov_b32_e32 v68, v66
	v_mov_b32_e32 v69, v66
	v_mov_b32_e32 v70, v66
	v_mov_b32_e32 v71, v66
	v_mov_b32_e32 v72, v66
	v_mov_b32_e32 v73, v66
	v_mov_b32_e32 v74, v66
	v_mov_b32_e32 v75, v66
	v_mov_b32_e32 v76, v66
	v_mov_b32_e32 v77, v66
	v_mov_b32_e32 v78, v66
	v_mov_b32_e32 v79, v66
	v_mov_b32_e32 v80, v66
	v_mov_b32_e32 v81, v66
	v_sub_f32_e32 v82, v82, v19
	v_sub_f32_e32 v83, v83, v19
	v_sub_f32_e32 v84, v84, v19
	v_sub_f32_e32 v85, v85, v19
	v_sub_f32_e32 v86, v86, v19
	v_sub_f32_e32 v87, v87, v19
	v_sub_f32_e32 v88, v88, v19
	v_sub_f32_e32 v89, v89, v19
	v_sub_f32_e32 v90, v90, v19
	v_sub_f32_e32 v91, v91, v19
	v_sub_f32_e32 v92, v92, v19
	v_sub_f32_e32 v93, v93, v19
	v_sub_f32_e32 v94, v94, v19
	v_sub_f32_e32 v95, v95, v19
	v_sub_f32_e32 v96, v96, v19
	v_sub_f32_e32 v97, v97, v19
	v_sub_f32_e32 v98, v98, v19
	v_sub_f32_e32 v99, v99, v19
	v_sub_f32_e32 v100, v100, v19
	v_sub_f32_e32 v101, v101, v19
	v_sub_f32_e32 v102, v102, v19
	v_sub_f32_e32 v103, v103, v19
	v_sub_f32_e32 v104, v104, v19
	v_sub_f32_e32 v105, v105, v19
	v_sub_f32_e32 v106, v106, v19
	v_sub_f32_e32 v107, v107, v19
	v_sub_f32_e32 v108, v108, v19
	v_sub_f32_e32 v109, v109, v19
	v_sub_f32_e32 v110, v110, v19
	v_sub_f32_e32 v111, v111, v19
	v_sub_f32_e32 v112, v112, v19
	v_sub_f32_e32 v113, v113, v19
	s_cmp_lt_i32 s79, 1
	s_cbranch_scc1 .Lmy_A_tail
	s_waitcnt lgkmcnt(0)
	v_mov_b32_e32 v2, v237
	v_mfma_f32_32x32x16_bf16 v[142:157], v[218:221], v[4:7], v[66:81]
	v_exp_f32_e32 v82, v82
	v_exp_f32_e32 v83, v83
	v_exp_f32_e32 v84, v84
	v_add_f32_e32 v27, v82, v83
	v_exp_f32_e32 v85, v85
	ds_read_b64_tr_b16 v[114:115], v2 offset:49152
	ds_read_b64_tr_b16 v[116:117], v2 offset:49664
	ds_read_b64_tr_b16 v[118:119], v2 offset:50176
	ds_read_b64_tr_b16 v[120:121], v2 offset:50688
	v_mfma_f32_32x32x16_bf16 v[158:173], v[214:217], v[4:7], v[66:81]
	v_exp_f32_e32 v86, v86
	v_add_f32_e32 v27, v27, v84
	v_exp_f32_e32 v87, v87
	v_add_f32_e32 v27, v27, v85
	v_exp_f32_e32 v88, v88
	ds_read_b64_tr_b16 v[122:123], v2 offset:51200
	ds_read_b64_tr_b16 v[124:125], v2 offset:51712
	ds_read_b64_tr_b16 v[126:127], v2 offset:52224
	ds_read_b64_tr_b16 v[128:129], v2 offset:52736
	v_mfma_f32_32x32x16_bf16 v[142:157], v[210:213], v[8:11], v[142:157]
	v_add_f32_e32 v27, v27, v86
	v_exp_f32_e32 v89, v89
	v_add_f32_e32 v27, v27, v87
	v_add_f32_e32 v27, v27, v88
	v_add_f32_e32 v27, v27, v89
	ds_read_b64_tr_b16 v[240:241], v2 offset:53248
	ds_read_b64_tr_b16 v[242:243], v2 offset:53760
	ds_read_b64_tr_b16 v[244:245], v2 offset:54272
	ds_read_b64_tr_b16 v[246:247], v2 offset:54784
	v_mfma_f32_32x32x16_bf16 v[158:173], v[206:209], v[8:11], v[158:173]
	v_cvt_pk_bf16_f32 v82, v82, v83
	v_cvt_pk_bf16_f32 v83, v84, v85
	v_cvt_pk_bf16_f32 v84, v86, v87
	v_cvt_pk_bf16_f32 v85, v88, v89
	ds_read_b64_tr_b16 v[248:249], v2 offset:55296
	ds_read_b64_tr_b16 v[250:251], v2 offset:55808
	ds_read_b64_tr_b16 v[20:21], v2 offset:56320
	ds_read_b64_tr_b16 v[22:23], v2 offset:56832
	v_mfma_f32_32x32x16_bf16 v[142:157], v[202:205], v[12:15], v[142:157]
	v_exp_f32_e32 v90, v90
	v_exp_f32_e32 v91, v91
	v_exp_f32_e32 v92, v92
	v_add_f32_e32 v27, v27, v90
	v_exp_f32_e32 v93, v93
	v_mfma_f32_32x32x16_bf16 v[158:173], v[198:201], v[12:15], v[158:173]
	v_add_f32_e32 v27, v27, v91
	v_exp_f32_e32 v94, v94
	v_add_f32_e32 v27, v27, v92
	v_exp_f32_e32 v95, v95
	v_add_f32_e32 v27, v27, v93
	s_waitcnt vmcnt(3)
	s_barrier
	v_mfma_f32_32x32x16_bf16 v[142:157], v[194:197], v[130:133], v[142:157]
	s_add_u32 m0, s57, 0x6000
	v_exp_f32_e32 v96, v96
	v_add_f32_e32 v27, v27, v94
	global_load_lds_dwordx4 v[28:29], off
	v_lshl_add_u64 v[28:29], v[28:29], 0, s[30:31]
	v_exp_f32_e32 v97, v97
	v_add_f32_e32 v27, v27, v95
	v_add_f32_e32 v27, v27, v96
	v_mfma_f32_32x32x16_bf16 v[158:173], v[190:193], v[130:133], v[158:173]
	s_add_u32 m0, s40, 0x0
	v_add_f32_e32 v27, v27, v97
	v_cvt_pk_bf16_f32 v90, v90, v91
	global_load_lds_dwordx4 v[24:25], off
	v_lshl_add_u64 v[24:25], v[24:25], 0, s[30:31]
	v_cvt_pk_bf16_f32 v91, v92, v93
	v_cvt_pk_bf16_f32 v92, v94, v95
	v_cvt_pk_bf16_f32 v93, v96, v97
	v_mfma_f32_32x32x16_bf16 v[142:157], v[186:189], v[134:137], v[142:157]
	s_add_u32 m0, s43, 0x0
	v_exp_f32_e32 v98, v98
	v_exp_f32_e32 v99, v99
	global_load_lds_dwordx4 v[30:31], off
	v_lshl_add_u64 v[30:31], v[30:31], 0, s[12:13]
	v_exp_f32_e32 v100, v100
	v_add_f32_e32 v27, v27, v98
	v_exp_f32_e32 v101, v101
	v_mfma_f32_32x32x16_bf16 v[158:173], v[182:185], v[134:137], v[158:173]
	s_add_u32 m0, s40, 0x3000
	v_add_f32_e32 v27, v27, v99
	v_exp_f32_e32 v102, v102
	global_load_lds_dwordx4 v[24:25], off
	v_lshl_add_u64 v[24:25], v[24:25], 0, s[30:31]
	v_add_f32_e32 v27, v27, v100
	v_exp_f32_e32 v103, v103
	v_add_f32_e32 v27, v27, v101
	v_mfma_f32_32x32x16_bf16 v[142:157], v[178:181], v[138:141], v[142:157]
	s_add_u32 m0, s43, 0x3000
	v_exp_f32_e32 v104, v104
	v_add_f32_e32 v27, v27, v102
	global_load_lds_dwordx4 v[30:31], off
	v_lshl_add_u64 v[30:31], v[30:31], 0, s[12:13]
	v_exp_f32_e32 v105, v105
	v_add_f32_e32 v27, v27, v103
	v_add_f32_e32 v27, v27, v104
	v_mfma_f32_32x32x16_bf16 v[158:173], v[174:177], v[138:141], v[158:173]
	v_add_f32_e32 v27, v27, v105
	v_cvt_pk_bf16_f32 v98, v98, v99
	v_cvt_pk_bf16_f32 v99, v100, v101
	v_cvt_pk_bf16_f32 v100, v102, v103
	v_cvt_pk_bf16_f32 v101, v104, v105
	s_waitcnt lgkmcnt(0)
	v_add_u32_e32 v2, 0x6000, v238
	v_mfma_f32_32x32x16_bf16 v[34:49], v[82:85], v[114:117], v[34:49]
	v_exp_f32_e32 v106, v106
	v_exp_f32_e32 v107, v107
	v_exp_f32_e32 v108, v108
	v_add_f32_e32 v27, v27, v106
	v_exp_f32_e32 v109, v109
	v_add_f32_e32 v27, v27, v107
	v_exp_f32_e32 v110, v110
	v_add_f32_e32 v27, v27, v108
	v_exp_f32_e32 v111, v111
	v_add_f32_e32 v27, v27, v109
	ds_read_b128 v[218:221], v2
	ds_read_b128 v[214:217], v2 offset:512
	ds_read_b128 v[210:213], v2 offset:2048
	v_mfma_f32_32x32x16_bf16 v[50:65], v[82:85], v[240:243], v[50:65]
	v_exp_f32_e32 v112, v112
	v_add_f32_e32 v27, v27, v110
	v_exp_f32_e32 v113, v113
	v_add_f32_e32 v27, v27, v111
	v_add_f32_e32 v27, v27, v112
	v_add_f32_e32 v27, v27, v113
	v_cvt_pk_bf16_f32 v106, v106, v107
	v_cvt_pk_bf16_f32 v107, v108, v109
	v_cvt_pk_bf16_f32 v108, v110, v111
	v_cvt_pk_bf16_f32 v109, v112, v113
	v_add_f32_e32 v236, v236, v27
	ds_read_b128 v[206:209], v2 offset:2560
	ds_read_b128 v[202:205], v2 offset:4096
	ds_read_b128 v[198:201], v2 offset:4608
	v_mfma_f32_32x32x16_bf16 v[34:49], v[90:93], v[118:121], v[34:49]
	ds_read_b128 v[194:197], v2 offset:6144
	ds_read_b128 v[190:193], v2 offset:6656
	ds_read_b128 v[186:189], v2 offset:8192
	v_max3_f32 v19, v142, v143, v144
	v_max3_f32 v26, v145, v146, v147
	v_max3_f32 v19, v19, v148, v149
	v_max3_f32 v26, v26, v150, v151
	v_max3_f32 v19, v19, v152, v153
	v_mfma_f32_32x32x16_bf16 v[50:65], v[90:93], v[244:247], v[50:65]
	ds_read_b128 v[182:185], v2 offset:8704
	ds_read_b128 v[178:181], v2 offset:10240
	ds_read_b128 v[174:177], v2 offset:10752
	v_max3_f32 v26, v26, v154, v155
	v_max3_f32 v19, v19, v156, v157
	v_max3_f32 v26, v26, v158, v159
	v_max3_f32 v19, v19, v160, v161
	v_max3_f32 v26, v26, v162, v163
	v_mfma_f32_32x32x16_bf16 v[34:49], v[98:101], v[122:125], v[34:49]
	v_max3_f32 v19, v19, v164, v165
	v_max3_f32 v26, v26, v166, v167
	v_max3_f32 v19, v19, v168, v169
	v_max3_f32 v26, v26, v170, v171
	v_mfma_f32_32x32x16_bf16 v[50:65], v[98:101], v[248:251], v[50:65]
	v_max3_f32 v19, v19, v172, v173
	v_max_f32_e32 v19, v19, v26
	v_mfma_f32_32x32x16_bf16 v[34:49], v[106:109], v[126:129], v[34:49]
	v_mfma_f32_32x32x16_bf16 v[50:65], v[106:109], v[20:23], v[50:65]
	v_cmp_lt_f32_e32 vcc, s41, v19
	s_cbranch_vccz .Lmy_nors_1
	s_nop 15
	s_nop 15
	v_mov_b32_e32 v26, v19
	s_nop 1
	v_permlane32_swap_b32_e32 v19, v26
	v_max_f32_e32 v19, v19, v26
	v_max_f32_e32 v19, v19, v19
	v_max_f32_e32 v90, 0, v19
	v_exp_f32_e64 v91, -v90
	v_add_f32_e32 v239, v239, v90
	v_xor_b32_e32 v66, 0x80000000, v239
	v_mov_b32_e32 v67, v66
	v_mov_b32_e32 v68, v66
	v_mov_b32_e32 v69, v66
	v_mov_b32_e32 v70, v66
	v_mov_b32_e32 v71, v66
	v_mov_b32_e32 v72, v66
	v_mov_b32_e32 v73, v66
	v_mov_b32_e32 v74, v66
	v_mov_b32_e32 v75, v66
	v_mov_b32_e32 v76, v66
	v_mov_b32_e32 v77, v66
	v_mov_b32_e32 v78, v66
	v_mov_b32_e32 v79, v66
	v_mov_b32_e32 v80, v66
	v_mov_b32_e32 v81, v66
	v_sub_f32_e32 v142, v142, v90
	v_sub_f32_e32 v143, v143, v90
	v_sub_f32_e32 v144, v144, v90
	v_sub_f32_e32 v145, v145, v90
	v_sub_f32_e32 v146, v146, v90
	v_sub_f32_e32 v147, v147, v90
	v_sub_f32_e32 v148, v148, v90
	v_sub_f32_e32 v149, v149, v90
	v_sub_f32_e32 v150, v150, v90
	v_sub_f32_e32 v151, v151, v90
	v_sub_f32_e32 v152, v152, v90
	v_sub_f32_e32 v153, v153, v90
	v_sub_f32_e32 v154, v154, v90
	v_sub_f32_e32 v155, v155, v90
	v_sub_f32_e32 v156, v156, v90
	v_sub_f32_e32 v157, v157, v90
	v_sub_f32_e32 v158, v158, v90
	v_sub_f32_e32 v159, v159, v90
	v_sub_f32_e32 v160, v160, v90
	v_sub_f32_e32 v161, v161, v90
	v_sub_f32_e32 v162, v162, v90
	v_sub_f32_e32 v163, v163, v90
	v_sub_f32_e32 v164, v164, v90
	v_sub_f32_e32 v165, v165, v90
	v_sub_f32_e32 v166, v166, v90
	v_sub_f32_e32 v167, v167, v90
	v_sub_f32_e32 v168, v168, v90
	v_sub_f32_e32 v169, v169, v90
	v_sub_f32_e32 v170, v170, v90
	v_sub_f32_e32 v171, v171, v90
	v_sub_f32_e32 v172, v172, v90
	v_sub_f32_e32 v173, v173, v90
	v_mul_f32_e32 v236, v236, v91
	s_mov_b64 s[96:97], exec
	s_and_b64 exec, exec, s[8:9]
	ds_write_b32 v235, v91
	s_mov_b64 exec, s[96:97]
	v_lshl_add_u32 v2, v228, 4, s47
	ds_read_b128 v[94:97], v2 offset:0
	s_waitcnt lgkmcnt(0)
	v_mul_f32_e32 v34, v34, v94
	v_mul_f32_e32 v50, v50, v94
	v_mul_f32_e32 v35, v35, v95
	v_mul_f32_e32 v51, v51, v95
	v_mul_f32_e32 v36, v36, v96
	v_mul_f32_e32 v52, v52, v96
	v_mul_f32_e32 v37, v37, v97
	v_mul_f32_e32 v53, v53, v97
	ds_read_b128 v[94:97], v2 offset:32
	s_waitcnt lgkmcnt(0)
	v_mul_f32_e32 v38, v38, v94
	v_mul_f32_e32 v54, v54, v94
	v_mul_f32_e32 v39, v39, v95
	v_mul_f32_e32 v55, v55, v95
	v_mul_f32_e32 v40, v40, v96
	v_mul_f32_e32 v56, v56, v96
	v_mul_f32_e32 v41, v41, v97
	v_mul_f32_e32 v57, v57, v97
	ds_read_b128 v[94:97], v2 offset:64
	s_waitcnt lgkmcnt(0)
	v_mul_f32_e32 v42, v42, v94
	v_mul_f32_e32 v58, v58, v94
	v_mul_f32_e32 v43, v43, v95
	v_mul_f32_e32 v59, v59, v95
	v_mul_f32_e32 v44, v44, v96
	v_mul_f32_e32 v60, v60, v96
	v_mul_f32_e32 v45, v45, v97
	v_mul_f32_e32 v61, v61, v97
	ds_read_b128 v[94:97], v2 offset:96
	s_waitcnt lgkmcnt(0)
	v_mul_f32_e32 v46, v46, v94
	v_mul_f32_e32 v62, v62, v94
	v_mul_f32_e32 v47, v47, v95
	v_mul_f32_e32 v63, v63, v95
	v_mul_f32_e32 v48, v48, v96
	v_mul_f32_e32 v64, v64, v96
	v_mul_f32_e32 v49, v49, v97
	v_mul_f32_e32 v65, v65, v97
.Lmy_nors_1:
	s_waitcnt lgkmcnt(0)
	v_add_u32_e32 v2, 0x2000, v237
	v_mfma_f32_32x32x16_bf16 v[82:97], v[218:221], v[4:7], v[66:81]
	v_exp_f32_e32 v142, v142
	v_exp_f32_e32 v143, v143
	v_exp_f32_e32 v144, v144
	v_add_f32_e32 v27, v142, v143
	v_exp_f32_e32 v145, v145
	ds_read_b64_tr_b16 v[114:115], v2 offset:49152
	ds_read_b64_tr_b16 v[116:117], v2 offset:49664
	ds_read_b64_tr_b16 v[118:119], v2 offset:50176
	ds_read_b64_tr_b16 v[120:121], v2 offset:50688
	v_mfma_f32_32x32x16_bf16 v[98:113], v[214:217], v[4:7], v[66:81]
	v_exp_f32_e32 v146, v146
	v_add_f32_e32 v27, v27, v144
	v_exp_f32_e32 v147, v147
	v_add_f32_e32 v27, v27, v145
	v_exp_f32_e32 v148, v148
	ds_read_b64_tr_b16 v[122:123], v2 offset:51200
	ds_read_b64_tr_b16 v[124:125], v2 offset:51712
	ds_read_b64_tr_b16 v[126:127], v2 offset:52224
	ds_read_b64_tr_b16 v[128:129], v2 offset:52736
	v_mfma_f32_32x32x16_bf16 v[82:97], v[210:213], v[8:11], v[82:97]
	v_add_f32_e32 v27, v27, v146
	v_exp_f32_e32 v149, v149
	v_add_f32_e32 v27, v27, v147
	v_add_f32_e32 v27, v27, v148
	v_add_f32_e32 v27, v27, v149
	ds_read_b64_tr_b16 v[240:241], v2 offset:53248
	ds_read_b64_tr_b16 v[242:243], v2 offset:53760
	ds_read_b64_tr_b16 v[244:245], v2 offset:54272
	ds_read_b64_tr_b16 v[246:247], v2 offset:54784
	v_mfma_f32_32x32x16_bf16 v[98:113], v[206:209], v[8:11], v[98:113]
	v_cvt_pk_bf16_f32 v142, v142, v143
	v_cvt_pk_bf16_f32 v143, v144, v145
	v_cvt_pk_bf16_f32 v144, v146, v147
	v_cvt_pk_bf16_f32 v145, v148, v149
	ds_read_b64_tr_b16 v[248:249], v2 offset:55296
	ds_read_b64_tr_b16 v[250:251], v2 offset:55808
	ds_read_b64_tr_b16 v[20:21], v2 offset:56320
	ds_read_b64_tr_b16 v[22:23], v2 offset:56832
	v_mfma_f32_32x32x16_bf16 v[82:97], v[202:205], v[12:15], v[82:97]
	v_exp_f32_e32 v150, v150
	v_exp_f32_e32 v151, v151
	v_exp_f32_e32 v152, v152
	v_add_f32_e32 v27, v27, v150
	v_exp_f32_e32 v153, v153
	v_mfma_f32_32x32x16_bf16 v[98:113], v[198:201], v[12:15], v[98:113]
	v_add_f32_e32 v27, v27, v151
	v_exp_f32_e32 v154, v154
	v_add_f32_e32 v27, v27, v152
	v_exp_f32_e32 v155, v155
	v_add_f32_e32 v27, v27, v153
	s_waitcnt vmcnt(5)
	s_barrier
	v_mfma_f32_32x32x16_bf16 v[82:97], v[194:197], v[130:133], v[82:97]
	s_add_u32 m0, s57, 0x0
	v_exp_f32_e32 v156, v156
	v_add_f32_e32 v27, v27, v154
	global_load_lds_dwordx4 v[28:29], off
	v_lshl_add_u64 v[28:29], v[28:29], 0, s[30:31]
	v_exp_f32_e32 v157, v157
	v_add_f32_e32 v27, v27, v155
	v_add_f32_e32 v27, v27, v156
	v_mfma_f32_32x32x16_bf16 v[98:113], v[190:193], v[130:133], v[98:113]
	s_add_u32 m0, s40, 0x6000
	v_add_f32_e32 v27, v27, v157
	v_cvt_pk_bf16_f32 v150, v150, v151
	global_load_lds_dwordx4 v[24:25], off
	v_lshl_add_u64 v[24:25], v[24:25], 0, s[30:31]
	v_cvt_pk_bf16_f32 v151, v152, v153
	v_cvt_pk_bf16_f32 v152, v154, v155
	v_cvt_pk_bf16_f32 v153, v156, v157
	v_mfma_f32_32x32x16_bf16 v[82:97], v[186:189], v[134:137], v[82:97]
	s_add_u32 m0, s43, 0x6000
	v_exp_f32_e32 v158, v158
	v_exp_f32_e32 v159, v159
	global_load_lds_dwordx4 v[30:31], off
	v_lshl_add_u64 v[30:31], v[30:31], 0, s[12:13]
	v_exp_f32_e32 v160, v160
	v_add_f32_e32 v27, v27, v158
	v_exp_f32_e32 v161, v161
	v_mfma_f32_32x32x16_bf16 v[98:113], v[182:185], v[134:137], v[98:113]
	v_add_f32_e32 v27, v27, v159
	v_exp_f32_e32 v162, v162
	v_add_f32_e32 v27, v27, v160
	v_exp_f32_e32 v163, v163
	v_add_f32_e32 v27, v27, v161
	v_mfma_f32_32x32x16_bf16 v[82:97], v[178:181], v[138:141], v[82:97]
	v_exp_f32_e32 v164, v164
	v_add_f32_e32 v27, v27, v162
	v_exp_f32_e32 v165, v165
	v_add_f32_e32 v27, v27, v163
	v_add_f32_e32 v27, v27, v164
	v_mfma_f32_32x32x16_bf16 v[98:113], v[174:177], v[138:141], v[98:113]
	v_add_f32_e32 v27, v27, v165
	v_cvt_pk_bf16_f32 v158, v158, v159
	v_cvt_pk_bf16_f32 v159, v160, v161
	v_cvt_pk_bf16_f32 v160, v162, v163
	v_cvt_pk_bf16_f32 v161, v164, v165
	s_waitcnt lgkmcnt(0)
	v_add_u32_e32 v2, 0x9000, v238
	v_mfma_f32_32x32x16_bf16 v[34:49], v[142:145], v[114:117], v[34:49]
	v_exp_f32_e32 v166, v166
	v_exp_f32_e32 v167, v167
	v_exp_f32_e32 v168, v168
	v_add_f32_e32 v27, v27, v166
	v_exp_f32_e32 v169, v169
	v_add_f32_e32 v27, v27, v167
	v_exp_f32_e32 v170, v170
	v_add_f32_e32 v27, v27, v168
	v_exp_f32_e32 v171, v171
	v_add_f32_e32 v27, v27, v169
	ds_read_b128 v[218:221], v2
	ds_read_b128 v[214:217], v2 offset:512
	ds_read_b128 v[210:213], v2 offset:2048
	v_mfma_f32_32x32x16_bf16 v[50:65], v[142:145], v[240:243], v[50:65]
	v_exp_f32_e32 v172, v172
	v_add_f32_e32 v27, v27, v170
	v_exp_f32_e32 v173, v173
	v_add_f32_e32 v27, v27, v171
	v_add_f32_e32 v27, v27, v172
	v_add_f32_e32 v27, v27, v173
	v_cvt_pk_bf16_f32 v166, v166, v167
	v_cvt_pk_bf16_f32 v167, v168, v169
	v_cvt_pk_bf16_f32 v168, v170, v171
	v_cvt_pk_bf16_f32 v169, v172, v173
	v_add_f32_e32 v236, v236, v27
	ds_read_b128 v[206:209], v2 offset:2560
	ds_read_b128 v[202:205], v2 offset:4096
	ds_read_b128 v[198:201], v2 offset:4608
	v_mfma_f32_32x32x16_bf16 v[34:49], v[150:153], v[118:121], v[34:49]
	ds_read_b128 v[194:197], v2 offset:6144
	ds_read_b128 v[190:193], v2 offset:6656
	ds_read_b128 v[186:189], v2 offset:8192
	v_max3_f32 v19, v82, v83, v84
	v_max3_f32 v26, v85, v86, v87
	v_max3_f32 v19, v19, v88, v89
	v_max3_f32 v26, v26, v90, v91
	v_max3_f32 v19, v19, v92, v93
	v_mfma_f32_32x32x16_bf16 v[50:65], v[150:153], v[244:247], v[50:65]
	ds_read_b128 v[182:185], v2 offset:8704
	ds_read_b128 v[178:181], v2 offset:10240
	ds_read_b128 v[174:177], v2 offset:10752
	v_max3_f32 v26, v26, v94, v95
	v_max3_f32 v19, v19, v96, v97
	v_max3_f32 v26, v26, v98, v99
	v_max3_f32 v19, v19, v100, v101
	v_max3_f32 v26, v26, v102, v103
	v_mfma_f32_32x32x16_bf16 v[34:49], v[158:161], v[122:125], v[34:49]
	v_max3_f32 v19, v19, v104, v105
	v_max3_f32 v26, v26, v106, v107
	v_max3_f32 v19, v19, v108, v109
	v_max3_f32 v26, v26, v110, v111
	v_mfma_f32_32x32x16_bf16 v[50:65], v[158:161], v[248:251], v[50:65]
	v_max3_f32 v19, v19, v112, v113
	v_max_f32_e32 v19, v19, v26
	v_mfma_f32_32x32x16_bf16 v[34:49], v[166:169], v[126:129], v[34:49]
	v_mfma_f32_32x32x16_bf16 v[50:65], v[166:169], v[20:23], v[50:65]
	v_cmp_lt_f32_e32 vcc, s41, v19
	s_cbranch_vccz .Lmy_nors_2
	s_nop 15
	s_nop 15
	v_mov_b32_e32 v26, v19
	s_nop 1
	v_permlane32_swap_b32_e32 v19, v26
	v_max_f32_e32 v19, v19, v26
	v_max_f32_e32 v19, v19, v19
	v_max_f32_e32 v150, 0, v19
	v_exp_f32_e64 v151, -v150
	v_add_f32_e32 v239, v239, v150
	v_xor_b32_e32 v66, 0x80000000, v239
	v_mov_b32_e32 v67, v66
	v_mov_b32_e32 v68, v66
	v_mov_b32_e32 v69, v66
	v_mov_b32_e32 v70, v66
	v_mov_b32_e32 v71, v66
	v_mov_b32_e32 v72, v66
	v_mov_b32_e32 v73, v66
	v_mov_b32_e32 v74, v66
	v_mov_b32_e32 v75, v66
	v_mov_b32_e32 v76, v66
	v_mov_b32_e32 v77, v66
	v_mov_b32_e32 v78, v66
	v_mov_b32_e32 v79, v66
	v_mov_b32_e32 v80, v66
	v_mov_b32_e32 v81, v66
	v_sub_f32_e32 v82, v82, v150
	v_sub_f32_e32 v83, v83, v150
	v_sub_f32_e32 v84, v84, v150
	v_sub_f32_e32 v85, v85, v150
	v_sub_f32_e32 v86, v86, v150
	v_sub_f32_e32 v87, v87, v150
	v_sub_f32_e32 v88, v88, v150
	v_sub_f32_e32 v89, v89, v150
	v_sub_f32_e32 v90, v90, v150
	v_sub_f32_e32 v91, v91, v150
	v_sub_f32_e32 v92, v92, v150
	v_sub_f32_e32 v93, v93, v150
	v_sub_f32_e32 v94, v94, v150
	v_sub_f32_e32 v95, v95, v150
	v_sub_f32_e32 v96, v96, v150
	v_sub_f32_e32 v97, v97, v150
	v_sub_f32_e32 v98, v98, v150
	v_sub_f32_e32 v99, v99, v150
	v_sub_f32_e32 v100, v100, v150
	v_sub_f32_e32 v101, v101, v150
	v_sub_f32_e32 v102, v102, v150
	v_sub_f32_e32 v103, v103, v150
	v_sub_f32_e32 v104, v104, v150
	v_sub_f32_e32 v105, v105, v150
	v_sub_f32_e32 v106, v106, v150
	v_sub_f32_e32 v107, v107, v150
	v_sub_f32_e32 v108, v108, v150
	v_sub_f32_e32 v109, v109, v150
	v_sub_f32_e32 v110, v110, v150
	v_sub_f32_e32 v111, v111, v150
	v_sub_f32_e32 v112, v112, v150
	v_sub_f32_e32 v113, v113, v150
	v_mul_f32_e32 v236, v236, v151
	s_mov_b64 s[96:97], exec
	s_and_b64 exec, exec, s[8:9]
	ds_write_b32 v235, v151
	s_mov_b64 exec, s[96:97]
	v_lshl_add_u32 v2, v228, 4, s47
	ds_read_b128 v[154:157], v2 offset:0
	s_waitcnt lgkmcnt(0)
	v_mul_f32_e32 v34, v34, v154
	v_mul_f32_e32 v50, v50, v154
	v_mul_f32_e32 v35, v35, v155
	v_mul_f32_e32 v51, v51, v155
	v_mul_f32_e32 v36, v36, v156
	v_mul_f32_e32 v52, v52, v156
	v_mul_f32_e32 v37, v37, v157
	v_mul_f32_e32 v53, v53, v157
	ds_read_b128 v[154:157], v2 offset:32
	s_waitcnt lgkmcnt(0)
	v_mul_f32_e32 v38, v38, v154
	v_mul_f32_e32 v54, v54, v154
	v_mul_f32_e32 v39, v39, v155
	v_mul_f32_e32 v55, v55, v155
	v_mul_f32_e32 v40, v40, v156
	v_mul_f32_e32 v56, v56, v156
	v_mul_f32_e32 v41, v41, v157
	v_mul_f32_e32 v57, v57, v157
	ds_read_b128 v[154:157], v2 offset:64
	s_waitcnt lgkmcnt(0)
	v_mul_f32_e32 v42, v42, v154
	v_mul_f32_e32 v58, v58, v154
	v_mul_f32_e32 v43, v43, v155
	v_mul_f32_e32 v59, v59, v155
	v_mul_f32_e32 v44, v44, v156
	v_mul_f32_e32 v60, v60, v156
	v_mul_f32_e32 v45, v45, v157
	v_mul_f32_e32 v61, v61, v157
	ds_read_b128 v[154:157], v2 offset:96
	s_waitcnt lgkmcnt(0)
	v_mul_f32_e32 v46, v46, v154
	v_mul_f32_e32 v62, v62, v154
	v_mul_f32_e32 v47, v47, v155
	v_mul_f32_e32 v63, v63, v155
	v_mul_f32_e32 v48, v48, v156
	v_mul_f32_e32 v64, v64, v156
	v_mul_f32_e32 v49, v49, v157
	v_mul_f32_e32 v65, v65, v157
.Lmy_nors_2:
	s_waitcnt lgkmcnt(0)
	v_add_u32_e32 v2, 0x4000, v237
	v_mfma_f32_32x32x16_bf16 v[142:157], v[218:221], v[4:7], v[66:81]
	v_exp_f32_e32 v82, v82
	v_exp_f32_e32 v83, v83
	v_exp_f32_e32 v84, v84
	v_add_f32_e32 v27, v82, v83
	v_exp_f32_e32 v85, v85
	ds_read_b64_tr_b16 v[114:115], v2 offset:49152
	ds_read_b64_tr_b16 v[116:117], v2 offset:49664
	ds_read_b64_tr_b16 v[118:119], v2 offset:50176
	ds_read_b64_tr_b16 v[120:121], v2 offset:50688
	v_mfma_f32_32x32x16_bf16 v[158:173], v[214:217], v[4:7], v[66:81]
	v_exp_f32_e32 v86, v86
	v_add_f32_e32 v27, v27, v84
	v_exp_f32_e32 v87, v87
	v_add_f32_e32 v27, v27, v85
	v_exp_f32_e32 v88, v88
	ds_read_b64_tr_b16 v[122:123], v2 offset:51200
	ds_read_b64_tr_b16 v[124:125], v2 offset:51712
	ds_read_b64_tr_b16 v[126:127], v2 offset:52224
	ds_read_b64_tr_b16 v[128:129], v2 offset:52736
	v_mfma_f32_32x32x16_bf16 v[142:157], v[210:213], v[8:11], v[142:157]
	v_add_f32_e32 v27, v27, v86
	v_exp_f32_e32 v89, v89
	v_add_f32_e32 v27, v27, v87
	v_add_f32_e32 v27, v27, v88
	v_add_f32_e32 v27, v27, v89
	ds_read_b64_tr_b16 v[240:241], v2 offset:53248
	ds_read_b64_tr_b16 v[242:243], v2 offset:53760
	ds_read_b64_tr_b16 v[244:245], v2 offset:54272
	ds_read_b64_tr_b16 v[246:247], v2 offset:54784
	v_mfma_f32_32x32x16_bf16 v[158:173], v[206:209], v[8:11], v[158:173]
	v_cvt_pk_bf16_f32 v82, v82, v83
	v_cvt_pk_bf16_f32 v83, v84, v85
	v_cvt_pk_bf16_f32 v84, v86, v87
	v_cvt_pk_bf16_f32 v85, v88, v89
	ds_read_b64_tr_b16 v[248:249], v2 offset:55296
	ds_read_b64_tr_b16 v[250:251], v2 offset:55808
	ds_read_b64_tr_b16 v[20:21], v2 offset:56320
	ds_read_b64_tr_b16 v[22:23], v2 offset:56832
	v_mfma_f32_32x32x16_bf16 v[142:157], v[202:205], v[12:15], v[142:157]
	v_exp_f32_e32 v90, v90
	v_exp_f32_e32 v91, v91
	v_exp_f32_e32 v92, v92
	v_add_f32_e32 v27, v27, v90
	v_exp_f32_e32 v93, v93
	v_mfma_f32_32x32x16_bf16 v[158:173], v[198:201], v[12:15], v[158:173]
	v_add_f32_e32 v27, v27, v91
	v_exp_f32_e32 v94, v94
	v_add_f32_e32 v27, v27, v92
	v_exp_f32_e32 v95, v95
	v_add_f32_e32 v27, v27, v93
	s_waitcnt vmcnt(5)
	s_barrier
	v_mfma_f32_32x32x16_bf16 v[142:157], v[194:197], v[130:133], v[142:157]
	s_add_u32 m0, s57, 0x2000
	v_exp_f32_e32 v96, v96
	v_add_f32_e32 v27, v27, v94
	global_load_lds_dwordx4 v[28:29], off
	v_lshl_add_u64 v[28:29], v[28:29], 0, s[30:31]
	v_exp_f32_e32 v97, v97
	v_add_f32_e32 v27, v27, v95
	v_add_f32_e32 v27, v27, v96
	v_mfma_f32_32x32x16_bf16 v[158:173], v[190:193], v[130:133], v[158:173]
	s_add_u32 m0, s40, 0x9000
	v_add_f32_e32 v27, v27, v97
	v_cvt_pk_bf16_f32 v90, v90, v91
	global_load_lds_dwordx4 v[24:25], off
	v_lshl_add_u64 v[24:25], v[24:25], 0, s[30:31]
	v_cvt_pk_bf16_f32 v91, v92, v93
	v_cvt_pk_bf16_f32 v92, v94, v95
	v_cvt_pk_bf16_f32 v93, v96, v97
	v_mfma_f32_32x32x16_bf16 v[142:157], v[186:189], v[134:137], v[142:157]
	s_add_u32 m0, s43, 0x9000
	v_exp_f32_e32 v98, v98
	v_exp_f32_e32 v99, v99
	global_load_lds_dwordx4 v[30:31], off
	v_lshl_add_u64 v[30:31], v[30:31], 0, s[12:13]
	v_exp_f32_e32 v100, v100
	v_add_f32_e32 v27, v27, v98
	v_exp_f32_e32 v101, v101
	v_mfma_f32_32x32x16_bf16 v[158:173], v[182:185], v[134:137], v[158:173]
	v_add_f32_e32 v27, v27, v99
	v_exp_f32_e32 v102, v102
	v_add_f32_e32 v27, v27, v100
	v_exp_f32_e32 v103, v103
	v_add_f32_e32 v27, v27, v101
	v_mfma_f32_32x32x16_bf16 v[142:157], v[178:181], v[138:141], v[142:157]
	v_exp_f32_e32 v104, v104
	v_add_f32_e32 v27, v27, v102
	v_exp_f32_e32 v105, v105
	v_add_f32_e32 v27, v27, v103
	v_add_f32_e32 v27, v27, v104
	v_mfma_f32_32x32x16_bf16 v[158:173], v[174:177], v[138:141], v[158:173]
	v_add_f32_e32 v27, v27, v105
	v_cvt_pk_bf16_f32 v98, v98, v99
	v_cvt_pk_bf16_f32 v99, v100, v101
	v_cvt_pk_bf16_f32 v100, v102, v103
	v_cvt_pk_bf16_f32 v101, v104, v105
	s_waitcnt lgkmcnt(0)
	v_mov_b32_e32 v2, v238
	v_mfma_f32_32x32x16_bf16 v[34:49], v[82:85], v[114:117], v[34:49]
	v_exp_f32_e32 v106, v106
	v_exp_f32_e32 v107, v107
	v_exp_f32_e32 v108, v108
	v_add_f32_e32 v27, v27, v106
	v_exp_f32_e32 v109, v109
	v_add_f32_e32 v27, v27, v107
	v_exp_f32_e32 v110, v110
	v_add_f32_e32 v27, v27, v108
	v_exp_f32_e32 v111, v111
	v_add_f32_e32 v27, v27, v109
	ds_read_b128 v[218:221], v2
	ds_read_b128 v[214:217], v2 offset:512
	ds_read_b128 v[210:213], v2 offset:2048
	v_mfma_f32_32x32x16_bf16 v[50:65], v[82:85], v[240:243], v[50:65]
	v_exp_f32_e32 v112, v112
	v_add_f32_e32 v27, v27, v110
	v_exp_f32_e32 v113, v113
	v_add_f32_e32 v27, v27, v111
	v_add_f32_e32 v27, v27, v112
	v_add_f32_e32 v27, v27, v113
	v_cvt_pk_bf16_f32 v106, v106, v107
	v_cvt_pk_bf16_f32 v107, v108, v109
	v_cvt_pk_bf16_f32 v108, v110, v111
	v_cvt_pk_bf16_f32 v109, v112, v113
	v_add_f32_e32 v236, v236, v27
	ds_read_b128 v[206:209], v2 offset:2560
	ds_read_b128 v[202:205], v2 offset:4096
	ds_read_b128 v[198:201], v2 offset:4608
	v_mfma_f32_32x32x16_bf16 v[34:49], v[90:93], v[118:121], v[34:49]
	ds_read_b128 v[194:197], v2 offset:6144
	ds_read_b128 v[190:193], v2 offset:6656
	ds_read_b128 v[186:189], v2 offset:8192
	v_max3_f32 v19, v142, v143, v144
	v_max3_f32 v26, v145, v146, v147
	v_max3_f32 v19, v19, v148, v149
	v_max3_f32 v26, v26, v150, v151
	v_max3_f32 v19, v19, v152, v153
	v_mfma_f32_32x32x16_bf16 v[50:65], v[90:93], v[244:247], v[50:65]
	ds_read_b128 v[182:185], v2 offset:8704
	ds_read_b128 v[178:181], v2 offset:10240
	ds_read_b128 v[174:177], v2 offset:10752
	v_max3_f32 v26, v26, v154, v155
	v_max3_f32 v19, v19, v156, v157
	v_max3_f32 v26, v26, v158, v159
	v_max3_f32 v19, v19, v160, v161
	v_max3_f32 v26, v26, v162, v163
	v_mfma_f32_32x32x16_bf16 v[34:49], v[98:101], v[122:125], v[34:49]
	v_max3_f32 v19, v19, v164, v165
	v_max3_f32 v26, v26, v166, v167
	v_max3_f32 v19, v19, v168, v169
	v_max3_f32 v26, v26, v170, v171
	v_mfma_f32_32x32x16_bf16 v[50:65], v[98:101], v[248:251], v[50:65]
	v_max3_f32 v19, v19, v172, v173
	v_max_f32_e32 v19, v19, v26
	v_mfma_f32_32x32x16_bf16 v[34:49], v[106:109], v[126:129], v[34:49]
	v_mfma_f32_32x32x16_bf16 v[50:65], v[106:109], v[20:23], v[50:65]
	v_cmp_lt_f32_e32 vcc, s41, v19
	s_cbranch_vccz .Lmy_nors_3
	s_nop 15
	s_nop 15
	v_mov_b32_e32 v26, v19
	s_nop 1
	v_permlane32_swap_b32_e32 v19, v26
	v_max_f32_e32 v19, v19, v26
	v_max_f32_e32 v19, v19, v19
	v_max_f32_e32 v90, 0, v19
	v_exp_f32_e64 v91, -v90
	v_add_f32_e32 v239, v239, v90
	v_xor_b32_e32 v66, 0x80000000, v239
	v_mov_b32_e32 v67, v66
	v_mov_b32_e32 v68, v66
	v_mov_b32_e32 v69, v66
	v_mov_b32_e32 v70, v66
	v_mov_b32_e32 v71, v66
	v_mov_b32_e32 v72, v66
	v_mov_b32_e32 v73, v66
	v_mov_b32_e32 v74, v66
	v_mov_b32_e32 v75, v66
	v_mov_b32_e32 v76, v66
	v_mov_b32_e32 v77, v66
	v_mov_b32_e32 v78, v66
	v_mov_b32_e32 v79, v66
	v_mov_b32_e32 v80, v66
	v_mov_b32_e32 v81, v66
	v_sub_f32_e32 v142, v142, v90
	v_sub_f32_e32 v143, v143, v90
	v_sub_f32_e32 v144, v144, v90
	v_sub_f32_e32 v145, v145, v90
	v_sub_f32_e32 v146, v146, v90
	v_sub_f32_e32 v147, v147, v90
	v_sub_f32_e32 v148, v148, v90
	v_sub_f32_e32 v149, v149, v90
	v_sub_f32_e32 v150, v150, v90
	v_sub_f32_e32 v151, v151, v90
	v_sub_f32_e32 v152, v152, v90
	v_sub_f32_e32 v153, v153, v90
	v_sub_f32_e32 v154, v154, v90
	v_sub_f32_e32 v155, v155, v90
	v_sub_f32_e32 v156, v156, v90
	v_sub_f32_e32 v157, v157, v90
	v_sub_f32_e32 v158, v158, v90
	v_sub_f32_e32 v159, v159, v90
	v_sub_f32_e32 v160, v160, v90
	v_sub_f32_e32 v161, v161, v90
	v_sub_f32_e32 v162, v162, v90
	v_sub_f32_e32 v163, v163, v90
	v_sub_f32_e32 v164, v164, v90
	v_sub_f32_e32 v165, v165, v90
	v_sub_f32_e32 v166, v166, v90
	v_sub_f32_e32 v167, v167, v90
	v_sub_f32_e32 v168, v168, v90
	v_sub_f32_e32 v169, v169, v90
	v_sub_f32_e32 v170, v170, v90
	v_sub_f32_e32 v171, v171, v90
	v_sub_f32_e32 v172, v172, v90
	v_sub_f32_e32 v173, v173, v90
	v_mul_f32_e32 v236, v236, v91
	s_mov_b64 s[96:97], exec
	s_and_b64 exec, exec, s[8:9]
	ds_write_b32 v235, v91
	s_mov_b64 exec, s[96:97]
	v_lshl_add_u32 v2, v228, 4, s47
	ds_read_b128 v[94:97], v2 offset:0
	s_waitcnt lgkmcnt(0)
	v_mul_f32_e32 v34, v34, v94
	v_mul_f32_e32 v50, v50, v94
	v_mul_f32_e32 v35, v35, v95
	v_mul_f32_e32 v51, v51, v95
	v_mul_f32_e32 v36, v36, v96
	v_mul_f32_e32 v52, v52, v96
	v_mul_f32_e32 v37, v37, v97
	v_mul_f32_e32 v53, v53, v97
	ds_read_b128 v[94:97], v2 offset:32
	s_waitcnt lgkmcnt(0)
	v_mul_f32_e32 v38, v38, v94
	v_mul_f32_e32 v54, v54, v94
	v_mul_f32_e32 v39, v39, v95
	v_mul_f32_e32 v55, v55, v95
	v_mul_f32_e32 v40, v40, v96
	v_mul_f32_e32 v56, v56, v96
	v_mul_f32_e32 v41, v41, v97
	v_mul_f32_e32 v57, v57, v97
	ds_read_b128 v[94:97], v2 offset:64
	s_waitcnt lgkmcnt(0)
	v_mul_f32_e32 v42, v42, v94
	v_mul_f32_e32 v58, v58, v94
	v_mul_f32_e32 v43, v43, v95
	v_mul_f32_e32 v59, v59, v95
	v_mul_f32_e32 v44, v44, v96
	v_mul_f32_e32 v60, v60, v96
	v_mul_f32_e32 v45, v45, v97
	v_mul_f32_e32 v61, v61, v97
	ds_read_b128 v[94:97], v2 offset:96
	s_waitcnt lgkmcnt(0)
	v_mul_f32_e32 v46, v46, v94
	v_mul_f32_e32 v62, v62, v94
	v_mul_f32_e32 v47, v47, v95
	v_mul_f32_e32 v63, v63, v95
	v_mul_f32_e32 v48, v48, v96
	v_mul_f32_e32 v64, v64, v96
	v_mul_f32_e32 v49, v49, v97
	v_mul_f32_e32 v65, v65, v97
.Lmy_nors_3:
	s_waitcnt lgkmcnt(0)
	v_add_u32_e32 v2, 0x6000, v237
	v_mfma_f32_32x32x16_bf16 v[82:97], v[218:221], v[4:7], v[66:81]
	v_exp_f32_e32 v142, v142
	v_exp_f32_e32 v143, v143
	v_exp_f32_e32 v144, v144
	v_add_f32_e32 v27, v142, v143
	v_exp_f32_e32 v145, v145
	ds_read_b64_tr_b16 v[114:115], v2 offset:49152
	ds_read_b64_tr_b16 v[116:117], v2 offset:49664
	ds_read_b64_tr_b16 v[118:119], v2 offset:50176
	ds_read_b64_tr_b16 v[120:121], v2 offset:50688
	v_mfma_f32_32x32x16_bf16 v[98:113], v[214:217], v[4:7], v[66:81]
	v_exp_f32_e32 v146, v146
	v_add_f32_e32 v27, v27, v144
	v_exp_f32_e32 v147, v147
	v_add_f32_e32 v27, v27, v145
	v_exp_f32_e32 v148, v148
	ds_read_b64_tr_b16 v[122:123], v2 offset:51200
	ds_read_b64_tr_b16 v[124:125], v2 offset:51712
	ds_read_b64_tr_b16 v[126:127], v2 offset:52224
	ds_read_b64_tr_b16 v[128:129], v2 offset:52736
	v_mfma_f32_32x32x16_bf16 v[82:97], v[210:213], v[8:11], v[82:97]
	v_add_f32_e32 v27, v27, v146
	v_exp_f32_e32 v149, v149
	v_add_f32_e32 v27, v27, v147
	v_add_f32_e32 v27, v27, v148
	v_add_f32_e32 v27, v27, v149
	ds_read_b64_tr_b16 v[240:241], v2 offset:53248
	ds_read_b64_tr_b16 v[242:243], v2 offset:53760
	ds_read_b64_tr_b16 v[244:245], v2 offset:54272
	ds_read_b64_tr_b16 v[246:247], v2 offset:54784
	v_mfma_f32_32x32x16_bf16 v[98:113], v[206:209], v[8:11], v[98:113]
	v_cvt_pk_bf16_f32 v142, v142, v143
	v_cvt_pk_bf16_f32 v143, v144, v145
	v_cvt_pk_bf16_f32 v144, v146, v147
	v_cvt_pk_bf16_f32 v145, v148, v149
	ds_read_b64_tr_b16 v[248:249], v2 offset:55296
	ds_read_b64_tr_b16 v[250:251], v2 offset:55808
	ds_read_b64_tr_b16 v[20:21], v2 offset:56320
	ds_read_b64_tr_b16 v[22:23], v2 offset:56832
	v_mfma_f32_32x32x16_bf16 v[82:97], v[202:205], v[12:15], v[82:97]
	v_exp_f32_e32 v150, v150
	v_exp_f32_e32 v151, v151
	v_exp_f32_e32 v152, v152
	v_add_f32_e32 v27, v27, v150
	v_exp_f32_e32 v153, v153
	v_mfma_f32_32x32x16_bf16 v[98:113], v[198:201], v[12:15], v[98:113]
	v_add_f32_e32 v27, v27, v151
	v_exp_f32_e32 v154, v154
	v_add_f32_e32 v27, v27, v152
	v_exp_f32_e32 v155, v155
	v_add_f32_e32 v27, v27, v153
	s_waitcnt vmcnt(6)
	s_barrier
	v_mfma_f32_32x32x16_bf16 v[82:97], v[194:197], v[130:133], v[82:97]
	s_add_u32 m0, s57, 0x4000
	v_exp_f32_e32 v156, v156
	v_add_f32_e32 v27, v27, v154
	global_load_lds_dwordx4 v[28:29], off
	v_lshl_add_u64 v[28:29], v[28:29], 0, s[30:31]
	v_exp_f32_e32 v157, v157
	v_add_f32_e32 v27, v27, v155
	v_add_f32_e32 v27, v27, v156
	v_mfma_f32_32x32x16_bf16 v[98:113], v[190:193], v[130:133], v[98:113]
	s_cmp_eq_u32 s79, 1
	s_cbranch_scc1 .Lmy_gl_4
	s_add_u32 m0, s40, 0x0
	s_nop 0
	global_load_lds_dwordx4 v[24:25], off
	v_lshl_add_u64 v[24:25], v[24:25], 0, s[30:31]
.Lmy_gl_4:
	v_add_f32_e32 v27, v27, v157
	v_cvt_pk_bf16_f32 v150, v150, v151
	v_cvt_pk_bf16_f32 v151, v152, v153
	v_cvt_pk_bf16_f32 v152, v154, v155
	v_cvt_pk_bf16_f32 v153, v156, v157
	v_mfma_f32_32x32x16_bf16 v[82:97], v[186:189], v[134:137], v[82:97]
	s_cmp_eq_u32 s79, 1
	s_cbranch_scc1 .Lmy_gl_5
	s_add_u32 m0, s43, 0x0
	s_nop 0
	global_load_lds_dwordx4 v[30:31], off
	v_lshl_add_u64 v[30:31], v[30:31], 0, s[12:13]
.Lmy_gl_5:
	v_exp_f32_e32 v158, v158
	v_exp_f32_e32 v159, v159
	v_exp_f32_e32 v160, v160
	v_add_f32_e32 v27, v27, v158
	v_exp_f32_e32 v161, v161
	v_mfma_f32_32x32x16_bf16 v[98:113], v[182:185], v[134:137], v[98:113]
	v_add_f32_e32 v27, v27, v159
	v_exp_f32_e32 v162, v162
	v_add_f32_e32 v27, v27, v160
	v_exp_f32_e32 v163, v163
	v_add_f32_e32 v27, v27, v161
	v_mfma_f32_32x32x16_bf16 v[82:97], v[178:181], v[138:141], v[82:97]
	v_exp_f32_e32 v164, v164
	v_add_f32_e32 v27, v27, v162
	v_exp_f32_e32 v165, v165
	v_add_f32_e32 v27, v27, v163
	v_add_f32_e32 v27, v27, v164
	v_mfma_f32_32x32x16_bf16 v[98:113], v[174:177], v[138:141], v[98:113]
	v_add_f32_e32 v27, v27, v165
	v_cvt_pk_bf16_f32 v158, v158, v159
	v_cvt_pk_bf16_f32 v159, v160, v161
	v_cvt_pk_bf16_f32 v160, v162, v163
	v_cvt_pk_bf16_f32 v161, v164, v165
	s_waitcnt lgkmcnt(0)
	v_add_u32_e32 v2, 0x3000, v238
	v_mfma_f32_32x32x16_bf16 v[34:49], v[142:145], v[114:117], v[34:49]
	v_exp_f32_e32 v166, v166
	v_exp_f32_e32 v167, v167
	v_exp_f32_e32 v168, v168
	v_add_f32_e32 v27, v27, v166
	v_exp_f32_e32 v169, v169
	v_add_f32_e32 v27, v27, v167
	v_exp_f32_e32 v170, v170
	v_add_f32_e32 v27, v27, v168
	v_exp_f32_e32 v171, v171
	v_add_f32_e32 v27, v27, v169
	ds_read_b128 v[218:221], v2
	ds_read_b128 v[214:217], v2 offset:512
	ds_read_b128 v[210:213], v2 offset:2048
	v_mfma_f32_32x32x16_bf16 v[50:65], v[142:145], v[240:243], v[50:65]
	v_exp_f32_e32 v172, v172
	v_add_f32_e32 v27, v27, v170
	v_exp_f32_e32 v173, v173
	v_add_f32_e32 v27, v27, v171
	v_add_f32_e32 v27, v27, v172
	v_add_f32_e32 v27, v27, v173
	v_cvt_pk_bf16_f32 v166, v166, v167
	v_cvt_pk_bf16_f32 v167, v168, v169
	v_cvt_pk_bf16_f32 v168, v170, v171
	v_cvt_pk_bf16_f32 v169, v172, v173
	v_add_f32_e32 v236, v236, v27
	ds_read_b128 v[206:209], v2 offset:2560
	ds_read_b128 v[202:205], v2 offset:4096
	ds_read_b128 v[198:201], v2 offset:4608
	v_mfma_f32_32x32x16_bf16 v[34:49], v[150:153], v[118:121], v[34:49]
	ds_read_b128 v[194:197], v2 offset:6144
	ds_read_b128 v[190:193], v2 offset:6656
	ds_read_b128 v[186:189], v2 offset:8192
	v_max3_f32 v19, v82, v83, v84
	v_max3_f32 v26, v85, v86, v87
	v_max3_f32 v19, v19, v88, v89
	v_max3_f32 v26, v26, v90, v91
	v_max3_f32 v19, v19, v92, v93
	v_mfma_f32_32x32x16_bf16 v[50:65], v[150:153], v[244:247], v[50:65]
	ds_read_b128 v[182:185], v2 offset:8704
	ds_read_b128 v[178:181], v2 offset:10240
	ds_read_b128 v[174:177], v2 offset:10752
	v_max3_f32 v26, v26, v94, v95
	v_max3_f32 v19, v19, v96, v97
	v_max3_f32 v26, v26, v98, v99
	v_max3_f32 v19, v19, v100, v101
	v_max3_f32 v26, v26, v102, v103
	v_mfma_f32_32x32x16_bf16 v[34:49], v[158:161], v[122:125], v[34:49]
	v_max3_f32 v19, v19, v104, v105
	v_max3_f32 v26, v26, v106, v107
	v_max3_f32 v19, v19, v108, v109
	v_max3_f32 v26, v26, v110, v111
	v_mfma_f32_32x32x16_bf16 v[50:65], v[158:161], v[248:251], v[50:65]
	v_max3_f32 v19, v19, v112, v113
	v_max_f32_e32 v19, v19, v26
	v_mfma_f32_32x32x16_bf16 v[34:49], v[166:169], v[126:129], v[34:49]
	v_mfma_f32_32x32x16_bf16 v[50:65], v[166:169], v[20:23], v[50:65]
	v_cmp_lt_f32_e32 vcc, s41, v19
	s_cbranch_vccz .Lmy_nors_6
	s_nop 15
	s_nop 15
	v_mov_b32_e32 v26, v19
	s_nop 1
	v_permlane32_swap_b32_e32 v19, v26
	v_max_f32_e32 v19, v19, v26
	v_max_f32_e32 v19, v19, v19
	v_max_f32_e32 v150, 0, v19
	v_exp_f32_e64 v151, -v150
	v_add_f32_e32 v239, v239, v150
	v_xor_b32_e32 v66, 0x80000000, v239
	v_mov_b32_e32 v67, v66
	v_mov_b32_e32 v68, v66
	v_mov_b32_e32 v69, v66
	v_mov_b32_e32 v70, v66
	v_mov_b32_e32 v71, v66
	v_mov_b32_e32 v72, v66
	v_mov_b32_e32 v73, v66
	v_mov_b32_e32 v74, v66
	v_mov_b32_e32 v75, v66
	v_mov_b32_e32 v76, v66
	v_mov_b32_e32 v77, v66
	v_mov_b32_e32 v78, v66
	v_mov_b32_e32 v79, v66
	v_mov_b32_e32 v80, v66
	v_mov_b32_e32 v81, v66
	v_sub_f32_e32 v82, v82, v150
	v_sub_f32_e32 v83, v83, v150
	v_sub_f32_e32 v84, v84, v150
	v_sub_f32_e32 v85, v85, v150
	v_sub_f32_e32 v86, v86, v150
	v_sub_f32_e32 v87, v87, v150
	v_sub_f32_e32 v88, v88, v150
	v_sub_f32_e32 v89, v89, v150
	v_sub_f32_e32 v90, v90, v150
	v_sub_f32_e32 v91, v91, v150
	v_sub_f32_e32 v92, v92, v150
	v_sub_f32_e32 v93, v93, v150
	v_sub_f32_e32 v94, v94, v150
	v_sub_f32_e32 v95, v95, v150
	v_sub_f32_e32 v96, v96, v150
	v_sub_f32_e32 v97, v97, v150
	v_sub_f32_e32 v98, v98, v150
	v_sub_f32_e32 v99, v99, v150
	v_sub_f32_e32 v100, v100, v150
	v_sub_f32_e32 v101, v101, v150
	v_sub_f32_e32 v102, v102, v150
	v_sub_f32_e32 v103, v103, v150
	v_sub_f32_e32 v104, v104, v150
	v_sub_f32_e32 v105, v105, v150
	v_sub_f32_e32 v106, v106, v150
	v_sub_f32_e32 v107, v107, v150
	v_sub_f32_e32 v108, v108, v150
	v_sub_f32_e32 v109, v109, v150
	v_sub_f32_e32 v110, v110, v150
	v_sub_f32_e32 v111, v111, v150
	v_sub_f32_e32 v112, v112, v150
	v_sub_f32_e32 v113, v113, v150
	v_mul_f32_e32 v236, v236, v151
	s_mov_b64 s[96:97], exec
	s_and_b64 exec, exec, s[8:9]
	ds_write_b32 v235, v151
	s_mov_b64 exec, s[96:97]
	v_lshl_add_u32 v2, v228, 4, s47
	ds_read_b128 v[154:157], v2 offset:0
	s_waitcnt lgkmcnt(0)
	v_mul_f32_e32 v34, v34, v154
	v_mul_f32_e32 v50, v50, v154
	v_mul_f32_e32 v35, v35, v155
	v_mul_f32_e32 v51, v51, v155
	v_mul_f32_e32 v36, v36, v156
	v_mul_f32_e32 v52, v52, v156
	v_mul_f32_e32 v37, v37, v157
	v_mul_f32_e32 v53, v53, v157
	ds_read_b128 v[154:157], v2 offset:32
	s_waitcnt lgkmcnt(0)
	v_mul_f32_e32 v38, v38, v154
	v_mul_f32_e32 v54, v54, v154
	v_mul_f32_e32 v39, v39, v155
	v_mul_f32_e32 v55, v55, v155
	v_mul_f32_e32 v40, v40, v156
	v_mul_f32_e32 v56, v56, v156
	v_mul_f32_e32 v41, v41, v157
	v_mul_f32_e32 v57, v57, v157
	ds_read_b128 v[154:157], v2 offset:64
	s_waitcnt lgkmcnt(0)
	v_mul_f32_e32 v42, v42, v154
	v_mul_f32_e32 v58, v58, v154
	v_mul_f32_e32 v43, v43, v155
	v_mul_f32_e32 v59, v59, v155
	v_mul_f32_e32 v44, v44, v156
	v_mul_f32_e32 v60, v60, v156
	v_mul_f32_e32 v45, v45, v157
	v_mul_f32_e32 v61, v61, v157
	ds_read_b128 v[154:157], v2 offset:96
	s_waitcnt lgkmcnt(0)
	v_mul_f32_e32 v46, v46, v154
	v_mul_f32_e32 v62, v62, v154
	v_mul_f32_e32 v47, v47, v155
	v_mul_f32_e32 v63, v63, v155
	v_mul_f32_e32 v48, v48, v156
	v_mul_f32_e32 v64, v64, v156
	v_mul_f32_e32 v49, v49, v157
	v_mul_f32_e32 v65, v65, v157
.Lmy_nors_6:
	s_add_i32 s79, s79, -1
	s_cmp_gt_i32 s79, 0
	s_cbranch_scc0 .Lmy_A_tail
.Lmy_A_loop:
	s_waitcnt lgkmcnt(0)
	v_mov_b32_e32 v2, v237
	v_mfma_f32_32x32x16_bf16 v[142:157], v[218:221], v[4:7], v[66:81]
	v_exp_f32_e32 v82, v82
	v_exp_f32_e32 v83, v83
	v_exp_f32_e32 v84, v84
	v_add_f32_e32 v27, v82, v83
	v_exp_f32_e32 v85, v85
	ds_read_b64_tr_b16 v[114:115], v2 offset:49152
	ds_read_b64_tr_b16 v[116:117], v2 offset:49664
	ds_read_b64_tr_b16 v[118:119], v2 offset:50176
	ds_read_b64_tr_b16 v[120:121], v2 offset:50688
	v_mfma_f32_32x32x16_bf16 v[158:173], v[214:217], v[4:7], v[66:81]
	v_exp_f32_e32 v86, v86
	v_add_f32_e32 v27, v27, v84
	v_exp_f32_e32 v87, v87
	v_add_f32_e32 v27, v27, v85
	v_exp_f32_e32 v88, v88
	ds_read_b64_tr_b16 v[122:123], v2 offset:51200
	ds_read_b64_tr_b16 v[124:125], v2 offset:51712
	ds_read_b64_tr_b16 v[126:127], v2 offset:52224
	ds_read_b64_tr_b16 v[128:129], v2 offset:52736
	v_mfma_f32_32x32x16_bf16 v[142:157], v[210:213], v[8:11], v[142:157]
	v_add_f32_e32 v27, v27, v86
	v_exp_f32_e32 v89, v89
	v_add_f32_e32 v27, v27, v87
	v_add_f32_e32 v27, v27, v88
	v_add_f32_e32 v27, v27, v89
	ds_read_b64_tr_b16 v[240:241], v2 offset:53248
	ds_read_b64_tr_b16 v[242:243], v2 offset:53760
	ds_read_b64_tr_b16 v[244:245], v2 offset:54272
	ds_read_b64_tr_b16 v[246:247], v2 offset:54784
	v_mfma_f32_32x32x16_bf16 v[158:173], v[206:209], v[8:11], v[158:173]
	v_cvt_pk_bf16_f32 v82, v82, v83
	v_cvt_pk_bf16_f32 v83, v84, v85
	v_cvt_pk_bf16_f32 v84, v86, v87
	v_cvt_pk_bf16_f32 v85, v88, v89
	ds_read_b64_tr_b16 v[248:249], v2 offset:55296
	ds_read_b64_tr_b16 v[250:251], v2 offset:55808
	ds_read_b64_tr_b16 v[20:21], v2 offset:56320
	ds_read_b64_tr_b16 v[22:23], v2 offset:56832
	v_mfma_f32_32x32x16_bf16 v[142:157], v[202:205], v[12:15], v[142:157]
	v_exp_f32_e32 v90, v90
	v_exp_f32_e32 v91, v91
	v_exp_f32_e32 v92, v92
	v_add_f32_e32 v27, v27, v90
	v_exp_f32_e32 v93, v93
	v_mfma_f32_32x32x16_bf16 v[158:173], v[198:201], v[12:15], v[158:173]
	v_add_f32_e32 v27, v27, v91
	v_exp_f32_e32 v94, v94
	v_add_f32_e32 v27, v27, v92
	v_exp_f32_e32 v95, v95
	v_add_f32_e32 v27, v27, v93
	s_waitcnt vmcnt(6)
	s_barrier
	v_mfma_f32_32x32x16_bf16 v[142:157], v[194:197], v[130:133], v[142:157]
	s_add_u32 m0, s57, 0x6000
	v_exp_f32_e32 v96, v96
	v_add_f32_e32 v27, v27, v94
	global_load_lds_dwordx4 v[28:29], off
	v_lshl_add_u64 v[28:29], v[28:29], 0, s[30:31]
	v_exp_f32_e32 v97, v97
	v_add_f32_e32 v27, v27, v95
	v_add_f32_e32 v27, v27, v96
	v_mfma_f32_32x32x16_bf16 v[158:173], v[190:193], v[130:133], v[158:173]
	s_add_u32 m0, s40, 0x3000
	v_add_f32_e32 v27, v27, v97
	v_cvt_pk_bf16_f32 v90, v90, v91
	global_load_lds_dwordx4 v[24:25], off
	v_lshl_add_u64 v[24:25], v[24:25], 0, s[30:31]
	v_cvt_pk_bf16_f32 v91, v92, v93
	v_cvt_pk_bf16_f32 v92, v94, v95
	v_cvt_pk_bf16_f32 v93, v96, v97
	v_mfma_f32_32x32x16_bf16 v[142:157], v[186:189], v[134:137], v[142:157]
	s_add_u32 m0, s43, 0x3000
	v_exp_f32_e32 v98, v98
	v_exp_f32_e32 v99, v99
	global_load_lds_dwordx4 v[30:31], off
	v_lshl_add_u64 v[30:31], v[30:31], 0, s[12:13]
	v_exp_f32_e32 v100, v100
	v_add_f32_e32 v27, v27, v98
	v_exp_f32_e32 v101, v101
	v_mfma_f32_32x32x16_bf16 v[158:173], v[182:185], v[134:137], v[158:173]
	v_add_f32_e32 v27, v27, v99
	v_exp_f32_e32 v102, v102
	v_add_f32_e32 v27, v27, v100
	v_exp_f32_e32 v103, v103
	v_add_f32_e32 v27, v27, v101
	v_mfma_f32_32x32x16_bf16 v[142:157], v[178:181], v[138:141], v[142:157]
	v_exp_f32_e32 v104, v104
	v_add_f32_e32 v27, v27, v102
	v_exp_f32_e32 v105, v105
	v_add_f32_e32 v27, v27, v103
	v_add_f32_e32 v27, v27, v104
	v_mfma_f32_32x32x16_bf16 v[158:173], v[174:177], v[138:141], v[158:173]
	v_add_f32_e32 v27, v27, v105
	v_cvt_pk_bf16_f32 v98, v98, v99
	v_cvt_pk_bf16_f32 v99, v100, v101
	v_cvt_pk_bf16_f32 v100, v102, v103
	v_cvt_pk_bf16_f32 v101, v104, v105
	s_waitcnt lgkmcnt(0)
	v_add_u32_e32 v2, 0x6000, v238
	v_mfma_f32_32x32x16_bf16 v[34:49], v[82:85], v[114:117], v[34:49]
	v_exp_f32_e32 v106, v106
	v_exp_f32_e32 v107, v107
	v_exp_f32_e32 v108, v108
	v_add_f32_e32 v27, v27, v106
	v_exp_f32_e32 v109, v109
	v_add_f32_e32 v27, v27, v107
	v_exp_f32_e32 v110, v110
	v_add_f32_e32 v27, v27, v108
	v_exp_f32_e32 v111, v111
	v_add_f32_e32 v27, v27, v109
	ds_read_b128 v[218:221], v2
	ds_read_b128 v[214:217], v2 offset:512
	ds_read_b128 v[210:213], v2 offset:2048
	v_mfma_f32_32x32x16_bf16 v[50:65], v[82:85], v[240:243], v[50:65]
	v_exp_f32_e32 v112, v112
	v_add_f32_e32 v27, v27, v110
	v_exp_f32_e32 v113, v113
	v_add_f32_e32 v27, v27, v111
	v_add_f32_e32 v27, v27, v112
	v_add_f32_e32 v27, v27, v113
	v_cvt_pk_bf16_f32 v106, v106, v107
	v_cvt_pk_bf16_f32 v107, v108, v109
	v_cvt_pk_bf16_f32 v108, v110, v111
	v_cvt_pk_bf16_f32 v109, v112, v113
	v_add_f32_e32 v236, v236, v27
	ds_read_b128 v[206:209], v2 offset:2560
	ds_read_b128 v[202:205], v2 offset:4096
	ds_read_b128 v[198:201], v2 offset:4608
	v_mfma_f32_32x32x16_bf16 v[34:49], v[90:93], v[118:121], v[34:49]
	ds_read_b128 v[194:197], v2 offset:6144
	ds_read_b128 v[190:193], v2 offset:6656
	ds_read_b128 v[186:189], v2 offset:8192
	v_max3_f32 v19, v142, v143, v144
	v_max3_f32 v26, v145, v146, v147
	v_max3_f32 v19, v19, v148, v149
	v_max3_f32 v26, v26, v150, v151
	v_max3_f32 v19, v19, v152, v153
	v_mfma_f32_32x32x16_bf16 v[50:65], v[90:93], v[244:247], v[50:65]
	ds_read_b128 v[182:185], v2 offset:8704
	ds_read_b128 v[178:181], v2 offset:10240
	ds_read_b128 v[174:177], v2 offset:10752
	v_max3_f32 v26, v26, v154, v155
	v_max3_f32 v19, v19, v156, v157
	v_max3_f32 v26, v26, v158, v159
	v_max3_f32 v19, v19, v160, v161
	v_max3_f32 v26, v26, v162, v163
	v_mfma_f32_32x32x16_bf16 v[34:49], v[98:101], v[122:125], v[34:49]
	v_max3_f32 v19, v19, v164, v165
	v_max3_f32 v26, v26, v166, v167
	v_max3_f32 v19, v19, v168, v169
	v_max3_f32 v26, v26, v170, v171
	v_mfma_f32_32x32x16_bf16 v[50:65], v[98:101], v[248:251], v[50:65]
	v_max3_f32 v19, v19, v172, v173
	v_max_f32_e32 v19, v19, v26
	v_mfma_f32_32x32x16_bf16 v[34:49], v[106:109], v[126:129], v[34:49]
	v_mfma_f32_32x32x16_bf16 v[50:65], v[106:109], v[20:23], v[50:65]
	v_cmp_lt_f32_e32 vcc, s41, v19
	s_cbranch_vccz .Lmy_nors_7
	s_nop 15
	s_nop 15
	v_mov_b32_e32 v26, v19
	s_nop 1
	v_permlane32_swap_b32_e32 v19, v26
	v_max_f32_e32 v19, v19, v26
	v_max_f32_e32 v19, v19, v19
	v_max_f32_e32 v90, 0, v19
	v_exp_f32_e64 v91, -v90
	v_add_f32_e32 v239, v239, v90
	v_xor_b32_e32 v66, 0x80000000, v239
	v_mov_b32_e32 v67, v66
	v_mov_b32_e32 v68, v66
	v_mov_b32_e32 v69, v66
	v_mov_b32_e32 v70, v66
	v_mov_b32_e32 v71, v66
	v_mov_b32_e32 v72, v66
	v_mov_b32_e32 v73, v66
	v_mov_b32_e32 v74, v66
	v_mov_b32_e32 v75, v66
	v_mov_b32_e32 v76, v66
	v_mov_b32_e32 v77, v66
	v_mov_b32_e32 v78, v66
	v_mov_b32_e32 v79, v66
	v_mov_b32_e32 v80, v66
	v_mov_b32_e32 v81, v66
	v_sub_f32_e32 v142, v142, v90
	v_sub_f32_e32 v143, v143, v90
	v_sub_f32_e32 v144, v144, v90
	v_sub_f32_e32 v145, v145, v90
	v_sub_f32_e32 v146, v146, v90
	v_sub_f32_e32 v147, v147, v90
	v_sub_f32_e32 v148, v148, v90
	v_sub_f32_e32 v149, v149, v90
	v_sub_f32_e32 v150, v150, v90
	v_sub_f32_e32 v151, v151, v90
	v_sub_f32_e32 v152, v152, v90
	v_sub_f32_e32 v153, v153, v90
	v_sub_f32_e32 v154, v154, v90
	v_sub_f32_e32 v155, v155, v90
	v_sub_f32_e32 v156, v156, v90
	v_sub_f32_e32 v157, v157, v90
	v_sub_f32_e32 v158, v158, v90
	v_sub_f32_e32 v159, v159, v90
	v_sub_f32_e32 v160, v160, v90
	v_sub_f32_e32 v161, v161, v90
	v_sub_f32_e32 v162, v162, v90
	v_sub_f32_e32 v163, v163, v90
	v_sub_f32_e32 v164, v164, v90
	v_sub_f32_e32 v165, v165, v90
	v_sub_f32_e32 v166, v166, v90
	v_sub_f32_e32 v167, v167, v90
	v_sub_f32_e32 v168, v168, v90
	v_sub_f32_e32 v169, v169, v90
	v_sub_f32_e32 v170, v170, v90
	v_sub_f32_e32 v171, v171, v90
	v_sub_f32_e32 v172, v172, v90
	v_sub_f32_e32 v173, v173, v90
	v_mul_f32_e32 v236, v236, v91
	s_mov_b64 s[96:97], exec
	s_and_b64 exec, exec, s[8:9]
	ds_write_b32 v235, v91
	s_mov_b64 exec, s[96:97]
	v_lshl_add_u32 v2, v228, 4, s47
	ds_read_b128 v[94:97], v2 offset:0
	s_waitcnt lgkmcnt(0)
	v_mul_f32_e32 v34, v34, v94
	v_mul_f32_e32 v50, v50, v94
	v_mul_f32_e32 v35, v35, v95
	v_mul_f32_e32 v51, v51, v95
	v_mul_f32_e32 v36, v36, v96
	v_mul_f32_e32 v52, v52, v96
	v_mul_f32_e32 v37, v37, v97
	v_mul_f32_e32 v53, v53, v97
	ds_read_b128 v[94:97], v2 offset:32
	s_waitcnt lgkmcnt(0)
	v_mul_f32_e32 v38, v38, v94
	v_mul_f32_e32 v54, v54, v94
	v_mul_f32_e32 v39, v39, v95
	v_mul_f32_e32 v55, v55, v95
	v_mul_f32_e32 v40, v40, v96
	v_mul_f32_e32 v56, v56, v96
	v_mul_f32_e32 v41, v41, v97
	v_mul_f32_e32 v57, v57, v97
	ds_read_b128 v[94:97], v2 offset:64
	s_waitcnt lgkmcnt(0)
	v_mul_f32_e32 v42, v42, v94
	v_mul_f32_e32 v58, v58, v94
	v_mul_f32_e32 v43, v43, v95
	v_mul_f32_e32 v59, v59, v95
	v_mul_f32_e32 v44, v44, v96
	v_mul_f32_e32 v60, v60, v96
	v_mul_f32_e32 v45, v45, v97
	v_mul_f32_e32 v61, v61, v97
	ds_read_b128 v[94:97], v2 offset:96
	s_waitcnt lgkmcnt(0)
	v_mul_f32_e32 v46, v46, v94
	v_mul_f32_e32 v62, v62, v94
	v_mul_f32_e32 v47, v47, v95
	v_mul_f32_e32 v63, v63, v95
	v_mul_f32_e32 v48, v48, v96
	v_mul_f32_e32 v64, v64, v96
	v_mul_f32_e32 v49, v49, v97
	v_mul_f32_e32 v65, v65, v97
.Lmy_nors_7:
	s_waitcnt lgkmcnt(0)
	v_add_u32_e32 v2, 0x2000, v237
	v_mfma_f32_32x32x16_bf16 v[82:97], v[218:221], v[4:7], v[66:81]
	v_exp_f32_e32 v142, v142
	v_exp_f32_e32 v143, v143
	v_exp_f32_e32 v144, v144
	v_add_f32_e32 v27, v142, v143
	v_exp_f32_e32 v145, v145
	ds_read_b64_tr_b16 v[114:115], v2 offset:49152
	ds_read_b64_tr_b16 v[116:117], v2 offset:49664
	ds_read_b64_tr_b16 v[118:119], v2 offset:50176
	ds_read_b64_tr_b16 v[120:121], v2 offset:50688
	v_mfma_f32_32x32x16_bf16 v[98:113], v[214:217], v[4:7], v[66:81]
	v_exp_f32_e32 v146, v146
	v_add_f32_e32 v27, v27, v144
	v_exp_f32_e32 v147, v147
	v_add_f32_e32 v27, v27, v145
	v_exp_f32_e32 v148, v148
	ds_read_b64_tr_b16 v[122:123], v2 offset:51200
	ds_read_b64_tr_b16 v[124:125], v2 offset:51712
	ds_read_b64_tr_b16 v[126:127], v2 offset:52224
	ds_read_b64_tr_b16 v[128:129], v2 offset:52736
	v_mfma_f32_32x32x16_bf16 v[82:97], v[210:213], v[8:11], v[82:97]
	v_add_f32_e32 v27, v27, v146
	v_exp_f32_e32 v149, v149
	v_add_f32_e32 v27, v27, v147
	v_add_f32_e32 v27, v27, v148
	v_add_f32_e32 v27, v27, v149
	ds_read_b64_tr_b16 v[240:241], v2 offset:53248
	ds_read_b64_tr_b16 v[242:243], v2 offset:53760
	ds_read_b64_tr_b16 v[244:245], v2 offset:54272
	ds_read_b64_tr_b16 v[246:247], v2 offset:54784
	v_mfma_f32_32x32x16_bf16 v[98:113], v[206:209], v[8:11], v[98:113]
	v_cvt_pk_bf16_f32 v142, v142, v143
	v_cvt_pk_bf16_f32 v143, v144, v145
	v_cvt_pk_bf16_f32 v144, v146, v147
	v_cvt_pk_bf16_f32 v145, v148, v149
	ds_read_b64_tr_b16 v[248:249], v2 offset:55296
	ds_read_b64_tr_b16 v[250:251], v2 offset:55808
	ds_read_b64_tr_b16 v[20:21], v2 offset:56320
	ds_read_b64_tr_b16 v[22:23], v2 offset:56832
	v_mfma_f32_32x32x16_bf16 v[82:97], v[202:205], v[12:15], v[82:97]
	v_exp_f32_e32 v150, v150
	v_exp_f32_e32 v151, v151
	v_exp_f32_e32 v152, v152
	v_add_f32_e32 v27, v27, v150
	v_exp_f32_e32 v153, v153
	v_mfma_f32_32x32x16_bf16 v[98:113], v[198:201], v[12:15], v[98:113]
	v_add_f32_e32 v27, v27, v151
	v_exp_f32_e32 v154, v154
	v_add_f32_e32 v27, v27, v152
	v_exp_f32_e32 v155, v155
	v_add_f32_e32 v27, v27, v153
	s_waitcnt vmcnt(6)
	s_barrier
	v_mfma_f32_32x32x16_bf16 v[82:97], v[194:197], v[130:133], v[82:97]
	s_add_u32 m0, s57, 0x0
	v_exp_f32_e32 v156, v156
	v_add_f32_e32 v27, v27, v154
	global_load_lds_dwordx4 v[28:29], off
	v_lshl_add_u64 v[28:29], v[28:29], 0, s[30:31]
	v_exp_f32_e32 v157, v157
	v_add_f32_e32 v27, v27, v155
	v_add_f32_e32 v27, v27, v156
	v_mfma_f32_32x32x16_bf16 v[98:113], v[190:193], v[130:133], v[98:113]
	s_add_u32 m0, s40, 0x6000
	v_add_f32_e32 v27, v27, v157
	v_cvt_pk_bf16_f32 v150, v150, v151
	global_load_lds_dwordx4 v[24:25], off
	v_lshl_add_u64 v[24:25], v[24:25], 0, s[30:31]
	v_cvt_pk_bf16_f32 v151, v152, v153
	v_cvt_pk_bf16_f32 v152, v154, v155
	v_cvt_pk_bf16_f32 v153, v156, v157
	v_mfma_f32_32x32x16_bf16 v[82:97], v[186:189], v[134:137], v[82:97]
	s_add_u32 m0, s43, 0x6000
	v_exp_f32_e32 v158, v158
	v_exp_f32_e32 v159, v159
	global_load_lds_dwordx4 v[30:31], off
	v_lshl_add_u64 v[30:31], v[30:31], 0, s[12:13]
	v_exp_f32_e32 v160, v160
	v_add_f32_e32 v27, v27, v158
	v_exp_f32_e32 v161, v161
	v_mfma_f32_32x32x16_bf16 v[98:113], v[182:185], v[134:137], v[98:113]
	v_add_f32_e32 v27, v27, v159
	v_exp_f32_e32 v162, v162
	v_add_f32_e32 v27, v27, v160
	v_exp_f32_e32 v163, v163
	v_add_f32_e32 v27, v27, v161
	v_mfma_f32_32x32x16_bf16 v[82:97], v[178:181], v[138:141], v[82:97]
	v_exp_f32_e32 v164, v164
	v_add_f32_e32 v27, v27, v162
	v_exp_f32_e32 v165, v165
	v_add_f32_e32 v27, v27, v163
	v_add_f32_e32 v27, v27, v164
	v_mfma_f32_32x32x16_bf16 v[98:113], v[174:177], v[138:141], v[98:113]
	v_add_f32_e32 v27, v27, v165
	v_cvt_pk_bf16_f32 v158, v158, v159
	v_cvt_pk_bf16_f32 v159, v160, v161
	v_cvt_pk_bf16_f32 v160, v162, v163
	v_cvt_pk_bf16_f32 v161, v164, v165
	s_waitcnt lgkmcnt(0)
	v_add_u32_e32 v2, 0x9000, v238
	v_mfma_f32_32x32x16_bf16 v[34:49], v[142:145], v[114:117], v[34:49]
	v_exp_f32_e32 v166, v166
	v_exp_f32_e32 v167, v167
	v_exp_f32_e32 v168, v168
	v_add_f32_e32 v27, v27, v166
	v_exp_f32_e32 v169, v169
	v_add_f32_e32 v27, v27, v167
	v_exp_f32_e32 v170, v170
	v_add_f32_e32 v27, v27, v168
	v_exp_f32_e32 v171, v171
	v_add_f32_e32 v27, v27, v169
	ds_read_b128 v[218:221], v2
	ds_read_b128 v[214:217], v2 offset:512
	ds_read_b128 v[210:213], v2 offset:2048
	v_mfma_f32_32x32x16_bf16 v[50:65], v[142:145], v[240:243], v[50:65]
	v_exp_f32_e32 v172, v172
	v_add_f32_e32 v27, v27, v170
	v_exp_f32_e32 v173, v173
	v_add_f32_e32 v27, v27, v171
	v_add_f32_e32 v27, v27, v172
	v_add_f32_e32 v27, v27, v173
	v_cvt_pk_bf16_f32 v166, v166, v167
	v_cvt_pk_bf16_f32 v167, v168, v169
	v_cvt_pk_bf16_f32 v168, v170, v171
	v_cvt_pk_bf16_f32 v169, v172, v173
	v_add_f32_e32 v236, v236, v27
	ds_read_b128 v[206:209], v2 offset:2560
	ds_read_b128 v[202:205], v2 offset:4096
	ds_read_b128 v[198:201], v2 offset:4608
	v_mfma_f32_32x32x16_bf16 v[34:49], v[150:153], v[118:121], v[34:49]
	ds_read_b128 v[194:197], v2 offset:6144
	ds_read_b128 v[190:193], v2 offset:6656
	ds_read_b128 v[186:189], v2 offset:8192
	v_max3_f32 v19, v82, v83, v84
	v_max3_f32 v26, v85, v86, v87
	v_max3_f32 v19, v19, v88, v89
	v_max3_f32 v26, v26, v90, v91
	v_max3_f32 v19, v19, v92, v93
	v_mfma_f32_32x32x16_bf16 v[50:65], v[150:153], v[244:247], v[50:65]
	ds_read_b128 v[182:185], v2 offset:8704
	ds_read_b128 v[178:181], v2 offset:10240
	ds_read_b128 v[174:177], v2 offset:10752
	v_max3_f32 v26, v26, v94, v95
	v_max3_f32 v19, v19, v96, v97
	v_max3_f32 v26, v26, v98, v99
	v_max3_f32 v19, v19, v100, v101
	v_max3_f32 v26, v26, v102, v103
	v_mfma_f32_32x32x16_bf16 v[34:49], v[158:161], v[122:125], v[34:49]
	v_max3_f32 v19, v19, v104, v105
	v_max3_f32 v26, v26, v106, v107
	v_max3_f32 v19, v19, v108, v109
	v_max3_f32 v26, v26, v110, v111
	v_mfma_f32_32x32x16_bf16 v[50:65], v[158:161], v[248:251], v[50:65]
	v_max3_f32 v19, v19, v112, v113
	v_max_f32_e32 v19, v19, v26
	v_mfma_f32_32x32x16_bf16 v[34:49], v[166:169], v[126:129], v[34:49]
	v_mfma_f32_32x32x16_bf16 v[50:65], v[166:169], v[20:23], v[50:65]
	v_cmp_lt_f32_e32 vcc, s41, v19
	s_cbranch_vccz .Lmy_nors_8
	s_nop 15
	s_nop 15
	v_mov_b32_e32 v26, v19
	s_nop 1
	v_permlane32_swap_b32_e32 v19, v26
	v_max_f32_e32 v19, v19, v26
	v_max_f32_e32 v19, v19, v19
	v_max_f32_e32 v150, 0, v19
	v_exp_f32_e64 v151, -v150
	v_add_f32_e32 v239, v239, v150
	v_xor_b32_e32 v66, 0x80000000, v239
	v_mov_b32_e32 v67, v66
	v_mov_b32_e32 v68, v66
	v_mov_b32_e32 v69, v66
	v_mov_b32_e32 v70, v66
	v_mov_b32_e32 v71, v66
	v_mov_b32_e32 v72, v66
	v_mov_b32_e32 v73, v66
	v_mov_b32_e32 v74, v66
	v_mov_b32_e32 v75, v66
	v_mov_b32_e32 v76, v66
	v_mov_b32_e32 v77, v66
	v_mov_b32_e32 v78, v66
	v_mov_b32_e32 v79, v66
	v_mov_b32_e32 v80, v66
	v_mov_b32_e32 v81, v66
	v_sub_f32_e32 v82, v82, v150
	v_sub_f32_e32 v83, v83, v150
	v_sub_f32_e32 v84, v84, v150
	v_sub_f32_e32 v85, v85, v150
	v_sub_f32_e32 v86, v86, v150
	v_sub_f32_e32 v87, v87, v150
	v_sub_f32_e32 v88, v88, v150
	v_sub_f32_e32 v89, v89, v150
	v_sub_f32_e32 v90, v90, v150
	v_sub_f32_e32 v91, v91, v150
	v_sub_f32_e32 v92, v92, v150
	v_sub_f32_e32 v93, v93, v150
	v_sub_f32_e32 v94, v94, v150
	v_sub_f32_e32 v95, v95, v150
	v_sub_f32_e32 v96, v96, v150
	v_sub_f32_e32 v97, v97, v150
	v_sub_f32_e32 v98, v98, v150
	v_sub_f32_e32 v99, v99, v150
	v_sub_f32_e32 v100, v100, v150
	v_sub_f32_e32 v101, v101, v150
	v_sub_f32_e32 v102, v102, v150
	v_sub_f32_e32 v103, v103, v150
	v_sub_f32_e32 v104, v104, v150
	v_sub_f32_e32 v105, v105, v150
	v_sub_f32_e32 v106, v106, v150
	v_sub_f32_e32 v107, v107, v150
	v_sub_f32_e32 v108, v108, v150
	v_sub_f32_e32 v109, v109, v150
	v_sub_f32_e32 v110, v110, v150
	v_sub_f32_e32 v111, v111, v150
	v_sub_f32_e32 v112, v112, v150
	v_sub_f32_e32 v113, v113, v150
	v_mul_f32_e32 v236, v236, v151
	s_mov_b64 s[96:97], exec
	s_and_b64 exec, exec, s[8:9]
	ds_write_b32 v235, v151
	s_mov_b64 exec, s[96:97]
	v_lshl_add_u32 v2, v228, 4, s47
	ds_read_b128 v[154:157], v2 offset:0
	s_waitcnt lgkmcnt(0)
	v_mul_f32_e32 v34, v34, v154
	v_mul_f32_e32 v50, v50, v154
	v_mul_f32_e32 v35, v35, v155
	v_mul_f32_e32 v51, v51, v155
	v_mul_f32_e32 v36, v36, v156
	v_mul_f32_e32 v52, v52, v156
	v_mul_f32_e32 v37, v37, v157
	v_mul_f32_e32 v53, v53, v157
	ds_read_b128 v[154:157], v2 offset:32
	s_waitcnt lgkmcnt(0)
	v_mul_f32_e32 v38, v38, v154
	v_mul_f32_e32 v54, v54, v154
	v_mul_f32_e32 v39, v39, v155
	v_mul_f32_e32 v55, v55, v155
	v_mul_f32_e32 v40, v40, v156
	v_mul_f32_e32 v56, v56, v156
	v_mul_f32_e32 v41, v41, v157
	v_mul_f32_e32 v57, v57, v157
	ds_read_b128 v[154:157], v2 offset:64
	s_waitcnt lgkmcnt(0)
	v_mul_f32_e32 v42, v42, v154
	v_mul_f32_e32 v58, v58, v154
	v_mul_f32_e32 v43, v43, v155
	v_mul_f32_e32 v59, v59, v155
	v_mul_f32_e32 v44, v44, v156
	v_mul_f32_e32 v60, v60, v156
	v_mul_f32_e32 v45, v45, v157
	v_mul_f32_e32 v61, v61, v157
	ds_read_b128 v[154:157], v2 offset:96
	s_waitcnt lgkmcnt(0)
	v_mul_f32_e32 v46, v46, v154
	v_mul_f32_e32 v62, v62, v154
	v_mul_f32_e32 v47, v47, v155
	v_mul_f32_e32 v63, v63, v155
	v_mul_f32_e32 v48, v48, v156
	v_mul_f32_e32 v64, v64, v156
	v_mul_f32_e32 v49, v49, v157
	v_mul_f32_e32 v65, v65, v157
.Lmy_nors_8:
	s_waitcnt lgkmcnt(0)
	v_add_u32_e32 v2, 0x4000, v237
	v_mfma_f32_32x32x16_bf16 v[142:157], v[218:221], v[4:7], v[66:81]
	v_exp_f32_e32 v82, v82
	v_exp_f32_e32 v83, v83
	v_exp_f32_e32 v84, v84
	v_add_f32_e32 v27, v82, v83
	v_exp_f32_e32 v85, v85
	ds_read_b64_tr_b16 v[114:115], v2 offset:49152
	ds_read_b64_tr_b16 v[116:117], v2 offset:49664
	ds_read_b64_tr_b16 v[118:119], v2 offset:50176
	ds_read_b64_tr_b16 v[120:121], v2 offset:50688
	v_mfma_f32_32x32x16_bf16 v[158:173], v[214:217], v[4:7], v[66:81]
	v_exp_f32_e32 v86, v86
	v_add_f32_e32 v27, v27, v84
	v_exp_f32_e32 v87, v87
	v_add_f32_e32 v27, v27, v85
	v_exp_f32_e32 v88, v88
	ds_read_b64_tr_b16 v[122:123], v2 offset:51200
	ds_read_b64_tr_b16 v[124:125], v2 offset:51712
	ds_read_b64_tr_b16 v[126:127], v2 offset:52224
	ds_read_b64_tr_b16 v[128:129], v2 offset:52736
	v_mfma_f32_32x32x16_bf16 v[142:157], v[210:213], v[8:11], v[142:157]
	v_add_f32_e32 v27, v27, v86
	v_exp_f32_e32 v89, v89
	v_add_f32_e32 v27, v27, v87
	v_add_f32_e32 v27, v27, v88
	v_add_f32_e32 v27, v27, v89
	ds_read_b64_tr_b16 v[240:241], v2 offset:53248
	ds_read_b64_tr_b16 v[242:243], v2 offset:53760
	ds_read_b64_tr_b16 v[244:245], v2 offset:54272
	ds_read_b64_tr_b16 v[246:247], v2 offset:54784
	v_mfma_f32_32x32x16_bf16 v[158:173], v[206:209], v[8:11], v[158:173]
	v_cvt_pk_bf16_f32 v82, v82, v83
	v_cvt_pk_bf16_f32 v83, v84, v85
	v_cvt_pk_bf16_f32 v84, v86, v87
	v_cvt_pk_bf16_f32 v85, v88, v89
	ds_read_b64_tr_b16 v[248:249], v2 offset:55296
	ds_read_b64_tr_b16 v[250:251], v2 offset:55808
	ds_read_b64_tr_b16 v[20:21], v2 offset:56320
	ds_read_b64_tr_b16 v[22:23], v2 offset:56832
	v_mfma_f32_32x32x16_bf16 v[142:157], v[202:205], v[12:15], v[142:157]
	v_exp_f32_e32 v90, v90
	v_exp_f32_e32 v91, v91
	v_exp_f32_e32 v92, v92
	v_add_f32_e32 v27, v27, v90
	v_exp_f32_e32 v93, v93
	v_mfma_f32_32x32x16_bf16 v[158:173], v[198:201], v[12:15], v[158:173]
	v_add_f32_e32 v27, v27, v91
	v_exp_f32_e32 v94, v94
	v_add_f32_e32 v27, v27, v92
	v_exp_f32_e32 v95, v95
	v_add_f32_e32 v27, v27, v93
	s_waitcnt vmcnt(6)
	s_barrier
	v_mfma_f32_32x32x16_bf16 v[142:157], v[194:197], v[130:133], v[142:157]
	s_add_u32 m0, s57, 0x2000
	v_exp_f32_e32 v96, v96
	v_add_f32_e32 v27, v27, v94
	global_load_lds_dwordx4 v[28:29], off
	v_lshl_add_u64 v[28:29], v[28:29], 0, s[30:31]
	v_exp_f32_e32 v97, v97
	v_add_f32_e32 v27, v27, v95
	v_add_f32_e32 v27, v27, v96
	v_mfma_f32_32x32x16_bf16 v[158:173], v[190:193], v[130:133], v[158:173]
	s_add_u32 m0, s40, 0x9000
	v_add_f32_e32 v27, v27, v97
	v_cvt_pk_bf16_f32 v90, v90, v91
	global_load_lds_dwordx4 v[24:25], off
	v_lshl_add_u64 v[24:25], v[24:25], 0, s[30:31]
	v_cvt_pk_bf16_f32 v91, v92, v93
	v_cvt_pk_bf16_f32 v92, v94, v95
	v_cvt_pk_bf16_f32 v93, v96, v97
	v_mfma_f32_32x32x16_bf16 v[142:157], v[186:189], v[134:137], v[142:157]
	s_add_u32 m0, s43, 0x9000
	v_exp_f32_e32 v98, v98
	v_exp_f32_e32 v99, v99
	global_load_lds_dwordx4 v[30:31], off
	v_lshl_add_u64 v[30:31], v[30:31], 0, s[12:13]
	v_exp_f32_e32 v100, v100
	v_add_f32_e32 v27, v27, v98
	v_exp_f32_e32 v101, v101
	v_mfma_f32_32x32x16_bf16 v[158:173], v[182:185], v[134:137], v[158:173]
	v_add_f32_e32 v27, v27, v99
	v_exp_f32_e32 v102, v102
	v_add_f32_e32 v27, v27, v100
	v_exp_f32_e32 v103, v103
	v_add_f32_e32 v27, v27, v101
	v_mfma_f32_32x32x16_bf16 v[142:157], v[178:181], v[138:141], v[142:157]
	v_exp_f32_e32 v104, v104
	v_add_f32_e32 v27, v27, v102
	v_exp_f32_e32 v105, v105
	v_add_f32_e32 v27, v27, v103
	v_add_f32_e32 v27, v27, v104
	v_mfma_f32_32x32x16_bf16 v[158:173], v[174:177], v[138:141], v[158:173]
	v_add_f32_e32 v27, v27, v105
	v_cvt_pk_bf16_f32 v98, v98, v99
	v_cvt_pk_bf16_f32 v99, v100, v101
	v_cvt_pk_bf16_f32 v100, v102, v103
	v_cvt_pk_bf16_f32 v101, v104, v105
	s_waitcnt lgkmcnt(0)
	v_mov_b32_e32 v2, v238
	v_mfma_f32_32x32x16_bf16 v[34:49], v[82:85], v[114:117], v[34:49]
	v_exp_f32_e32 v106, v106
	v_exp_f32_e32 v107, v107
	v_exp_f32_e32 v108, v108
	v_add_f32_e32 v27, v27, v106
	v_exp_f32_e32 v109, v109
	v_add_f32_e32 v27, v27, v107
	v_exp_f32_e32 v110, v110
	v_add_f32_e32 v27, v27, v108
	v_exp_f32_e32 v111, v111
	v_add_f32_e32 v27, v27, v109
	ds_read_b128 v[218:221], v2
	ds_read_b128 v[214:217], v2 offset:512
	ds_read_b128 v[210:213], v2 offset:2048
	v_mfma_f32_32x32x16_bf16 v[50:65], v[82:85], v[240:243], v[50:65]
	v_exp_f32_e32 v112, v112
	v_add_f32_e32 v27, v27, v110
	v_exp_f32_e32 v113, v113
	v_add_f32_e32 v27, v27, v111
	v_add_f32_e32 v27, v27, v112
	v_add_f32_e32 v27, v27, v113
	v_cvt_pk_bf16_f32 v106, v106, v107
	v_cvt_pk_bf16_f32 v107, v108, v109
	v_cvt_pk_bf16_f32 v108, v110, v111
	v_cvt_pk_bf16_f32 v109, v112, v113
	v_add_f32_e32 v236, v236, v27
	ds_read_b128 v[206:209], v2 offset:2560
	ds_read_b128 v[202:205], v2 offset:4096
	ds_read_b128 v[198:201], v2 offset:4608
	v_mfma_f32_32x32x16_bf16 v[34:49], v[90:93], v[118:121], v[34:49]
	ds_read_b128 v[194:197], v2 offset:6144
	ds_read_b128 v[190:193], v2 offset:6656
	ds_read_b128 v[186:189], v2 offset:8192
	v_max3_f32 v19, v142, v143, v144
	v_max3_f32 v26, v145, v146, v147
	v_max3_f32 v19, v19, v148, v149
	v_max3_f32 v26, v26, v150, v151
	v_max3_f32 v19, v19, v152, v153
	v_mfma_f32_32x32x16_bf16 v[50:65], v[90:93], v[244:247], v[50:65]
	ds_read_b128 v[182:185], v2 offset:8704
	ds_read_b128 v[178:181], v2 offset:10240
	ds_read_b128 v[174:177], v2 offset:10752
	v_max3_f32 v26, v26, v154, v155
	v_max3_f32 v19, v19, v156, v157
	v_max3_f32 v26, v26, v158, v159
	v_max3_f32 v19, v19, v160, v161
	v_max3_f32 v26, v26, v162, v163
	v_mfma_f32_32x32x16_bf16 v[34:49], v[98:101], v[122:125], v[34:49]
	v_max3_f32 v19, v19, v164, v165
	v_max3_f32 v26, v26, v166, v167
	v_max3_f32 v19, v19, v168, v169
	v_max3_f32 v26, v26, v170, v171
	v_mfma_f32_32x32x16_bf16 v[50:65], v[98:101], v[248:251], v[50:65]
	v_max3_f32 v19, v19, v172, v173
	v_max_f32_e32 v19, v19, v26
	v_mfma_f32_32x32x16_bf16 v[34:49], v[106:109], v[126:129], v[34:49]
	v_mfma_f32_32x32x16_bf16 v[50:65], v[106:109], v[20:23], v[50:65]
	v_cmp_lt_f32_e32 vcc, s41, v19
	s_cbranch_vccz .Lmy_nors_9
	s_nop 15
	s_nop 15
	v_mov_b32_e32 v26, v19
	s_nop 1
	v_permlane32_swap_b32_e32 v19, v26
	v_max_f32_e32 v19, v19, v26
	v_max_f32_e32 v19, v19, v19
	v_max_f32_e32 v90, 0, v19
	v_exp_f32_e64 v91, -v90
	v_add_f32_e32 v239, v239, v90
	v_xor_b32_e32 v66, 0x80000000, v239
	v_mov_b32_e32 v67, v66
	v_mov_b32_e32 v68, v66
	v_mov_b32_e32 v69, v66
	v_mov_b32_e32 v70, v66
	v_mov_b32_e32 v71, v66
	v_mov_b32_e32 v72, v66
	v_mov_b32_e32 v73, v66
	v_mov_b32_e32 v74, v66
	v_mov_b32_e32 v75, v66
	v_mov_b32_e32 v76, v66
	v_mov_b32_e32 v77, v66
	v_mov_b32_e32 v78, v66
	v_mov_b32_e32 v79, v66
	v_mov_b32_e32 v80, v66
	v_mov_b32_e32 v81, v66
	v_sub_f32_e32 v142, v142, v90
	v_sub_f32_e32 v143, v143, v90
	v_sub_f32_e32 v144, v144, v90
	v_sub_f32_e32 v145, v145, v90
	v_sub_f32_e32 v146, v146, v90
	v_sub_f32_e32 v147, v147, v90
	v_sub_f32_e32 v148, v148, v90
	v_sub_f32_e32 v149, v149, v90
	v_sub_f32_e32 v150, v150, v90
	v_sub_f32_e32 v151, v151, v90
	v_sub_f32_e32 v152, v152, v90
	v_sub_f32_e32 v153, v153, v90
	v_sub_f32_e32 v154, v154, v90
	v_sub_f32_e32 v155, v155, v90
	v_sub_f32_e32 v156, v156, v90
	v_sub_f32_e32 v157, v157, v90
	v_sub_f32_e32 v158, v158, v90
	v_sub_f32_e32 v159, v159, v90
	v_sub_f32_e32 v160, v160, v90
	v_sub_f32_e32 v161, v161, v90
	v_sub_f32_e32 v162, v162, v90
	v_sub_f32_e32 v163, v163, v90
	v_sub_f32_e32 v164, v164, v90
	v_sub_f32_e32 v165, v165, v90
	v_sub_f32_e32 v166, v166, v90
	v_sub_f32_e32 v167, v167, v90
	v_sub_f32_e32 v168, v168, v90
	v_sub_f32_e32 v169, v169, v90
	v_sub_f32_e32 v170, v170, v90
	v_sub_f32_e32 v171, v171, v90
	v_sub_f32_e32 v172, v172, v90
	v_sub_f32_e32 v173, v173, v90
	v_mul_f32_e32 v236, v236, v91
	s_mov_b64 s[96:97], exec
	s_and_b64 exec, exec, s[8:9]
	ds_write_b32 v235, v91
	s_mov_b64 exec, s[96:97]
	v_lshl_add_u32 v2, v228, 4, s47
	ds_read_b128 v[94:97], v2 offset:0
	s_waitcnt lgkmcnt(0)
	v_mul_f32_e32 v34, v34, v94
	v_mul_f32_e32 v50, v50, v94
	v_mul_f32_e32 v35, v35, v95
	v_mul_f32_e32 v51, v51, v95
	v_mul_f32_e32 v36, v36, v96
	v_mul_f32_e32 v52, v52, v96
	v_mul_f32_e32 v37, v37, v97
	v_mul_f32_e32 v53, v53, v97
	ds_read_b128 v[94:97], v2 offset:32
	s_waitcnt lgkmcnt(0)
	v_mul_f32_e32 v38, v38, v94
	v_mul_f32_e32 v54, v54, v94
	v_mul_f32_e32 v39, v39, v95
	v_mul_f32_e32 v55, v55, v95
	v_mul_f32_e32 v40, v40, v96
	v_mul_f32_e32 v56, v56, v96
	v_mul_f32_e32 v41, v41, v97
	v_mul_f32_e32 v57, v57, v97
	ds_read_b128 v[94:97], v2 offset:64
	s_waitcnt lgkmcnt(0)
	v_mul_f32_e32 v42, v42, v94
	v_mul_f32_e32 v58, v58, v94
	v_mul_f32_e32 v43, v43, v95
	v_mul_f32_e32 v59, v59, v95
	v_mul_f32_e32 v44, v44, v96
	v_mul_f32_e32 v60, v60, v96
	v_mul_f32_e32 v45, v45, v97
	v_mul_f32_e32 v61, v61, v97
	ds_read_b128 v[94:97], v2 offset:96
	s_waitcnt lgkmcnt(0)
	v_mul_f32_e32 v46, v46, v94
	v_mul_f32_e32 v62, v62, v94
	v_mul_f32_e32 v47, v47, v95
	v_mul_f32_e32 v63, v63, v95
	v_mul_f32_e32 v48, v48, v96
	v_mul_f32_e32 v64, v64, v96
	v_mul_f32_e32 v49, v49, v97
	v_mul_f32_e32 v65, v65, v97

.Lmy_B_entry:
	s_mov_b32 s30, 0x20000
	s_mov_b32 s31, 0
	s_mov_b32 s12, 0x1000
	s_mov_b32 s13, 0
	s_lshr_b32 s71, s24, 1
	s_lshr_b32 s79, s25, 2
	s_add_i32 s79, s79, -1
	s_mov_b32 s0, 0x80000
	s_mov_b32 s1, 0
	v_lshl_add_u64 v[24:25], v[16:17], 0, s[0:1]
	s_mov_b32 s0, 0x60000
	v_lshl_add_u64 v[28:29], v[224:225], 0, s[0:1]
	s_mov_b32 s0, 0x4000
	v_lshl_add_u64 v[30:31], v[222:223], 0, s[0:1]
	s_waitcnt lgkmcnt(0)
	v_mfma_f32_32x32x16_bf16 v[82:97], v[218:221], v[4:7], v[66:81]
	v_mfma_f32_32x32x16_bf16 v[98:113], v[214:217], v[4:7], v[66:81]
	v_mfma_f32_32x32x16_bf16 v[82:97], v[210:213], v[8:11], v[82:97]
	v_mfma_f32_32x32x16_bf16 v[98:113], v[206:209], v[8:11], v[98:113]
	v_mfma_f32_32x32x16_bf16 v[82:97], v[202:205], v[12:15], v[82:97]
	v_mfma_f32_32x32x16_bf16 v[98:113], v[198:201], v[12:15], v[98:113]
	v_mfma_f32_32x32x16_bf16 v[82:97], v[194:197], v[130:133], v[82:97]
	v_mfma_f32_32x32x16_bf16 v[98:113], v[190:193], v[130:133], v[98:113]
	v_mfma_f32_32x32x16_bf16 v[82:97], v[186:189], v[134:137], v[82:97]
	v_mfma_f32_32x32x16_bf16 v[98:113], v[182:185], v[134:137], v[98:113]
	v_mfma_f32_32x32x16_bf16 v[82:97], v[178:181], v[138:141], v[82:97]
	v_mfma_f32_32x32x16_bf16 v[98:113], v[174:177], v[138:141], v[98:113]
	v_add_u32_e32 v2, 0x3000, v238
	ds_read_b128 v[218:221], v2
	ds_read_b128 v[214:217], v2 offset:512
	ds_read_b128 v[210:213], v2 offset:2048
	ds_read_b128 v[206:209], v2 offset:2560
	ds_read_b128 v[202:205], v2 offset:4096
	ds_read_b128 v[198:201], v2 offset:4608
	ds_read_b128 v[194:197], v2 offset:6144
	ds_read_b128 v[190:193], v2 offset:6656
	ds_read_b128 v[186:189], v2 offset:8192
	ds_read_b128 v[182:185], v2 offset:8704
	ds_read_b128 v[178:181], v2 offset:10240
	ds_read_b128 v[174:177], v2 offset:10752
	s_nop 7
	v_max3_f32 v19, v82, v83, v84
	v_max3_f32 v26, v85, v86, v87
	v_max3_f32 v19, v19, v88, v89
	v_max3_f32 v26, v26, v90, v91
	v_max3_f32 v19, v19, v92, v93
	v_max3_f32 v26, v26, v94, v95
	v_max3_f32 v19, v19, v96, v97
	v_max3_f32 v26, v26, v98, v99
	v_max3_f32 v19, v19, v100, v101
	v_max3_f32 v26, v26, v102, v103
	v_max3_f32 v19, v19, v104, v105
	v_max3_f32 v26, v26, v106, v107
	v_max3_f32 v19, v19, v108, v109
	v_max3_f32 v26, v26, v110, v111
	v_max3_f32 v19, v19, v112, v113
	v_max_f32_e32 v19, v19, v26
	v_mov_b32_e32 v26, v19
	s_nop 1
	v_permlane32_swap_b32_e32 v19, v26
	v_max_f32_e32 v19, v19, v26
	v_max_f32_e32 v19, v19, v19
	v_mov_b32_e32 v239, v19
	v_xor_b32_e32 v66, 0x80000000, v19
	v_mov_b32_e32 v67, v66
	v_mov_b32_e32 v68, v66
	v_mov_b32_e32 v69, v66
	v_mov_b32_e32 v70, v66
	v_mov_b32_e32 v71, v66
	v_mov_b32_e32 v72, v66
	v_mov_b32_e32 v73, v66
	v_mov_b32_e32 v74, v66
	v_mov_b32_e32 v75, v66
	v_mov_b32_e32 v76, v66
	v_mov_b32_e32 v77, v66
	v_mov_b32_e32 v78, v66
	v_mov_b32_e32 v79, v66
	v_mov_b32_e32 v80, v66
	v_mov_b32_e32 v81, v66
	v_sub_f32_e32 v82, v82, v19
	v_sub_f32_e32 v83, v83, v19
	v_sub_f32_e32 v84, v84, v19
	v_sub_f32_e32 v85, v85, v19
	v_sub_f32_e32 v86, v86, v19
	v_sub_f32_e32 v87, v87, v19
	v_sub_f32_e32 v88, v88, v19
	v_sub_f32_e32 v89, v89, v19
	v_sub_f32_e32 v90, v90, v19
	v_sub_f32_e32 v91, v91, v19
	v_sub_f32_e32 v92, v92, v19
	v_sub_f32_e32 v93, v93, v19
	v_sub_f32_e32 v94, v94, v19
	v_sub_f32_e32 v95, v95, v19
	v_sub_f32_e32 v96, v96, v19
	v_sub_f32_e32 v97, v97, v19
	v_sub_f32_e32 v98, v98, v19
	v_sub_f32_e32 v99, v99, v19
	v_sub_f32_e32 v100, v100, v19
	v_sub_f32_e32 v101, v101, v19
	v_sub_f32_e32 v102, v102, v19
	v_sub_f32_e32 v103, v103, v19
	v_sub_f32_e32 v104, v104, v19
	v_sub_f32_e32 v105, v105, v19
	v_sub_f32_e32 v106, v106, v19
	v_sub_f32_e32 v107, v107, v19
	v_sub_f32_e32 v108, v108, v19
	v_sub_f32_e32 v109, v109, v19
	v_sub_f32_e32 v110, v110, v19
	v_sub_f32_e32 v111, v111, v19
	v_sub_f32_e32 v112, v112, v19
	v_sub_f32_e32 v113, v113, v19
	s_cmp_lt_i32 s79, 1
	s_cbranch_scc1 .Lmy_B_tail
	s_waitcnt lgkmcnt(0)
	v_mov_b32_e32 v2, v237
	v_mfma_f32_32x32x16_bf16 v[142:157], v[218:221], v[4:7], v[66:81]
	v_exp_f32_e32 v82, v82
	v_exp_f32_e32 v83, v83
	v_exp_f32_e32 v84, v84
	v_add_f32_e32 v27, v82, v83
	v_exp_f32_e32 v85, v85
	ds_read_b64_tr_b16 v[114:115], v2 offset:49152
	ds_read_b64_tr_b16 v[116:117], v2 offset:49664
	ds_read_b64_tr_b16 v[118:119], v2 offset:50176
	ds_read_b64_tr_b16 v[120:121], v2 offset:50688
	v_mfma_f32_32x32x16_bf16 v[158:173], v[214:217], v[4:7], v[66:81]
	v_exp_f32_e32 v86, v86
	v_add_f32_e32 v27, v27, v84
	v_exp_f32_e32 v87, v87
	v_add_f32_e32 v27, v27, v85
	v_exp_f32_e32 v88, v88
	ds_read_b64_tr_b16 v[122:123], v2 offset:51200
	ds_read_b64_tr_b16 v[124:125], v2 offset:51712
	ds_read_b64_tr_b16 v[126:127], v2 offset:52224
	ds_read_b64_tr_b16 v[128:129], v2 offset:52736
	v_mfma_f32_32x32x16_bf16 v[142:157], v[210:213], v[8:11], v[142:157]
	v_add_f32_e32 v27, v27, v86
	v_exp_f32_e32 v89, v89
	v_add_f32_e32 v27, v27, v87
	v_add_f32_e32 v27, v27, v88
	v_add_f32_e32 v27, v27, v89
	ds_read_b64_tr_b16 v[240:241], v2 offset:53248
	ds_read_b64_tr_b16 v[242:243], v2 offset:53760
	ds_read_b64_tr_b16 v[244:245], v2 offset:54272
	ds_read_b64_tr_b16 v[246:247], v2 offset:54784
	v_mfma_f32_32x32x16_bf16 v[158:173], v[206:209], v[8:11], v[158:173]
	v_cvt_pk_bf16_f32 v82, v82, v83
	v_cvt_pk_bf16_f32 v83, v84, v85
	v_cvt_pk_bf16_f32 v84, v86, v87
	v_cvt_pk_bf16_f32 v85, v88, v89
	ds_read_b64_tr_b16 v[248:249], v2 offset:55296
	ds_read_b64_tr_b16 v[250:251], v2 offset:55808
	ds_read_b64_tr_b16 v[20:21], v2 offset:56320
	ds_read_b64_tr_b16 v[22:23], v2 offset:56832
	v_mfma_f32_32x32x16_bf16 v[142:157], v[202:205], v[12:15], v[142:157]
	v_exp_f32_e32 v90, v90
	v_exp_f32_e32 v91, v91
	v_exp_f32_e32 v92, v92
	v_add_f32_e32 v27, v27, v90
	v_exp_f32_e32 v93, v93
	v_mfma_f32_32x32x16_bf16 v[158:173], v[198:201], v[12:15], v[158:173]
	v_add_f32_e32 v27, v27, v91
	v_exp_f32_e32 v94, v94
	v_add_f32_e32 v27, v27, v92
	v_exp_f32_e32 v95, v95
	v_add_f32_e32 v27, v27, v93
	s_waitcnt vmcnt(2)
	s_barrier
	v_mfma_f32_32x32x16_bf16 v[142:157], v[194:197], v[130:133], v[142:157]
	s_add_u32 m0, s57, 0x6000
	v_exp_f32_e32 v96, v96
	v_add_f32_e32 v27, v27, v94
	global_load_lds_dwordx4 v[28:29], off
	v_lshl_add_u64 v[28:29], v[28:29], 0, s[30:31]
	v_exp_f32_e32 v97, v97
	v_add_f32_e32 v27, v27, v95
	v_add_f32_e32 v27, v27, v96
	v_mfma_f32_32x32x16_bf16 v[158:173], v[190:193], v[130:133], v[158:173]
	s_add_u32 m0, s40, 0x0
	v_add_f32_e32 v27, v27, v97
	v_cvt_pk_bf16_f32 v90, v90, v91
	global_load_lds_dwordx4 v[24:25], off
	v_lshl_add_u64 v[24:25], v[24:25], 0, s[30:31]
	v_cvt_pk_bf16_f32 v91, v92, v93
	v_cvt_pk_bf16_f32 v92, v94, v95
	v_cvt_pk_bf16_f32 v93, v96, v97
	v_mfma_f32_32x32x16_bf16 v[142:157], v[186:189], v[134:137], v[142:157]
	s_add_u32 m0, s40, 0x3000
	v_exp_f32_e32 v98, v98
	v_exp_f32_e32 v99, v99
	global_load_lds_dwordx4 v[24:25], off
	v_lshl_add_u64 v[24:25], v[24:25], 0, s[30:31]
	v_exp_f32_e32 v100, v100
	v_add_f32_e32 v27, v27, v98
	v_exp_f32_e32 v101, v101
	v_mfma_f32_32x32x16_bf16 v[158:173], v[182:185], v[134:137], v[158:173]
	v_add_f32_e32 v27, v27, v99
	v_exp_f32_e32 v102, v102
	v_add_f32_e32 v27, v27, v100
	v_exp_f32_e32 v103, v103
	v_add_f32_e32 v27, v27, v101
	v_mfma_f32_32x32x16_bf16 v[142:157], v[178:181], v[138:141], v[142:157]
	v_exp_f32_e32 v104, v104
	v_add_f32_e32 v27, v27, v102
	v_exp_f32_e32 v105, v105
	v_add_f32_e32 v27, v27, v103
	v_add_f32_e32 v27, v27, v104
	v_mfma_f32_32x32x16_bf16 v[158:173], v[174:177], v[138:141], v[158:173]
	v_add_f32_e32 v27, v27, v105
	v_cvt_pk_bf16_f32 v98, v98, v99
	v_cvt_pk_bf16_f32 v99, v100, v101
	v_cvt_pk_bf16_f32 v100, v102, v103
	v_cvt_pk_bf16_f32 v101, v104, v105
	s_waitcnt lgkmcnt(0)
	v_add_u32_e32 v2, 0x6000, v238
	v_mfma_f32_32x32x16_bf16 v[34:49], v[82:85], v[114:117], v[34:49]
	v_exp_f32_e32 v106, v106
	v_exp_f32_e32 v107, v107
	v_exp_f32_e32 v108, v108
	v_add_f32_e32 v27, v27, v106
	v_exp_f32_e32 v109, v109
	v_add_f32_e32 v27, v27, v107
	v_exp_f32_e32 v110, v110
	v_add_f32_e32 v27, v27, v108
	v_exp_f32_e32 v111, v111
	v_add_f32_e32 v27, v27, v109
	ds_read_b128 v[218:221], v2
	ds_read_b128 v[214:217], v2 offset:512
	ds_read_b128 v[210:213], v2 offset:2048
	v_mfma_f32_32x32x16_bf16 v[50:65], v[82:85], v[240:243], v[50:65]
	v_exp_f32_e32 v112, v112
	v_add_f32_e32 v27, v27, v110
	v_exp_f32_e32 v113, v113
	v_add_f32_e32 v27, v27, v111
	v_add_f32_e32 v27, v27, v112
	v_add_f32_e32 v27, v27, v113
	v_cvt_pk_bf16_f32 v106, v106, v107
	v_cvt_pk_bf16_f32 v107, v108, v109
	v_cvt_pk_bf16_f32 v108, v110, v111
	v_cvt_pk_bf16_f32 v109, v112, v113
	v_add_f32_e32 v236, v236, v27
	ds_read_b128 v[206:209], v2 offset:2560
	ds_read_b128 v[202:205], v2 offset:4096
	ds_read_b128 v[198:201], v2 offset:4608
	v_mfma_f32_32x32x16_bf16 v[34:49], v[90:93], v[118:121], v[34:49]
	ds_read_b128 v[194:197], v2 offset:6144
	ds_read_b128 v[190:193], v2 offset:6656
	ds_read_b128 v[186:189], v2 offset:8192
	v_max3_f32 v19, v142, v143, v144
	v_max3_f32 v26, v145, v146, v147
	v_max3_f32 v19, v19, v148, v149
	v_max3_f32 v26, v26, v150, v151
	v_max3_f32 v19, v19, v152, v153
	v_mfma_f32_32x32x16_bf16 v[50:65], v[90:93], v[244:247], v[50:65]
	ds_read_b128 v[182:185], v2 offset:8704
	ds_read_b128 v[178:181], v2 offset:10240
	ds_read_b128 v[174:177], v2 offset:10752
	v_max3_f32 v26, v26, v154, v155
	v_max3_f32 v19, v19, v156, v157
	v_max3_f32 v26, v26, v158, v159
	v_max3_f32 v19, v19, v160, v161
	v_max3_f32 v26, v26, v162, v163
	v_mfma_f32_32x32x16_bf16 v[34:49], v[98:101], v[122:125], v[34:49]
	v_max3_f32 v19, v19, v164, v165
	v_max3_f32 v26, v26, v166, v167
	v_max3_f32 v19, v19, v168, v169
	v_max3_f32 v26, v26, v170, v171
	v_mfma_f32_32x32x16_bf16 v[50:65], v[98:101], v[248:251], v[50:65]
	v_max3_f32 v19, v19, v172, v173
	v_max_f32_e32 v19, v19, v26
	v_mfma_f32_32x32x16_bf16 v[34:49], v[106:109], v[126:129], v[34:49]
	v_mfma_f32_32x32x16_bf16 v[50:65], v[106:109], v[20:23], v[50:65]
	v_cmp_lt_f32_e32 vcc, s41, v19
	s_cbranch_vccz .Lmy_nors_31
	s_nop 15
	s_nop 15
	v_mov_b32_e32 v26, v19
	s_nop 1
	v_permlane32_swap_b32_e32 v19, v26
	v_max_f32_e32 v19, v19, v26
	v_max_f32_e32 v19, v19, v19
	v_max_f32_e32 v90, 0, v19
	v_exp_f32_e64 v91, -v90
	v_add_f32_e32 v239, v239, v90
	v_xor_b32_e32 v66, 0x80000000, v239
	v_mov_b32_e32 v67, v66
	v_mov_b32_e32 v68, v66
	v_mov_b32_e32 v69, v66
	v_mov_b32_e32 v70, v66
	v_mov_b32_e32 v71, v66
	v_mov_b32_e32 v72, v66
	v_mov_b32_e32 v73, v66
	v_mov_b32_e32 v74, v66
	v_mov_b32_e32 v75, v66
	v_mov_b32_e32 v76, v66
	v_mov_b32_e32 v77, v66
	v_mov_b32_e32 v78, v66
	v_mov_b32_e32 v79, v66
	v_mov_b32_e32 v80, v66
	v_mov_b32_e32 v81, v66
	v_sub_f32_e32 v142, v142, v90
	v_sub_f32_e32 v143, v143, v90
	v_sub_f32_e32 v144, v144, v90
	v_sub_f32_e32 v145, v145, v90
	v_sub_f32_e32 v146, v146, v90
	v_sub_f32_e32 v147, v147, v90
	v_sub_f32_e32 v148, v148, v90
	v_sub_f32_e32 v149, v149, v90
	v_sub_f32_e32 v150, v150, v90
	v_sub_f32_e32 v151, v151, v90
	v_sub_f32_e32 v152, v152, v90
	v_sub_f32_e32 v153, v153, v90
	v_sub_f32_e32 v154, v154, v90
	v_sub_f32_e32 v155, v155, v90
	v_sub_f32_e32 v156, v156, v90
	v_sub_f32_e32 v157, v157, v90
	v_sub_f32_e32 v158, v158, v90
	v_sub_f32_e32 v159, v159, v90
	v_sub_f32_e32 v160, v160, v90
	v_sub_f32_e32 v161, v161, v90
	v_sub_f32_e32 v162, v162, v90
	v_sub_f32_e32 v163, v163, v90
	v_sub_f32_e32 v164, v164, v90
	v_sub_f32_e32 v165, v165, v90
	v_sub_f32_e32 v166, v166, v90
	v_sub_f32_e32 v167, v167, v90
	v_sub_f32_e32 v168, v168, v90
	v_sub_f32_e32 v169, v169, v90
	v_sub_f32_e32 v170, v170, v90
	v_sub_f32_e32 v171, v171, v90
	v_sub_f32_e32 v172, v172, v90
	v_sub_f32_e32 v173, v173, v90
	v_mul_f32_e32 v236, v236, v91
	s_mov_b64 s[96:97], exec
	s_and_b64 exec, exec, s[8:9]
	ds_write_b32 v235, v91
	s_mov_b64 exec, s[96:97]
	v_lshl_add_u32 v2, v228, 4, s47
	ds_read_b128 v[94:97], v2 offset:0
	s_waitcnt lgkmcnt(0)
	v_mul_f32_e32 v34, v34, v94
	v_mul_f32_e32 v50, v50, v94
	v_mul_f32_e32 v35, v35, v95
	v_mul_f32_e32 v51, v51, v95
	v_mul_f32_e32 v36, v36, v96
	v_mul_f32_e32 v52, v52, v96
	v_mul_f32_e32 v37, v37, v97
	v_mul_f32_e32 v53, v53, v97
	ds_read_b128 v[94:97], v2 offset:32
	s_waitcnt lgkmcnt(0)
	v_mul_f32_e32 v38, v38, v94
	v_mul_f32_e32 v54, v54, v94
	v_mul_f32_e32 v39, v39, v95
	v_mul_f32_e32 v55, v55, v95
	v_mul_f32_e32 v40, v40, v96
	v_mul_f32_e32 v56, v56, v96
	v_mul_f32_e32 v41, v41, v97
	v_mul_f32_e32 v57, v57, v97
	ds_read_b128 v[94:97], v2 offset:64
	s_waitcnt lgkmcnt(0)
	v_mul_f32_e32 v42, v42, v94
	v_mul_f32_e32 v58, v58, v94
	v_mul_f32_e32 v43, v43, v95
	v_mul_f32_e32 v59, v59, v95
	v_mul_f32_e32 v44, v44, v96
	v_mul_f32_e32 v60, v60, v96
	v_mul_f32_e32 v45, v45, v97
	v_mul_f32_e32 v61, v61, v97
	ds_read_b128 v[94:97], v2 offset:96
	s_waitcnt lgkmcnt(0)
	v_mul_f32_e32 v46, v46, v94
	v_mul_f32_e32 v62, v62, v94
	v_mul_f32_e32 v47, v47, v95
	v_mul_f32_e32 v63, v63, v95
	v_mul_f32_e32 v48, v48, v96
	v_mul_f32_e32 v64, v64, v96
	v_mul_f32_e32 v49, v49, v97
	v_mul_f32_e32 v65, v65, v97
.Lmy_nors_31:
	s_waitcnt lgkmcnt(0)
	v_add_u32_e32 v2, 0x2000, v237
	v_mfma_f32_32x32x16_bf16 v[82:97], v[218:221], v[4:7], v[66:81]
	v_exp_f32_e32 v142, v142
	v_exp_f32_e32 v143, v143
	v_exp_f32_e32 v144, v144
	v_add_f32_e32 v27, v142, v143
	v_exp_f32_e32 v145, v145
	ds_read_b64_tr_b16 v[114:115], v2 offset:49152
	ds_read_b64_tr_b16 v[116:117], v2 offset:49664
	ds_read_b64_tr_b16 v[118:119], v2 offset:50176
	ds_read_b64_tr_b16 v[120:121], v2 offset:50688
	v_mfma_f32_32x32x16_bf16 v[98:113], v[214:217], v[4:7], v[66:81]
	v_exp_f32_e32 v146, v146
	v_add_f32_e32 v27, v27, v144
	v_exp_f32_e32 v147, v147
	v_add_f32_e32 v27, v27, v145
	v_exp_f32_e32 v148, v148
	ds_read_b64_tr_b16 v[122:123], v2 offset:51200
	ds_read_b64_tr_b16 v[124:125], v2 offset:51712
	ds_read_b64_tr_b16 v[126:127], v2 offset:52224
	ds_read_b64_tr_b16 v[128:129], v2 offset:52736
	v_mfma_f32_32x32x16_bf16 v[82:97], v[210:213], v[8:11], v[82:97]
	v_add_f32_e32 v27, v27, v146
	v_exp_f32_e32 v149, v149
	v_add_f32_e32 v27, v27, v147
	v_add_f32_e32 v27, v27, v148
	v_add_f32_e32 v27, v27, v149
	ds_read_b64_tr_b16 v[240:241], v2 offset:53248
	ds_read_b64_tr_b16 v[242:243], v2 offset:53760
	ds_read_b64_tr_b16 v[244:245], v2 offset:54272
	ds_read_b64_tr_b16 v[246:247], v2 offset:54784
	v_mfma_f32_32x32x16_bf16 v[98:113], v[206:209], v[8:11], v[98:113]
	v_cvt_pk_bf16_f32 v142, v142, v143
	v_cvt_pk_bf16_f32 v143, v144, v145
	v_cvt_pk_bf16_f32 v144, v146, v147
	v_cvt_pk_bf16_f32 v145, v148, v149
	ds_read_b64_tr_b16 v[248:249], v2 offset:55296
	ds_read_b64_tr_b16 v[250:251], v2 offset:55808
	ds_read_b64_tr_b16 v[20:21], v2 offset:56320
	ds_read_b64_tr_b16 v[22:23], v2 offset:56832
	v_mfma_f32_32x32x16_bf16 v[82:97], v[202:205], v[12:15], v[82:97]
	v_exp_f32_e32 v150, v150
	v_exp_f32_e32 v151, v151
	v_exp_f32_e32 v152, v152
	v_add_f32_e32 v27, v27, v150
	v_exp_f32_e32 v153, v153
	v_mfma_f32_32x32x16_bf16 v[98:113], v[198:201], v[12:15], v[98:113]
	v_add_f32_e32 v27, v27, v151
	v_exp_f32_e32 v154, v154
	v_add_f32_e32 v27, v27, v152
	v_exp_f32_e32 v155, v155
	v_add_f32_e32 v27, v27, v153
	s_waitcnt vmcnt(4)
	s_barrier
	v_mfma_f32_32x32x16_bf16 v[82:97], v[194:197], v[130:133], v[82:97]
	s_add_u32 m0, s57, 0x0
	v_exp_f32_e32 v156, v156
	v_add_f32_e32 v27, v27, v154
	global_load_lds_dwordx4 v[28:29], off
	v_lshl_add_u64 v[28:29], v[28:29], 0, s[30:31]
	v_exp_f32_e32 v157, v157
	v_add_f32_e32 v27, v27, v155
	v_add_f32_e32 v27, v27, v156
	v_mfma_f32_32x32x16_bf16 v[98:113], v[190:193], v[130:133], v[98:113]
	s_add_u32 m0, s40, 0x6000
	v_add_f32_e32 v27, v27, v157
	v_cvt_pk_bf16_f32 v150, v150, v151
	global_load_lds_dwordx4 v[24:25], off
	v_lshl_add_u64 v[24:25], v[24:25], 0, s[30:31]
	v_cvt_pk_bf16_f32 v151, v152, v153
	v_cvt_pk_bf16_f32 v152, v154, v155
	v_cvt_pk_bf16_f32 v153, v156, v157
	v_mfma_f32_32x32x16_bf16 v[82:97], v[186:189], v[134:137], v[82:97]
	v_exp_f32_e32 v158, v158
	v_exp_f32_e32 v159, v159
	v_exp_f32_e32 v160, v160
	v_add_f32_e32 v27, v27, v158
	v_exp_f32_e32 v161, v161
	v_mfma_f32_32x32x16_bf16 v[98:113], v[182:185], v[134:137], v[98:113]
	v_add_f32_e32 v27, v27, v159
	v_exp_f32_e32 v162, v162
	v_add_f32_e32 v27, v27, v160
	v_exp_f32_e32 v163, v163
	v_add_f32_e32 v27, v27, v161
	v_mfma_f32_32x32x16_bf16 v[82:97], v[178:181], v[138:141], v[82:97]
	v_exp_f32_e32 v164, v164
	v_add_f32_e32 v27, v27, v162
	v_exp_f32_e32 v165, v165
	v_add_f32_e32 v27, v27, v163
	v_add_f32_e32 v27, v27, v164
	v_mfma_f32_32x32x16_bf16 v[98:113], v[174:177], v[138:141], v[98:113]
	v_add_f32_e32 v27, v27, v165
	v_cvt_pk_bf16_f32 v158, v158, v159
	v_cvt_pk_bf16_f32 v159, v160, v161
	v_cvt_pk_bf16_f32 v160, v162, v163
	v_cvt_pk_bf16_f32 v161, v164, v165
	s_waitcnt lgkmcnt(0)
	v_add_u32_e32 v2, 0x9000, v238
	v_mfma_f32_32x32x16_bf16 v[34:49], v[142:145], v[114:117], v[34:49]
	v_exp_f32_e32 v166, v166
	v_exp_f32_e32 v167, v167
	v_exp_f32_e32 v168, v168
	v_add_f32_e32 v27, v27, v166
	v_exp_f32_e32 v169, v169
	v_add_f32_e32 v27, v27, v167
	v_exp_f32_e32 v170, v170
	v_add_f32_e32 v27, v27, v168
	v_exp_f32_e32 v171, v171
	v_add_f32_e32 v27, v27, v169
	ds_read_b128 v[218:221], v2
	ds_read_b128 v[214:217], v2 offset:512
	ds_read_b128 v[210:213], v2 offset:2048
	v_mfma_f32_32x32x16_bf16 v[50:65], v[142:145], v[240:243], v[50:65]
	v_exp_f32_e32 v172, v172
	v_add_f32_e32 v27, v27, v170
	v_exp_f32_e32 v173, v173
	v_add_f32_e32 v27, v27, v171
	v_add_f32_e32 v27, v27, v172
	v_add_f32_e32 v27, v27, v173
	v_cvt_pk_bf16_f32 v166, v166, v167
	v_cvt_pk_bf16_f32 v167, v168, v169
	v_cvt_pk_bf16_f32 v168, v170, v171
	v_cvt_pk_bf16_f32 v169, v172, v173
	v_add_f32_e32 v236, v236, v27
	ds_read_b128 v[206:209], v2 offset:2560
	ds_read_b128 v[202:205], v2 offset:4096
	ds_read_b128 v[198:201], v2 offset:4608
	v_mfma_f32_32x32x16_bf16 v[34:49], v[150:153], v[118:121], v[34:49]
	ds_read_b128 v[194:197], v2 offset:6144
	ds_read_b128 v[190:193], v2 offset:6656
	ds_read_b128 v[186:189], v2 offset:8192
	v_max3_f32 v19, v82, v83, v84
	v_max3_f32 v26, v85, v86, v87
	v_max3_f32 v19, v19, v88, v89
	v_max3_f32 v26, v26, v90, v91
	v_max3_f32 v19, v19, v92, v93
	v_mfma_f32_32x32x16_bf16 v[50:65], v[150:153], v[244:247], v[50:65]
	ds_read_b128 v[182:185], v2 offset:8704
	ds_read_b128 v[178:181], v2 offset:10240
	ds_read_b128 v[174:177], v2 offset:10752
	v_max3_f32 v26, v26, v94, v95
	v_max3_f32 v19, v19, v96, v97
	v_max3_f32 v26, v26, v98, v99
	v_max3_f32 v19, v19, v100, v101
	v_max3_f32 v26, v26, v102, v103
	v_mfma_f32_32x32x16_bf16 v[34:49], v[158:161], v[122:125], v[34:49]
	v_max3_f32 v19, v19, v104, v105
	v_max3_f32 v26, v26, v106, v107
	v_max3_f32 v19, v19, v108, v109
	v_max3_f32 v26, v26, v110, v111
	v_mfma_f32_32x32x16_bf16 v[50:65], v[158:161], v[248:251], v[50:65]
	v_max3_f32 v19, v19, v112, v113
	v_max_f32_e32 v19, v19, v26
	v_mfma_f32_32x32x16_bf16 v[34:49], v[166:169], v[126:129], v[34:49]
	v_mfma_f32_32x32x16_bf16 v[50:65], v[166:169], v[20:23], v[50:65]
	v_cmp_lt_f32_e32 vcc, s41, v19
	s_cbranch_vccz .Lmy_nors_32
	s_nop 15
	s_nop 15
	v_mov_b32_e32 v26, v19
	s_nop 1
	v_permlane32_swap_b32_e32 v19, v26
	v_max_f32_e32 v19, v19, v26
	v_max_f32_e32 v19, v19, v19
	v_max_f32_e32 v150, 0, v19
	v_exp_f32_e64 v151, -v150
	v_add_f32_e32 v239, v239, v150
	v_xor_b32_e32 v66, 0x80000000, v239
	v_mov_b32_e32 v67, v66
	v_mov_b32_e32 v68, v66
	v_mov_b32_e32 v69, v66
	v_mov_b32_e32 v70, v66
	v_mov_b32_e32 v71, v66
	v_mov_b32_e32 v72, v66
	v_mov_b32_e32 v73, v66
	v_mov_b32_e32 v74, v66
	v_mov_b32_e32 v75, v66
	v_mov_b32_e32 v76, v66
	v_mov_b32_e32 v77, v66
	v_mov_b32_e32 v78, v66
	v_mov_b32_e32 v79, v66
	v_mov_b32_e32 v80, v66
	v_mov_b32_e32 v81, v66
	v_sub_f32_e32 v82, v82, v150
	v_sub_f32_e32 v83, v83, v150
	v_sub_f32_e32 v84, v84, v150
	v_sub_f32_e32 v85, v85, v150
	v_sub_f32_e32 v86, v86, v150
	v_sub_f32_e32 v87, v87, v150
	v_sub_f32_e32 v88, v88, v150
	v_sub_f32_e32 v89, v89, v150
	v_sub_f32_e32 v90, v90, v150
	v_sub_f32_e32 v91, v91, v150
	v_sub_f32_e32 v92, v92, v150
	v_sub_f32_e32 v93, v93, v150
	v_sub_f32_e32 v94, v94, v150
	v_sub_f32_e32 v95, v95, v150
	v_sub_f32_e32 v96, v96, v150
	v_sub_f32_e32 v97, v97, v150
	v_sub_f32_e32 v98, v98, v150
	v_sub_f32_e32 v99, v99, v150
	v_sub_f32_e32 v100, v100, v150
	v_sub_f32_e32 v101, v101, v150
	v_sub_f32_e32 v102, v102, v150
	v_sub_f32_e32 v103, v103, v150
	v_sub_f32_e32 v104, v104, v150
	v_sub_f32_e32 v105, v105, v150
	v_sub_f32_e32 v106, v106, v150
	v_sub_f32_e32 v107, v107, v150
	v_sub_f32_e32 v108, v108, v150
	v_sub_f32_e32 v109, v109, v150
	v_sub_f32_e32 v110, v110, v150
	v_sub_f32_e32 v111, v111, v150
	v_sub_f32_e32 v112, v112, v150
	v_sub_f32_e32 v113, v113, v150
	v_mul_f32_e32 v236, v236, v151
	s_mov_b64 s[96:97], exec
	s_and_b64 exec, exec, s[8:9]
	ds_write_b32 v235, v151
	s_mov_b64 exec, s[96:97]
	v_lshl_add_u32 v2, v228, 4, s47
	ds_read_b128 v[154:157], v2 offset:0
	s_waitcnt lgkmcnt(0)
	v_mul_f32_e32 v34, v34, v154
	v_mul_f32_e32 v50, v50, v154
	v_mul_f32_e32 v35, v35, v155
	v_mul_f32_e32 v51, v51, v155
	v_mul_f32_e32 v36, v36, v156
	v_mul_f32_e32 v52, v52, v156
	v_mul_f32_e32 v37, v37, v157
	v_mul_f32_e32 v53, v53, v157
	ds_read_b128 v[154:157], v2 offset:32
	s_waitcnt lgkmcnt(0)
	v_mul_f32_e32 v38, v38, v154
	v_mul_f32_e32 v54, v54, v154
	v_mul_f32_e32 v39, v39, v155
	v_mul_f32_e32 v55, v55, v155
	v_mul_f32_e32 v40, v40, v156
	v_mul_f32_e32 v56, v56, v156
	v_mul_f32_e32 v41, v41, v157
	v_mul_f32_e32 v57, v57, v157
	ds_read_b128 v[154:157], v2 offset:64
	s_waitcnt lgkmcnt(0)
	v_mul_f32_e32 v42, v42, v154
	v_mul_f32_e32 v58, v58, v154
	v_mul_f32_e32 v43, v43, v155
	v_mul_f32_e32 v59, v59, v155
	v_mul_f32_e32 v44, v44, v156
	v_mul_f32_e32 v60, v60, v156
	v_mul_f32_e32 v45, v45, v157
	v_mul_f32_e32 v61, v61, v157
	ds_read_b128 v[154:157], v2 offset:96
	s_waitcnt lgkmcnt(0)
	v_mul_f32_e32 v46, v46, v154
	v_mul_f32_e32 v62, v62, v154
	v_mul_f32_e32 v47, v47, v155
	v_mul_f32_e32 v63, v63, v155
	v_mul_f32_e32 v48, v48, v156
	v_mul_f32_e32 v64, v64, v156
	v_mul_f32_e32 v49, v49, v157
	v_mul_f32_e32 v65, v65, v157
.Lmy_nors_32:
	s_waitcnt lgkmcnt(0)
	v_add_u32_e32 v2, 0x4000, v237
	v_mfma_f32_32x32x16_bf16 v[142:157], v[218:221], v[4:7], v[66:81]
	v_exp_f32_e32 v82, v82
	v_exp_f32_e32 v83, v83
	v_exp_f32_e32 v84, v84
	v_add_f32_e32 v27, v82, v83
	v_exp_f32_e32 v85, v85
	ds_read_b64_tr_b16 v[114:115], v2 offset:49152
	ds_read_b64_tr_b16 v[116:117], v2 offset:49664
	ds_read_b64_tr_b16 v[118:119], v2 offset:50176
	ds_read_b64_tr_b16 v[120:121], v2 offset:50688
	v_mfma_f32_32x32x16_bf16 v[158:173], v[214:217], v[4:7], v[66:81]
	v_exp_f32_e32 v86, v86
	v_add_f32_e32 v27, v27, v84
	v_exp_f32_e32 v87, v87
	v_add_f32_e32 v27, v27, v85
	v_exp_f32_e32 v88, v88
	ds_read_b64_tr_b16 v[122:123], v2 offset:51200
	ds_read_b64_tr_b16 v[124:125], v2 offset:51712
	ds_read_b64_tr_b16 v[126:127], v2 offset:52224
	ds_read_b64_tr_b16 v[128:129], v2 offset:52736
	v_mfma_f32_32x32x16_bf16 v[142:157], v[210:213], v[8:11], v[142:157]
	v_add_f32_e32 v27, v27, v86
	v_exp_f32_e32 v89, v89
	v_add_f32_e32 v27, v27, v87
	v_add_f32_e32 v27, v27, v88
	v_add_f32_e32 v27, v27, v89
	ds_read_b64_tr_b16 v[240:241], v2 offset:53248
	ds_read_b64_tr_b16 v[242:243], v2 offset:53760
	ds_read_b64_tr_b16 v[244:245], v2 offset:54272
	ds_read_b64_tr_b16 v[246:247], v2 offset:54784
	v_mfma_f32_32x32x16_bf16 v[158:173], v[206:209], v[8:11], v[158:173]
	v_cvt_pk_bf16_f32 v82, v82, v83
	v_cvt_pk_bf16_f32 v83, v84, v85
	v_cvt_pk_bf16_f32 v84, v86, v87
	v_cvt_pk_bf16_f32 v85, v88, v89
	ds_read_b64_tr_b16 v[248:249], v2 offset:55296
	ds_read_b64_tr_b16 v[250:251], v2 offset:55808
	ds_read_b64_tr_b16 v[20:21], v2 offset:56320
	ds_read_b64_tr_b16 v[22:23], v2 offset:56832
	v_mfma_f32_32x32x16_bf16 v[142:157], v[202:205], v[12:15], v[142:157]
	v_exp_f32_e32 v90, v90
	v_exp_f32_e32 v91, v91
	v_exp_f32_e32 v92, v92
	v_add_f32_e32 v27, v27, v90
	v_exp_f32_e32 v93, v93
	v_mfma_f32_32x32x16_bf16 v[158:173], v[198:201], v[12:15], v[158:173]
	v_add_f32_e32 v27, v27, v91
	v_exp_f32_e32 v94, v94
	v_add_f32_e32 v27, v27, v92
	v_exp_f32_e32 v95, v95
	v_add_f32_e32 v27, v27, v93
	s_waitcnt vmcnt(3)
	s_barrier
	v_mfma_f32_32x32x16_bf16 v[142:157], v[194:197], v[130:133], v[142:157]
	s_add_u32 m0, s57, 0x2000
	v_exp_f32_e32 v96, v96
	v_add_f32_e32 v27, v27, v94
	global_load_lds_dwordx4 v[28:29], off
	v_lshl_add_u64 v[28:29], v[28:29], 0, s[30:31]
	v_exp_f32_e32 v97, v97
	v_add_f32_e32 v27, v27, v95
	v_add_f32_e32 v27, v27, v96
	v_mfma_f32_32x32x16_bf16 v[158:173], v[190:193], v[130:133], v[158:173]
	s_add_u32 m0, s40, 0x9000
	v_add_f32_e32 v27, v27, v97
	v_cvt_pk_bf16_f32 v90, v90, v91
	global_load_lds_dwordx4 v[24:25], off
	v_lshl_add_u64 v[24:25], v[24:25], 0, s[30:31]
	v_cvt_pk_bf16_f32 v91, v92, v93
	v_cvt_pk_bf16_f32 v92, v94, v95
	v_cvt_pk_bf16_f32 v93, v96, v97
	v_mfma_f32_32x32x16_bf16 v[142:157], v[186:189], v[134:137], v[142:157]
	v_exp_f32_e32 v98, v98
	v_exp_f32_e32 v99, v99
	v_exp_f32_e32 v100, v100
	v_add_f32_e32 v27, v27, v98
	v_exp_f32_e32 v101, v101
	v_mfma_f32_32x32x16_bf16 v[158:173], v[182:185], v[134:137], v[158:173]
	v_add_f32_e32 v27, v27, v99
	v_exp_f32_e32 v102, v102
	v_add_f32_e32 v27, v27, v100
	v_exp_f32_e32 v103, v103
	v_add_f32_e32 v27, v27, v101
	v_mfma_f32_32x32x16_bf16 v[142:157], v[178:181], v[138:141], v[142:157]
	v_exp_f32_e32 v104, v104
	v_add_f32_e32 v27, v27, v102
	v_exp_f32_e32 v105, v105
	v_add_f32_e32 v27, v27, v103
	v_add_f32_e32 v27, v27, v104
	v_mfma_f32_32x32x16_bf16 v[158:173], v[174:177], v[138:141], v[158:173]
	v_add_f32_e32 v27, v27, v105
	v_cvt_pk_bf16_f32 v98, v98, v99
	v_cvt_pk_bf16_f32 v99, v100, v101
	v_cvt_pk_bf16_f32 v100, v102, v103
	v_cvt_pk_bf16_f32 v101, v104, v105
	s_waitcnt lgkmcnt(0)
	v_mov_b32_e32 v2, v238
	v_mfma_f32_32x32x16_bf16 v[34:49], v[82:85], v[114:117], v[34:49]
	v_exp_f32_e32 v106, v106
	v_exp_f32_e32 v107, v107
	v_exp_f32_e32 v108, v108
	v_add_f32_e32 v27, v27, v106
	v_exp_f32_e32 v109, v109
	v_add_f32_e32 v27, v27, v107
	v_exp_f32_e32 v110, v110
	v_add_f32_e32 v27, v27, v108
	v_exp_f32_e32 v111, v111
	v_add_f32_e32 v27, v27, v109
	ds_read_b128 v[218:221], v2
	ds_read_b128 v[214:217], v2 offset:512
	ds_read_b128 v[210:213], v2 offset:2048
	v_mfma_f32_32x32x16_bf16 v[50:65], v[82:85], v[240:243], v[50:65]
	v_exp_f32_e32 v112, v112
	v_add_f32_e32 v27, v27, v110
	v_exp_f32_e32 v113, v113
	v_add_f32_e32 v27, v27, v111
	v_add_f32_e32 v27, v27, v112
	v_add_f32_e32 v27, v27, v113
	v_cvt_pk_bf16_f32 v106, v106, v107
	v_cvt_pk_bf16_f32 v107, v108, v109
	v_cvt_pk_bf16_f32 v108, v110, v111
	v_cvt_pk_bf16_f32 v109, v112, v113
	v_add_f32_e32 v236, v236, v27
	ds_read_b128 v[206:209], v2 offset:2560
	ds_read_b128 v[202:205], v2 offset:4096
	ds_read_b128 v[198:201], v2 offset:4608
	v_mfma_f32_32x32x16_bf16 v[34:49], v[90:93], v[118:121], v[34:49]
	ds_read_b128 v[194:197], v2 offset:6144
	ds_read_b128 v[190:193], v2 offset:6656
	ds_read_b128 v[186:189], v2 offset:8192
	v_max3_f32 v19, v142, v143, v144
	v_max3_f32 v26, v145, v146, v147
	v_max3_f32 v19, v19, v148, v149
	v_max3_f32 v26, v26, v150, v151
	v_max3_f32 v19, v19, v152, v153
	v_mfma_f32_32x32x16_bf16 v[50:65], v[90:93], v[244:247], v[50:65]
	ds_read_b128 v[182:185], v2 offset:8704
	ds_read_b128 v[178:181], v2 offset:10240
	ds_read_b128 v[174:177], v2 offset:10752
	v_max3_f32 v26, v26, v154, v155
	v_max3_f32 v19, v19, v156, v157
	v_max3_f32 v26, v26, v158, v159
	v_max3_f32 v19, v19, v160, v161
	v_max3_f32 v26, v26, v162, v163
	v_mfma_f32_32x32x16_bf16 v[34:49], v[98:101], v[122:125], v[34:49]
	v_max3_f32 v19, v19, v164, v165
	v_max3_f32 v26, v26, v166, v167
	v_max3_f32 v19, v19, v168, v169
	v_max3_f32 v26, v26, v170, v171
	v_mfma_f32_32x32x16_bf16 v[50:65], v[98:101], v[248:251], v[50:65]
	v_max3_f32 v19, v19, v172, v173
	v_max_f32_e32 v19, v19, v26
	v_mfma_f32_32x32x16_bf16 v[34:49], v[106:109], v[126:129], v[34:49]
	v_mfma_f32_32x32x16_bf16 v[50:65], v[106:109], v[20:23], v[50:65]
	v_cmp_lt_f32_e32 vcc, s41, v19
	s_cbranch_vccz .Lmy_nors_33
	s_nop 15
	s_nop 15
	v_mov_b32_e32 v26, v19
	s_nop 1
	v_permlane32_swap_b32_e32 v19, v26
	v_max_f32_e32 v19, v19, v26
	v_max_f32_e32 v19, v19, v19
	v_max_f32_e32 v90, 0, v19
	v_exp_f32_e64 v91, -v90
	v_add_f32_e32 v239, v239, v90
	v_xor_b32_e32 v66, 0x80000000, v239
	v_mov_b32_e32 v67, v66
	v_mov_b32_e32 v68, v66
	v_mov_b32_e32 v69, v66
	v_mov_b32_e32 v70, v66
	v_mov_b32_e32 v71, v66
	v_mov_b32_e32 v72, v66
	v_mov_b32_e32 v73, v66
	v_mov_b32_e32 v74, v66
	v_mov_b32_e32 v75, v66
	v_mov_b32_e32 v76, v66
	v_mov_b32_e32 v77, v66
	v_mov_b32_e32 v78, v66
	v_mov_b32_e32 v79, v66
	v_mov_b32_e32 v80, v66
	v_mov_b32_e32 v81, v66
	v_sub_f32_e32 v142, v142, v90
	v_sub_f32_e32 v143, v143, v90
	v_sub_f32_e32 v144, v144, v90
	v_sub_f32_e32 v145, v145, v90
	v_sub_f32_e32 v146, v146, v90
	v_sub_f32_e32 v147, v147, v90
	v_sub_f32_e32 v148, v148, v90
	v_sub_f32_e32 v149, v149, v90
	v_sub_f32_e32 v150, v150, v90
	v_sub_f32_e32 v151, v151, v90
	v_sub_f32_e32 v152, v152, v90
	v_sub_f32_e32 v153, v153, v90
	v_sub_f32_e32 v154, v154, v90
	v_sub_f32_e32 v155, v155, v90
	v_sub_f32_e32 v156, v156, v90
	v_sub_f32_e32 v157, v157, v90
	v_sub_f32_e32 v158, v158, v90
	v_sub_f32_e32 v159, v159, v90
	v_sub_f32_e32 v160, v160, v90
	v_sub_f32_e32 v161, v161, v90
	v_sub_f32_e32 v162, v162, v90
	v_sub_f32_e32 v163, v163, v90
	v_sub_f32_e32 v164, v164, v90
	v_sub_f32_e32 v165, v165, v90
	v_sub_f32_e32 v166, v166, v90
	v_sub_f32_e32 v167, v167, v90
	v_sub_f32_e32 v168, v168, v90
	v_sub_f32_e32 v169, v169, v90
	v_sub_f32_e32 v170, v170, v90
	v_sub_f32_e32 v171, v171, v90
	v_sub_f32_e32 v172, v172, v90
	v_sub_f32_e32 v173, v173, v90
	v_mul_f32_e32 v236, v236, v91
	s_mov_b64 s[96:97], exec
	s_and_b64 exec, exec, s[8:9]
	ds_write_b32 v235, v91
	s_mov_b64 exec, s[96:97]
	v_lshl_add_u32 v2, v228, 4, s47
	ds_read_b128 v[94:97], v2 offset:0
	s_waitcnt lgkmcnt(0)
	v_mul_f32_e32 v34, v34, v94
	v_mul_f32_e32 v50, v50, v94
	v_mul_f32_e32 v35, v35, v95
	v_mul_f32_e32 v51, v51, v95
	v_mul_f32_e32 v36, v36, v96
	v_mul_f32_e32 v52, v52, v96
	v_mul_f32_e32 v37, v37, v97
	v_mul_f32_e32 v53, v53, v97
	ds_read_b128 v[94:97], v2 offset:32
	s_waitcnt lgkmcnt(0)
	v_mul_f32_e32 v38, v38, v94
	v_mul_f32_e32 v54, v54, v94
	v_mul_f32_e32 v39, v39, v95
	v_mul_f32_e32 v55, v55, v95
	v_mul_f32_e32 v40, v40, v96
	v_mul_f32_e32 v56, v56, v96
	v_mul_f32_e32 v41, v41, v97
	v_mul_f32_e32 v57, v57, v97
	ds_read_b128 v[94:97], v2 offset:64
	s_waitcnt lgkmcnt(0)
	v_mul_f32_e32 v42, v42, v94
	v_mul_f32_e32 v58, v58, v94
	v_mul_f32_e32 v43, v43, v95
	v_mul_f32_e32 v59, v59, v95
	v_mul_f32_e32 v44, v44, v96
	v_mul_f32_e32 v60, v60, v96
	v_mul_f32_e32 v45, v45, v97
	v_mul_f32_e32 v61, v61, v97
	ds_read_b128 v[94:97], v2 offset:96
	s_waitcnt lgkmcnt(0)
	v_mul_f32_e32 v46, v46, v94
	v_mul_f32_e32 v62, v62, v94
	v_mul_f32_e32 v47, v47, v95
	v_mul_f32_e32 v63, v63, v95
	v_mul_f32_e32 v48, v48, v96
	v_mul_f32_e32 v64, v64, v96
	v_mul_f32_e32 v49, v49, v97
	v_mul_f32_e32 v65, v65, v97
.Lmy_nors_33:
	s_waitcnt lgkmcnt(0)
	v_add_u32_e32 v2, 0x6000, v237
	v_mfma_f32_32x32x16_bf16 v[82:97], v[218:221], v[4:7], v[66:81]
	v_exp_f32_e32 v142, v142
	v_exp_f32_e32 v143, v143
	v_exp_f32_e32 v144, v144
	v_add_f32_e32 v27, v142, v143
	v_exp_f32_e32 v145, v145
	ds_read_b64_tr_b16 v[114:115], v2 offset:49152
	ds_read_b64_tr_b16 v[116:117], v2 offset:49664
	ds_read_b64_tr_b16 v[118:119], v2 offset:50176
	ds_read_b64_tr_b16 v[120:121], v2 offset:50688
	v_mfma_f32_32x32x16_bf16 v[98:113], v[214:217], v[4:7], v[66:81]
	v_exp_f32_e32 v146, v146
	v_add_f32_e32 v27, v27, v144
	v_exp_f32_e32 v147, v147
	v_add_f32_e32 v27, v27, v145
	v_exp_f32_e32 v148, v148
	ds_read_b64_tr_b16 v[122:123], v2 offset:51200
	ds_read_b64_tr_b16 v[124:125], v2 offset:51712
	ds_read_b64_tr_b16 v[126:127], v2 offset:52224
	ds_read_b64_tr_b16 v[128:129], v2 offset:52736
	v_mfma_f32_32x32x16_bf16 v[82:97], v[210:213], v[8:11], v[82:97]
	v_add_f32_e32 v27, v27, v146
	v_exp_f32_e32 v149, v149
	v_add_f32_e32 v27, v27, v147
	v_add_f32_e32 v27, v27, v148
	v_add_f32_e32 v27, v27, v149
	ds_read_b64_tr_b16 v[240:241], v2 offset:53248
	ds_read_b64_tr_b16 v[242:243], v2 offset:53760
	ds_read_b64_tr_b16 v[244:245], v2 offset:54272
	ds_read_b64_tr_b16 v[246:247], v2 offset:54784
	v_mfma_f32_32x32x16_bf16 v[98:113], v[206:209], v[8:11], v[98:113]
	v_cvt_pk_bf16_f32 v142, v142, v143
	v_cvt_pk_bf16_f32 v143, v144, v145
	v_cvt_pk_bf16_f32 v144, v146, v147
	v_cvt_pk_bf16_f32 v145, v148, v149
	ds_read_b64_tr_b16 v[248:249], v2 offset:55296
	ds_read_b64_tr_b16 v[250:251], v2 offset:55808
	ds_read_b64_tr_b16 v[20:21], v2 offset:56320
	ds_read_b64_tr_b16 v[22:23], v2 offset:56832
	v_mfma_f32_32x32x16_bf16 v[82:97], v[202:205], v[12:15], v[82:97]
	v_exp_f32_e32 v150, v150
	v_exp_f32_e32 v151, v151
	v_exp_f32_e32 v152, v152
	v_add_f32_e32 v27, v27, v150
	v_exp_f32_e32 v153, v153
	v_mfma_f32_32x32x16_bf16 v[98:113], v[198:201], v[12:15], v[98:113]
	v_add_f32_e32 v27, v27, v151
	v_exp_f32_e32 v154, v154
	v_add_f32_e32 v27, v27, v152
	v_exp_f32_e32 v155, v155
	v_add_f32_e32 v27, v27, v153
	s_waitcnt vmcnt(4)
	s_barrier
	v_mfma_f32_32x32x16_bf16 v[82:97], v[194:197], v[130:133], v[82:97]
	s_add_u32 m0, s57, 0x4000
	v_exp_f32_e32 v156, v156
	v_add_f32_e32 v27, v27, v154
	global_load_lds_dwordx4 v[28:29], off
	v_lshl_add_u64 v[28:29], v[28:29], 0, s[30:31]
	v_exp_f32_e32 v157, v157
	v_add_f32_e32 v27, v27, v155
	v_add_f32_e32 v27, v27, v156
	v_mfma_f32_32x32x16_bf16 v[98:113], v[190:193], v[130:133], v[98:113]
	s_cmp_eq_u32 s79, 1
	s_cbranch_scc1 .Lmy_gl_34
	s_add_u32 m0, s40, 0x0
	s_nop 0
	global_load_lds_dwordx4 v[24:25], off
	v_lshl_add_u64 v[24:25], v[24:25], 0, s[30:31]
.Lmy_gl_34:
	v_add_f32_e32 v27, v27, v157
	v_cvt_pk_bf16_f32 v150, v150, v151
	v_cvt_pk_bf16_f32 v151, v152, v153
	v_cvt_pk_bf16_f32 v152, v154, v155
	v_cvt_pk_bf16_f32 v153, v156, v157
	v_mfma_f32_32x32x16_bf16 v[82:97], v[186:189], v[134:137], v[82:97]
	v_exp_f32_e32 v158, v158
	v_exp_f32_e32 v159, v159
	v_exp_f32_e32 v160, v160
	v_add_f32_e32 v27, v27, v158
	v_exp_f32_e32 v161, v161
	v_mfma_f32_32x32x16_bf16 v[98:113], v[182:185], v[134:137], v[98:113]
	v_add_f32_e32 v27, v27, v159
	v_exp_f32_e32 v162, v162
	v_add_f32_e32 v27, v27, v160
	v_exp_f32_e32 v163, v163
	v_add_f32_e32 v27, v27, v161
	v_mfma_f32_32x32x16_bf16 v[82:97], v[178:181], v[138:141], v[82:97]
	v_exp_f32_e32 v164, v164
	v_add_f32_e32 v27, v27, v162
	v_exp_f32_e32 v165, v165
	v_add_f32_e32 v27, v27, v163
	v_add_f32_e32 v27, v27, v164
	v_mfma_f32_32x32x16_bf16 v[98:113], v[174:177], v[138:141], v[98:113]
	v_add_f32_e32 v27, v27, v165
	v_cvt_pk_bf16_f32 v158, v158, v159
	v_cvt_pk_bf16_f32 v159, v160, v161
	v_cvt_pk_bf16_f32 v160, v162, v163
	v_cvt_pk_bf16_f32 v161, v164, v165
	s_waitcnt lgkmcnt(0)
	v_add_u32_e32 v2, 0x3000, v238
	v_mfma_f32_32x32x16_bf16 v[34:49], v[142:145], v[114:117], v[34:49]
	v_exp_f32_e32 v166, v166
	v_exp_f32_e32 v167, v167
	v_exp_f32_e32 v168, v168
	v_add_f32_e32 v27, v27, v166
	v_exp_f32_e32 v169, v169
	v_add_f32_e32 v27, v27, v167
	v_exp_f32_e32 v170, v170
	v_add_f32_e32 v27, v27, v168
	v_exp_f32_e32 v171, v171
	v_add_f32_e32 v27, v27, v169
	ds_read_b128 v[218:221], v2
	ds_read_b128 v[214:217], v2 offset:512
	ds_read_b128 v[210:213], v2 offset:2048
	v_mfma_f32_32x32x16_bf16 v[50:65], v[142:145], v[240:243], v[50:65]
	v_exp_f32_e32 v172, v172
	v_add_f32_e32 v27, v27, v170
	v_exp_f32_e32 v173, v173
	v_add_f32_e32 v27, v27, v171
	v_add_f32_e32 v27, v27, v172
	v_add_f32_e32 v27, v27, v173
	v_cvt_pk_bf16_f32 v166, v166, v167
	v_cvt_pk_bf16_f32 v167, v168, v169
	v_cvt_pk_bf16_f32 v168, v170, v171
	v_cvt_pk_bf16_f32 v169, v172, v173
	v_add_f32_e32 v236, v236, v27
	ds_read_b128 v[206:209], v2 offset:2560
	ds_read_b128 v[202:205], v2 offset:4096
	ds_read_b128 v[198:201], v2 offset:4608
	v_mfma_f32_32x32x16_bf16 v[34:49], v[150:153], v[118:121], v[34:49]
	ds_read_b128 v[194:197], v2 offset:6144
	ds_read_b128 v[190:193], v2 offset:6656
	ds_read_b128 v[186:189], v2 offset:8192
	v_max3_f32 v19, v82, v83, v84
	v_max3_f32 v26, v85, v86, v87
	v_max3_f32 v19, v19, v88, v89
	v_max3_f32 v26, v26, v90, v91
	v_max3_f32 v19, v19, v92, v93
	v_mfma_f32_32x32x16_bf16 v[50:65], v[150:153], v[244:247], v[50:65]
	ds_read_b128 v[182:185], v2 offset:8704
	ds_read_b128 v[178:181], v2 offset:10240
	ds_read_b128 v[174:177], v2 offset:10752
	v_max3_f32 v26, v26, v94, v95
	v_max3_f32 v19, v19, v96, v97
	v_max3_f32 v26, v26, v98, v99
	v_max3_f32 v19, v19, v100, v101
	v_max3_f32 v26, v26, v102, v103
	v_mfma_f32_32x32x16_bf16 v[34:49], v[158:161], v[122:125], v[34:49]
	v_max3_f32 v19, v19, v104, v105
	v_max3_f32 v26, v26, v106, v107
	v_max3_f32 v19, v19, v108, v109
	v_max3_f32 v26, v26, v110, v111
	v_mfma_f32_32x32x16_bf16 v[50:65], v[158:161], v[248:251], v[50:65]
	v_max3_f32 v19, v19, v112, v113
	v_max_f32_e32 v19, v19, v26
	v_mfma_f32_32x32x16_bf16 v[34:49], v[166:169], v[126:129], v[34:49]
	v_mfma_f32_32x32x16_bf16 v[50:65], v[166:169], v[20:23], v[50:65]
	v_cmp_lt_f32_e32 vcc, s41, v19
	s_cbranch_vccz .Lmy_nors_35
	s_nop 15
	s_nop 15
	v_mov_b32_e32 v26, v19
	s_nop 1
	v_permlane32_swap_b32_e32 v19, v26
	v_max_f32_e32 v19, v19, v26
	v_max_f32_e32 v19, v19, v19
	v_max_f32_e32 v150, 0, v19
	v_exp_f32_e64 v151, -v150
	v_add_f32_e32 v239, v239, v150
	v_xor_b32_e32 v66, 0x80000000, v239
	v_mov_b32_e32 v67, v66
	v_mov_b32_e32 v68, v66
	v_mov_b32_e32 v69, v66
	v_mov_b32_e32 v70, v66
	v_mov_b32_e32 v71, v66
	v_mov_b32_e32 v72, v66
	v_mov_b32_e32 v73, v66
	v_mov_b32_e32 v74, v66
	v_mov_b32_e32 v75, v66
	v_mov_b32_e32 v76, v66
	v_mov_b32_e32 v77, v66
	v_mov_b32_e32 v78, v66
	v_mov_b32_e32 v79, v66
	v_mov_b32_e32 v80, v66
	v_mov_b32_e32 v81, v66
	v_sub_f32_e32 v82, v82, v150
	v_sub_f32_e32 v83, v83, v150
	v_sub_f32_e32 v84, v84, v150
	v_sub_f32_e32 v85, v85, v150
	v_sub_f32_e32 v86, v86, v150
	v_sub_f32_e32 v87, v87, v150
	v_sub_f32_e32 v88, v88, v150
	v_sub_f32_e32 v89, v89, v150
	v_sub_f32_e32 v90, v90, v150
	v_sub_f32_e32 v91, v91, v150
	v_sub_f32_e32 v92, v92, v150
	v_sub_f32_e32 v93, v93, v150
	v_sub_f32_e32 v94, v94, v150
	v_sub_f32_e32 v95, v95, v150
	v_sub_f32_e32 v96, v96, v150
	v_sub_f32_e32 v97, v97, v150
	v_sub_f32_e32 v98, v98, v150
	v_sub_f32_e32 v99, v99, v150
	v_sub_f32_e32 v100, v100, v150
	v_sub_f32_e32 v101, v101, v150
	v_sub_f32_e32 v102, v102, v150
	v_sub_f32_e32 v103, v103, v150
	v_sub_f32_e32 v104, v104, v150
	v_sub_f32_e32 v105, v105, v150
	v_sub_f32_e32 v106, v106, v150
	v_sub_f32_e32 v107, v107, v150
	v_sub_f32_e32 v108, v108, v150
	v_sub_f32_e32 v109, v109, v150
	v_sub_f32_e32 v110, v110, v150
	v_sub_f32_e32 v111, v111, v150
	v_sub_f32_e32 v112, v112, v150
	v_sub_f32_e32 v113, v113, v150
	v_mul_f32_e32 v236, v236, v151
	s_mov_b64 s[96:97], exec
	s_and_b64 exec, exec, s[8:9]
	ds_write_b32 v235, v151
	s_mov_b64 exec, s[96:97]
	v_lshl_add_u32 v2, v228, 4, s47
	ds_read_b128 v[154:157], v2 offset:0
	s_waitcnt lgkmcnt(0)
	v_mul_f32_e32 v34, v34, v154
	v_mul_f32_e32 v50, v50, v154
	v_mul_f32_e32 v35, v35, v155
	v_mul_f32_e32 v51, v51, v155
	v_mul_f32_e32 v36, v36, v156
	v_mul_f32_e32 v52, v52, v156
	v_mul_f32_e32 v37, v37, v157
	v_mul_f32_e32 v53, v53, v157
	ds_read_b128 v[154:157], v2 offset:32
	s_waitcnt lgkmcnt(0)
	v_mul_f32_e32 v38, v38, v154
	v_mul_f32_e32 v54, v54, v154
	v_mul_f32_e32 v39, v39, v155
	v_mul_f32_e32 v55, v55, v155
	v_mul_f32_e32 v40, v40, v156
	v_mul_f32_e32 v56, v56, v156
	v_mul_f32_e32 v41, v41, v157
	v_mul_f32_e32 v57, v57, v157
	ds_read_b128 v[154:157], v2 offset:64
	s_waitcnt lgkmcnt(0)
	v_mul_f32_e32 v42, v42, v154
	v_mul_f32_e32 v58, v58, v154
	v_mul_f32_e32 v43, v43, v155
	v_mul_f32_e32 v59, v59, v155
	v_mul_f32_e32 v44, v44, v156
	v_mul_f32_e32 v60, v60, v156
	v_mul_f32_e32 v45, v45, v157
	v_mul_f32_e32 v61, v61, v157
	ds_read_b128 v[154:157], v2 offset:96
	s_waitcnt lgkmcnt(0)
	v_mul_f32_e32 v46, v46, v154
	v_mul_f32_e32 v62, v62, v154
	v_mul_f32_e32 v47, v47, v155
	v_mul_f32_e32 v63, v63, v155
	v_mul_f32_e32 v48, v48, v156
	v_mul_f32_e32 v64, v64, v156
	v_mul_f32_e32 v49, v49, v157
	v_mul_f32_e32 v65, v65, v157

.Lmy_B_loop:
	s_waitcnt lgkmcnt(0)
	v_mov_b32_e32 v2, v237
	v_mfma_f32_32x32x16_bf16 v[142:157], v[218:221], v[4:7], v[66:81]
	v_exp_f32_e32 v82, v82
	v_exp_f32_e32 v83, v83
	v_exp_f32_e32 v84, v84
	v_add_f32_e32 v27, v82, v83
	v_exp_f32_e32 v85, v85
	ds_read_b64_tr_b16 v[114:115], v2 offset:49152
	ds_read_b64_tr_b16 v[116:117], v2 offset:49664
	ds_read_b64_tr_b16 v[118:119], v2 offset:50176
	ds_read_b64_tr_b16 v[120:121], v2 offset:50688
	v_mfma_f32_32x32x16_bf16 v[158:173], v[214:217], v[4:7], v[66:81]
	v_exp_f32_e32 v86, v86
	v_add_f32_e32 v27, v27, v84
	v_exp_f32_e32 v87, v87
	v_add_f32_e32 v27, v27, v85
	v_exp_f32_e32 v88, v88
	ds_read_b64_tr_b16 v[122:123], v2 offset:51200
	ds_read_b64_tr_b16 v[124:125], v2 offset:51712
	ds_read_b64_tr_b16 v[126:127], v2 offset:52224
	ds_read_b64_tr_b16 v[128:129], v2 offset:52736
	v_mfma_f32_32x32x16_bf16 v[142:157], v[210:213], v[8:11], v[142:157]
	v_add_f32_e32 v27, v27, v86
	v_exp_f32_e32 v89, v89
	v_add_f32_e32 v27, v27, v87
	v_add_f32_e32 v27, v27, v88
	v_add_f32_e32 v27, v27, v89
	ds_read_b64_tr_b16 v[240:241], v2 offset:53248
	ds_read_b64_tr_b16 v[242:243], v2 offset:53760
	ds_read_b64_tr_b16 v[244:245], v2 offset:54272
	ds_read_b64_tr_b16 v[246:247], v2 offset:54784
	v_mfma_f32_32x32x16_bf16 v[158:173], v[206:209], v[8:11], v[158:173]
	v_cvt_pk_bf16_f32 v82, v82, v83
	v_cvt_pk_bf16_f32 v83, v84, v85
	v_cvt_pk_bf16_f32 v84, v86, v87
	v_cvt_pk_bf16_f32 v85, v88, v89
	ds_read_b64_tr_b16 v[248:249], v2 offset:55296
	ds_read_b64_tr_b16 v[250:251], v2 offset:55808
	ds_read_b64_tr_b16 v[20:21], v2 offset:56320
	ds_read_b64_tr_b16 v[22:23], v2 offset:56832
	v_mfma_f32_32x32x16_bf16 v[142:157], v[202:205], v[12:15], v[142:157]
	v_exp_f32_e32 v90, v90
	v_exp_f32_e32 v91, v91
	v_exp_f32_e32 v92, v92
	v_add_f32_e32 v27, v27, v90
	v_exp_f32_e32 v93, v93
	v_mfma_f32_32x32x16_bf16 v[158:173], v[198:201], v[12:15], v[158:173]
	v_add_f32_e32 v27, v27, v91
	v_exp_f32_e32 v94, v94
	v_add_f32_e32 v27, v27, v92
	v_exp_f32_e32 v95, v95
	v_add_f32_e32 v27, v27, v93
	s_waitcnt vmcnt(4)
	s_barrier
	v_mfma_f32_32x32x16_bf16 v[142:157], v[194:197], v[130:133], v[142:157]
	s_add_u32 m0, s57, 0x6000
	v_exp_f32_e32 v96, v96
	v_add_f32_e32 v27, v27, v94
	global_load_lds_dwordx4 v[28:29], off
	v_lshl_add_u64 v[28:29], v[28:29], 0, s[30:31]
	v_exp_f32_e32 v97, v97
	v_add_f32_e32 v27, v27, v95
	v_add_f32_e32 v27, v27, v96
	v_mfma_f32_32x32x16_bf16 v[158:173], v[190:193], v[130:133], v[158:173]
	s_add_u32 m0, s40, 0x3000
	v_add_f32_e32 v27, v27, v97
	v_cvt_pk_bf16_f32 v90, v90, v91
	global_load_lds_dwordx4 v[24:25], off
	v_lshl_add_u64 v[24:25], v[24:25], 0, s[30:31]
	v_cvt_pk_bf16_f32 v91, v92, v93
	v_cvt_pk_bf16_f32 v92, v94, v95
	v_cvt_pk_bf16_f32 v93, v96, v97
	v_mfma_f32_32x32x16_bf16 v[142:157], v[186:189], v[134:137], v[142:157]
	v_exp_f32_e32 v98, v98
	v_exp_f32_e32 v99, v99
	v_exp_f32_e32 v100, v100
	v_add_f32_e32 v27, v27, v98
	v_exp_f32_e32 v101, v101
	v_mfma_f32_32x32x16_bf16 v[158:173], v[182:185], v[134:137], v[158:173]
	v_add_f32_e32 v27, v27, v99
	v_exp_f32_e32 v102, v102
	v_add_f32_e32 v27, v27, v100
	v_exp_f32_e32 v103, v103
	v_add_f32_e32 v27, v27, v101
	v_mfma_f32_32x32x16_bf16 v[142:157], v[178:181], v[138:141], v[142:157]
	v_exp_f32_e32 v104, v104
	v_add_f32_e32 v27, v27, v102
	v_exp_f32_e32 v105, v105
	v_add_f32_e32 v27, v27, v103
	v_add_f32_e32 v27, v27, v104
	v_mfma_f32_32x32x16_bf16 v[158:173], v[174:177], v[138:141], v[158:173]
	v_add_f32_e32 v27, v27, v105
	v_cvt_pk_bf16_f32 v98, v98, v99
	v_cvt_pk_bf16_f32 v99, v100, v101
	v_cvt_pk_bf16_f32 v100, v102, v103
	v_cvt_pk_bf16_f32 v101, v104, v105
	s_waitcnt lgkmcnt(0)
	v_add_u32_e32 v2, 0x6000, v238
	v_mfma_f32_32x32x16_bf16 v[34:49], v[82:85], v[114:117], v[34:49]
	v_exp_f32_e32 v106, v106
	v_exp_f32_e32 v107, v107
	v_exp_f32_e32 v108, v108
	v_add_f32_e32 v27, v27, v106
	v_exp_f32_e32 v109, v109
	v_add_f32_e32 v27, v27, v107
	v_exp_f32_e32 v110, v110
	v_add_f32_e32 v27, v27, v108
	v_exp_f32_e32 v111, v111
	v_add_f32_e32 v27, v27, v109
	ds_read_b128 v[218:221], v2
	ds_read_b128 v[214:217], v2 offset:512
	ds_read_b128 v[210:213], v2 offset:2048
	v_mfma_f32_32x32x16_bf16 v[50:65], v[82:85], v[240:243], v[50:65]
	v_exp_f32_e32 v112, v112
	v_add_f32_e32 v27, v27, v110
	v_exp_f32_e32 v113, v113
	v_add_f32_e32 v27, v27, v111
	v_add_f32_e32 v27, v27, v112
	v_add_f32_e32 v27, v27, v113
	v_cvt_pk_bf16_f32 v106, v106, v107
	v_cvt_pk_bf16_f32 v107, v108, v109
	v_cvt_pk_bf16_f32 v108, v110, v111
	v_cvt_pk_bf16_f32 v109, v112, v113
	v_add_f32_e32 v236, v236, v27
	ds_read_b128 v[206:209], v2 offset:2560
	ds_read_b128 v[202:205], v2 offset:4096
	ds_read_b128 v[198:201], v2 offset:4608
	v_mfma_f32_32x32x16_bf16 v[34:49], v[90:93], v[118:121], v[34:49]
	ds_read_b128 v[194:197], v2 offset:6144
	ds_read_b128 v[190:193], v2 offset:6656
	ds_read_b128 v[186:189], v2 offset:8192
	v_max3_f32 v19, v142, v143, v144
	v_max3_f32 v26, v145, v146, v147
	v_max3_f32 v19, v19, v148, v149
	v_max3_f32 v26, v26, v150, v151
	v_max3_f32 v19, v19, v152, v153
	v_mfma_f32_32x32x16_bf16 v[50:65], v[90:93], v[244:247], v[50:65]
	ds_read_b128 v[182:185], v2 offset:8704
	ds_read_b128 v[178:181], v2 offset:10240
	ds_read_b128 v[174:177], v2 offset:10752
	v_max3_f32 v26, v26, v154, v155
	v_max3_f32 v19, v19, v156, v157
	v_max3_f32 v26, v26, v158, v159
	v_max3_f32 v19, v19, v160, v161
	v_max3_f32 v26, v26, v162, v163
	v_mfma_f32_32x32x16_bf16 v[34:49], v[98:101], v[122:125], v[34:49]
	v_max3_f32 v19, v19, v164, v165
	v_max3_f32 v26, v26, v166, v167
	v_max3_f32 v19, v19, v168, v169
	v_max3_f32 v26, v26, v170, v171
	v_mfma_f32_32x32x16_bf16 v[50:65], v[98:101], v[248:251], v[50:65]
	v_max3_f32 v19, v19, v172, v173
	v_max_f32_e32 v19, v19, v26
	v_mfma_f32_32x32x16_bf16 v[34:49], v[106:109], v[126:129], v[34:49]
	v_mfma_f32_32x32x16_bf16 v[50:65], v[106:109], v[20:23], v[50:65]
	v_cmp_lt_f32_e32 vcc, s41, v19
	s_cbranch_vccz .Lmy_nors_36
	s_nop 15
	s_nop 15
	v_mov_b32_e32 v26, v19
	s_nop 1
	v_permlane32_swap_b32_e32 v19, v26
	v_max_f32_e32 v19, v19, v26
	v_max_f32_e32 v19, v19, v19
	v_max_f32_e32 v90, 0, v19
	v_exp_f32_e64 v91, -v90
	v_add_f32_e32 v239, v239, v90
	v_xor_b32_e32 v66, 0x80000000, v239
	v_mov_b32_e32 v67, v66
	v_mov_b32_e32 v68, v66
	v_mov_b32_e32 v69, v66
	v_mov_b32_e32 v70, v66
	v_mov_b32_e32 v71, v66
	v_mov_b32_e32 v72, v66
	v_mov_b32_e32 v73, v66
	v_mov_b32_e32 v74, v66
	v_mov_b32_e32 v75, v66
	v_mov_b32_e32 v76, v66
	v_mov_b32_e32 v77, v66
	v_mov_b32_e32 v78, v66
	v_mov_b32_e32 v79, v66
	v_mov_b32_e32 v80, v66
	v_mov_b32_e32 v81, v66
	v_sub_f32_e32 v142, v142, v90
	v_sub_f32_e32 v143, v143, v90
	v_sub_f32_e32 v144, v144, v90
	v_sub_f32_e32 v145, v145, v90
	v_sub_f32_e32 v146, v146, v90
	v_sub_f32_e32 v147, v147, v90
	v_sub_f32_e32 v148, v148, v90
	v_sub_f32_e32 v149, v149, v90
	v_sub_f32_e32 v150, v150, v90
	v_sub_f32_e32 v151, v151, v90
	v_sub_f32_e32 v152, v152, v90
	v_sub_f32_e32 v153, v153, v90
	v_sub_f32_e32 v154, v154, v90
	v_sub_f32_e32 v155, v155, v90
	v_sub_f32_e32 v156, v156, v90
	v_sub_f32_e32 v157, v157, v90
	v_sub_f32_e32 v158, v158, v90
	v_sub_f32_e32 v159, v159, v90
	v_sub_f32_e32 v160, v160, v90
	v_sub_f32_e32 v161, v161, v90
	v_sub_f32_e32 v162, v162, v90
	v_sub_f32_e32 v163, v163, v90
	v_sub_f32_e32 v164, v164, v90
	v_sub_f32_e32 v165, v165, v90
	v_sub_f32_e32 v166, v166, v90
	v_sub_f32_e32 v167, v167, v90
	v_sub_f32_e32 v168, v168, v90
	v_sub_f32_e32 v169, v169, v90
	v_sub_f32_e32 v170, v170, v90
	v_sub_f32_e32 v171, v171, v90
	v_sub_f32_e32 v172, v172, v90
	v_sub_f32_e32 v173, v173, v90
	v_mul_f32_e32 v236, v236, v91
	s_mov_b64 s[96:97], exec
	s_and_b64 exec, exec, s[8:9]
	ds_write_b32 v235, v91
	s_mov_b64 exec, s[96:97]
	v_lshl_add_u32 v2, v228, 4, s47
	ds_read_b128 v[94:97], v2 offset:0
	s_waitcnt lgkmcnt(0)
	v_mul_f32_e32 v34, v34, v94
	v_mul_f32_e32 v50, v50, v94
	v_mul_f32_e32 v35, v35, v95
	v_mul_f32_e32 v51, v51, v95
	v_mul_f32_e32 v36, v36, v96
	v_mul_f32_e32 v52, v52, v96
	v_mul_f32_e32 v37, v37, v97
	v_mul_f32_e32 v53, v53, v97
	ds_read_b128 v[94:97], v2 offset:32
	s_waitcnt lgkmcnt(0)
	v_mul_f32_e32 v38, v38, v94
	v_mul_f32_e32 v54, v54, v94
	v_mul_f32_e32 v39, v39, v95
	v_mul_f32_e32 v55, v55, v95
	v_mul_f32_e32 v40, v40, v96
	v_mul_f32_e32 v56, v56, v96
	v_mul_f32_e32 v41, v41, v97
	v_mul_f32_e32 v57, v57, v97
	ds_read_b128 v[94:97], v2 offset:64
	s_waitcnt lgkmcnt(0)
	v_mul_f32_e32 v42, v42, v94
	v_mul_f32_e32 v58, v58, v94
	v_mul_f32_e32 v43, v43, v95
	v_mul_f32_e32 v59, v59, v95
	v_mul_f32_e32 v44, v44, v96
	v_mul_f32_e32 v60, v60, v96
	v_mul_f32_e32 v45, v45, v97
	v_mul_f32_e32 v61, v61, v97
	ds_read_b128 v[94:97], v2 offset:96
	s_waitcnt lgkmcnt(0)
	v_mul_f32_e32 v46, v46, v94
	v_mul_f32_e32 v62, v62, v94
	v_mul_f32_e32 v47, v47, v95
	v_mul_f32_e32 v63, v63, v95
	v_mul_f32_e32 v48, v48, v96
	v_mul_f32_e32 v64, v64, v96
	v_mul_f32_e32 v49, v49, v97
	v_mul_f32_e32 v65, v65, v97

.Lmy_nors_37:
	s_waitcnt lgkmcnt(0)
	v_add_u32_e32 v2, 0x4000, v237
	v_mfma_f32_32x32x16_bf16 v[142:157], v[218:221], v[4:7], v[66:81]
	v_exp_f32_e32 v82, v82
	v_exp_f32_e32 v83, v83
	v_exp_f32_e32 v84, v84
	v_add_f32_e32 v27, v82, v83
	v_exp_f32_e32 v85, v85
	ds_read_b64_tr_b16 v[114:115], v2 offset:49152
	ds_read_b64_tr_b16 v[116:117], v2 offset:49664
	ds_read_b64_tr_b16 v[118:119], v2 offset:50176
	ds_read_b64_tr_b16 v[120:121], v2 offset:50688
	v_mfma_f32_32x32x16_bf16 v[158:173], v[214:217], v[4:7], v[66:81]
	v_exp_f32_e32 v86, v86
	v_add_f32_e32 v27, v27, v84
	v_exp_f32_e32 v87, v87
	v_add_f32_e32 v27, v27, v85
	v_exp_f32_e32 v88, v88
	ds_read_b64_tr_b16 v[122:123], v2 offset:51200
	ds_read_b64_tr_b16 v[124:125], v2 offset:51712
	ds_read_b64_tr_b16 v[126:127], v2 offset:52224
	ds_read_b64_tr_b16 v[128:129], v2 offset:52736
	v_mfma_f32_32x32x16_bf16 v[142:157], v[210:213], v[8:11], v[142:157]
	v_add_f32_e32 v27, v27, v86
	v_exp_f32_e32 v89, v89
	v_add_f32_e32 v27, v27, v87
	v_add_f32_e32 v27, v27, v88
	v_add_f32_e32 v27, v27, v89
	ds_read_b64_tr_b16 v[240:241], v2 offset:53248
	ds_read_b64_tr_b16 v[242:243], v2 offset:53760
	ds_read_b64_tr_b16 v[244:245], v2 offset:54272
	ds_read_b64_tr_b16 v[246:247], v2 offset:54784
	v_mfma_f32_32x32x16_bf16 v[158:173], v[206:209], v[8:11], v[158:173]
	v_cvt_pk_bf16_f32 v82, v82, v83
	v_cvt_pk_bf16_f32 v83, v84, v85
	v_cvt_pk_bf16_f32 v84, v86, v87
	v_cvt_pk_bf16_f32 v85, v88, v89
	ds_read_b64_tr_b16 v[248:249], v2 offset:55296
	ds_read_b64_tr_b16 v[250:251], v2 offset:55808
	ds_read_b64_tr_b16 v[20:21], v2 offset:56320
	ds_read_b64_tr_b16 v[22:23], v2 offset:56832
	v_mfma_f32_32x32x16_bf16 v[142:157], v[202:205], v[12:15], v[142:157]
	v_exp_f32_e32 v90, v90
	v_exp_f32_e32 v91, v91
	v_exp_f32_e32 v92, v92
	v_add_f32_e32 v27, v27, v90
	v_exp_f32_e32 v93, v93
	v_mfma_f32_32x32x16_bf16 v[158:173], v[198:201], v[12:15], v[158:173]
	v_add_f32_e32 v27, v27, v91
	v_exp_f32_e32 v94, v94
	v_add_f32_e32 v27, v27, v92
	v_exp_f32_e32 v95, v95
	v_add_f32_e32 v27, v27, v93
	s_waitcnt vmcnt(4)
	s_barrier
	v_mfma_f32_32x32x16_bf16 v[142:157], v[194:197], v[130:133], v[142:157]
	s_add_u32 m0, s57, 0x2000
	v_exp_f32_e32 v96, v96
	v_add_f32_e32 v27, v27, v94
	global_load_lds_dwordx4 v[28:29], off
	v_lshl_add_u64 v[28:29], v[28:29], 0, s[30:31]
	v_exp_f32_e32 v97, v97
	v_add_f32_e32 v27, v27, v95
	v_add_f32_e32 v27, v27, v96
	v_mfma_f32_32x32x16_bf16 v[158:173], v[190:193], v[130:133], v[158:173]
	s_add_u32 m0, s40, 0x9000
	v_add_f32_e32 v27, v27, v97
	v_cvt_pk_bf16_f32 v90, v90, v91
	global_load_lds_dwordx4 v[24:25], off
	v_lshl_add_u64 v[24:25], v[24:25], 0, s[30:31]
	v_cvt_pk_bf16_f32 v91, v92, v93
	v_cvt_pk_bf16_f32 v92, v94, v95
	v_cvt_pk_bf16_f32 v93, v96, v97
	v_mfma_f32_32x32x16_bf16 v[142:157], v[186:189], v[134:137], v[142:157]
	v_exp_f32_e32 v98, v98
	v_exp_f32_e32 v99, v99
	v_exp_f32_e32 v100, v100
	v_add_f32_e32 v27, v27, v98
	v_exp_f32_e32 v101, v101
	v_mfma_f32_32x32x16_bf16 v[158:173], v[182:185], v[134:137], v[158:173]
	v_add_f32_e32 v27, v27, v99
	v_exp_f32_e32 v102, v102
	v_add_f32_e32 v27, v27, v100
	v_exp_f32_e32 v103, v103
	v_add_f32_e32 v27, v27, v101
	v_mfma_f32_32x32x16_bf16 v[142:157], v[178:181], v[138:141], v[142:157]
	v_exp_f32_e32 v104, v104
	v_add_f32_e32 v27, v27, v102
	v_exp_f32_e32 v105, v105
	v_add_f32_e32 v27, v27, v103
	v_add_f32_e32 v27, v27, v104
	v_mfma_f32_32x32x16_bf16 v[158:173], v[174:177], v[138:141], v[158:173]
	v_add_f32_e32 v27, v27, v105
	v_cvt_pk_bf16_f32 v98, v98, v99
	v_cvt_pk_bf16_f32 v99, v100, v101
	v_cvt_pk_bf16_f32 v100, v102, v103
	v_cvt_pk_bf16_f32 v101, v104, v105
	s_waitcnt lgkmcnt(0)
	v_mov_b32_e32 v2, v238
	v_mfma_f32_32x32x16_bf16 v[34:49], v[82:85], v[114:117], v[34:49]
	v_exp_f32_e32 v106, v106
	v_exp_f32_e32 v107, v107
	v_exp_f32_e32 v108, v108
	v_add_f32_e32 v27, v27, v106
	v_exp_f32_e32 v109, v109
	v_add_f32_e32 v27, v27, v107
	v_exp_f32_e32 v110, v110
	v_add_f32_e32 v27, v27, v108
	v_exp_f32_e32 v111, v111
	v_add_f32_e32 v27, v27, v109
	ds_read_b128 v[218:221], v2
	ds_read_b128 v[214:217], v2 offset:512
	ds_read_b128 v[210:213], v2 offset:2048
	v_mfma_f32_32x32x16_bf16 v[50:65], v[82:85], v[240:243], v[50:65]
	v_exp_f32_e32 v112, v112
	v_add_f32_e32 v27, v27, v110
	v_exp_f32_e32 v113, v113
	v_add_f32_e32 v27, v27, v111
	v_add_f32_e32 v27, v27, v112
	v_add_f32_e32 v27, v27, v113
	v_cvt_pk_bf16_f32 v106, v106, v107
	v_cvt_pk_bf16_f32 v107, v108, v109
	v_cvt_pk_bf16_f32 v108, v110, v111
	v_cvt_pk_bf16_f32 v109, v112, v113
	v_add_f32_e32 v236, v236, v27
	ds_read_b128 v[206:209], v2 offset:2560
	ds_read_b128 v[202:205], v2 offset:4096
	ds_read_b128 v[198:201], v2 offset:4608
	v_mfma_f32_32x32x16_bf16 v[34:49], v[90:93], v[118:121], v[34:49]
	ds_read_b128 v[194:197], v2 offset:6144
	ds_read_b128 v[190:193], v2 offset:6656
	ds_read_b128 v[186:189], v2 offset:8192
	v_max3_f32 v19, v142, v143, v144
	v_max3_f32 v26, v145, v146, v147
	v_max3_f32 v19, v19, v148, v149
	v_max3_f32 v26, v26, v150, v151
	v_max3_f32 v19, v19, v152, v153
	v_mfma_f32_32x32x16_bf16 v[50:65], v[90:93], v[244:247], v[50:65]
	ds_read_b128 v[182:185], v2 offset:8704
	ds_read_b128 v[178:181], v2 offset:10240
	ds_read_b128 v[174:177], v2 offset:10752
	v_max3_f32 v26, v26, v154, v155
	v_max3_f32 v19, v19, v156, v157
	v_max3_f32 v26, v26, v158, v159
	v_max3_f32 v19, v19, v160, v161
	v_max3_f32 v26, v26, v162, v163
	v_mfma_f32_32x32x16_bf16 v[34:49], v[98:101], v[122:125], v[34:49]
	v_max3_f32 v19, v19, v164, v165
	v_max3_f32 v26, v26, v166, v167
	v_max3_f32 v19, v19, v168, v169
	v_max3_f32 v26, v26, v170, v171
	v_mfma_f32_32x32x16_bf16 v[50:65], v[98:101], v[248:251], v[50:65]
	v_max3_f32 v19, v19, v172, v173
	v_max_f32_e32 v19, v19, v26
	v_mfma_f32_32x32x16_bf16 v[34:49], v[106:109], v[126:129], v[34:49]
	v_mfma_f32_32x32x16_bf16 v[50:65], v[106:109], v[20:23], v[50:65]
	v_cmp_lt_f32_e32 vcc, s41, v19
	s_cbranch_vccz .Lmy_nors_38
	s_nop 15
	s_nop 15
	v_mov_b32_e32 v26, v19
	s_nop 1
	v_permlane32_swap_b32_e32 v19, v26
	v_max_f32_e32 v19, v19, v26
	v_max_f32_e32 v19, v19, v19
	v_max_f32_e32 v90, 0, v19
	v_exp_f32_e64 v91, -v90
	v_add_f32_e32 v239, v239, v90
	v_xor_b32_e32 v66, 0x80000000, v239
	v_mov_b32_e32 v67, v66
	v_mov_b32_e32 v68, v66
	v_mov_b32_e32 v69, v66
	v_mov_b32_e32 v70, v66
	v_mov_b32_e32 v71, v66
	v_mov_b32_e32 v72, v66
	v_mov_b32_e32 v73, v66
	v_mov_b32_e32 v74, v66
	v_mov_b32_e32 v75, v66
	v_mov_b32_e32 v76, v66
	v_mov_b32_e32 v77, v66
	v_mov_b32_e32 v78, v66
	v_mov_b32_e32 v79, v66
	v_mov_b32_e32 v80, v66
	v_mov_b32_e32 v81, v66
	v_sub_f32_e32 v142, v142, v90
	v_sub_f32_e32 v143, v143, v90
	v_sub_f32_e32 v144, v144, v90
	v_sub_f32_e32 v145, v145, v90
	v_sub_f32_e32 v146, v146, v90
	v_sub_f32_e32 v147, v147, v90
	v_sub_f32_e32 v148, v148, v90
	v_sub_f32_e32 v149, v149, v90
	v_sub_f32_e32 v150, v150, v90
	v_sub_f32_e32 v151, v151, v90
	v_sub_f32_e32 v152, v152, v90
	v_sub_f32_e32 v153, v153, v90
	v_sub_f32_e32 v154, v154, v90
	v_sub_f32_e32 v155, v155, v90
	v_sub_f32_e32 v156, v156, v90
	v_sub_f32_e32 v157, v157, v90
	v_sub_f32_e32 v158, v158, v90
	v_sub_f32_e32 v159, v159, v90
	v_sub_f32_e32 v160, v160, v90
	v_sub_f32_e32 v161, v161, v90
	v_sub_f32_e32 v162, v162, v90
	v_sub_f32_e32 v163, v163, v90
	v_sub_f32_e32 v164, v164, v90
	v_sub_f32_e32 v165, v165, v90
	v_sub_f32_e32 v166, v166, v90
	v_sub_f32_e32 v167, v167, v90
	v_sub_f32_e32 v168, v168, v90
	v_sub_f32_e32 v169, v169, v90
	v_sub_f32_e32 v170, v170, v90
	v_sub_f32_e32 v171, v171, v90
	v_sub_f32_e32 v172, v172, v90
	v_sub_f32_e32 v173, v173, v90
	v_mul_f32_e32 v236, v236, v91
	s_mov_b64 s[96:97], exec
	s_and_b64 exec, exec, s[8:9]
	ds_write_b32 v235, v91
	s_mov_b64 exec, s[96:97]
	v_lshl_add_u32 v2, v228, 4, s47
	ds_read_b128 v[94:97], v2 offset:0
	s_waitcnt lgkmcnt(0)
	v_mul_f32_e32 v34, v34, v94
	v_mul_f32_e32 v50, v50, v94
	v_mul_f32_e32 v35, v35, v95
	v_mul_f32_e32 v51, v51, v95
	v_mul_f32_e32 v36, v36, v96
	v_mul_f32_e32 v52, v52, v96
	v_mul_f32_e32 v37, v37, v97
	v_mul_f32_e32 v53, v53, v97
	ds_read_b128 v[94:97], v2 offset:32
	s_waitcnt lgkmcnt(0)
	v_mul_f32_e32 v38, v38, v94
	v_mul_f32_e32 v54, v54, v94
	v_mul_f32_e32 v39, v39, v95
	v_mul_f32_e32 v55, v55, v95
	v_mul_f32_e32 v40, v40, v96
	v_mul_f32_e32 v56, v56, v96
	v_mul_f32_e32 v41, v41, v97
	v_mul_f32_e32 v57, v57, v97
	ds_read_b128 v[94:97], v2 offset:64
	s_waitcnt lgkmcnt(0)
	v_mul_f32_e32 v42, v42, v94
	v_mul_f32_e32 v58, v58, v94
	v_mul_f32_e32 v43, v43, v95
	v_mul_f32_e32 v59, v59, v95
	v_mul_f32_e32 v44, v44, v96
	v_mul_f32_e32 v60, v60, v96
	v_mul_f32_e32 v45, v45, v97
	v_mul_f32_e32 v61, v61, v97
	ds_read_b128 v[94:97], v2 offset:96
	s_waitcnt lgkmcnt(0)
	v_mul_f32_e32 v46, v46, v94
	v_mul_f32_e32 v62, v62, v94
	v_mul_f32_e32 v47, v47, v95
	v_mul_f32_e32 v63, v63, v95
	v_mul_f32_e32 v48, v48, v96
	v_mul_f32_e32 v64, v64, v96
	v_mul_f32_e32 v49, v49, v97
	v_mul_f32_e32 v65, v65, v97
